# all global stores write-through (sc1) so L2 never holds dirty lines; the now-redundant buffer_wbl2 release write-backs removed (stores drained by vmcnt(0) before each arrive)
# speedup vs baseline: 1.0344x; 1.0174x over previous
.LBB0_196:
	s_cmp_eq_u64 s[16:17], 0
	v_lshlrev_b32_e32 v83, 3, v82
	s_cbranch_scc1 .LBB0_200
	v_mul_f32_e32 v86, v7, v7
	v_mul_f32_e32 v87, v9, v9
	v_fmac_f32_e32 v86, v6, v6
	v_fmac_f32_e32 v87, v8, v8
	v_add_f32_e32 v86, v86, v87
	v_mul_f32_e32 v87, v3, v3
	v_mul_f32_e32 v88, v5, v5
	v_fmac_f32_e32 v87, v2, v2
	v_fmac_f32_e32 v88, v4, v4
	v_add_f32_e32 v87, v87, v88
	v_add_f32_e32 v86, v86, v87
	v_mul_f32_e32 v87, v15, v15
	v_mul_f32_e32 v88, v17, v17
	v_fmac_f32_e32 v87, v14, v14
	v_fmac_f32_e32 v88, v16, v16
	v_add_f32_e32 v87, v87, v88
	v_add_f32_e32 v86, v86, v87
	v_mul_f32_e32 v87, v11, v11
	v_mul_f32_e32 v88, v13, v13
	v_fmac_f32_e32 v87, v10, v10
	v_fmac_f32_e32 v88, v12, v12
	v_add_f32_e32 v87, v87, v88
	v_add_f32_e32 v86, v86, v87
	v_and_b32_e32 v87, 64, v1
	v_add_u32_e32 v87, 64, v87
	v_xor_b32_e32 v88, 1, v1
	v_cmp_lt_i32_e32 vcc, v88, v87
	v_cvt_pk_bf16_f32 v2, v2, v3
	v_cvt_pk_bf16_f32 v3, v4, v5
	v_cndmask_b32_e32 v88, v1, v88, vcc
	v_lshlrev_b32_e32 v88, 2, v88
	ds_bpermute_b32 v88, v88, v86
	global_store_dwordx2 v83, v[2:3], s[16:17] offset:512 sc1
	v_cvt_pk_bf16_f32 v2, v14, v15
	v_cvt_pk_bf16_f32 v3, v16, v17
	v_cvt_pk_bf16_f32 v6, v6, v7
	s_waitcnt lgkmcnt(0)
	v_add_f32_e32 v86, v86, v88
	v_xor_b32_e32 v88, 2, v1
	v_cmp_lt_i32_e32 vcc, v88, v87
	v_cvt_pk_bf16_f32 v7, v8, v9
	global_store_dwordx2 v83, v[2:3], s[16:17] offset:1024 sc1
	v_cndmask_b32_e32 v88, v1, v88, vcc
	v_lshlrev_b32_e32 v88, 2, v88
	ds_bpermute_b32 v88, v88, v86
	v_cvt_pk_bf16_f32 v2, v10, v11
	v_cvt_pk_bf16_f32 v3, v12, v13
	global_store_dwordx2 v83, v[6:7], s[16:17] sc1
	global_store_dwordx2 v83, v[2:3], s[16:17] offset:1536 sc1
	s_waitcnt lgkmcnt(0)
	v_add_f32_e32 v86, v86, v88
	v_xor_b32_e32 v88, 4, v1
	v_cmp_lt_i32_e32 vcc, v88, v87
	s_nop 1
	v_cndmask_b32_e32 v88, v1, v88, vcc
	v_lshlrev_b32_e32 v88, 2, v88
	ds_bpermute_b32 v88, v88, v86
	s_waitcnt lgkmcnt(0)
	v_add_f32_e32 v86, v86, v88
	v_xor_b32_e32 v88, 8, v1
	v_cmp_lt_i32_e32 vcc, v88, v87
	s_nop 1
	v_cndmask_b32_e32 v88, v1, v88, vcc
	v_lshlrev_b32_e32 v88, 2, v88
	ds_bpermute_b32 v88, v88, v86
	s_waitcnt lgkmcnt(0)
	v_add_f32_e32 v86, v86, v88
	v_xor_b32_e32 v88, 16, v1
	v_cmp_lt_i32_e32 vcc, v88, v87
	s_nop 1
	v_cndmask_b32_e32 v88, v1, v88, vcc
	v_lshlrev_b32_e32 v88, 2, v88
	ds_bpermute_b32 v88, v88, v86
	s_waitcnt lgkmcnt(0)
	v_add_f32_e32 v86, v86, v88
	v_xor_b32_e32 v88, 32, v1
	v_cmp_lt_i32_e32 vcc, v88, v87
	s_nop 1
	v_cndmask_b32_e32 v87, v1, v88, vcc
	v_lshlrev_b32_e32 v87, 2, v87
	ds_bpermute_b32 v87, v87, v86
	s_and_saveexec_b64 s[6:7], s[4:5]
	s_cbranch_execz .LBB0_199
	s_waitcnt lgkmcnt(0)
	v_add_f32_e32 v2, v86, v87
	global_store_dword v85, v2, s[18:19] sc1

.LBB0_200:
	s_cmp_eq_u64 s[20:21], 0
	s_cbranch_scc1 .LBB0_204
	v_mul_f32_e32 v2, v23, v23
	v_mul_f32_e32 v3, v25, v25
	v_fmac_f32_e32 v2, v22, v22
	v_fmac_f32_e32 v3, v24, v24
	v_add_f32_e32 v2, v2, v3
	v_mul_f32_e32 v3, v19, v19
	v_mul_f32_e32 v4, v21, v21
	v_fmac_f32_e32 v3, v18, v18
	v_fmac_f32_e32 v4, v20, v20
	v_add_f32_e32 v3, v3, v4
	v_add_f32_e32 v2, v2, v3
	s_waitcnt vmcnt(0)
	v_mul_f32_e32 v3, v31, v31
	v_mul_f32_e32 v4, v33, v33
	v_fmac_f32_e32 v3, v30, v30
	v_fmac_f32_e32 v4, v32, v32
	v_add_f32_e32 v3, v3, v4
	v_add_f32_e32 v2, v2, v3
	v_mul_f32_e32 v3, v27, v27
	v_mul_f32_e32 v4, v29, v29
	v_fmac_f32_e32 v3, v26, v26
	v_fmac_f32_e32 v4, v28, v28
	v_add_f32_e32 v3, v3, v4
	v_add_f32_e32 v2, v2, v3
	v_and_b32_e32 v3, 64, v1
	v_add_u32_e32 v3, 64, v3
	v_xor_b32_e32 v4, 1, v1
	v_cmp_lt_i32_e32 vcc, v4, v3
	v_cvt_pk_bf16_f32 v5, v24, v25
	s_nop 0
	v_cndmask_b32_e32 v4, v1, v4, vcc
	v_lshlrev_b32_e32 v4, 2, v4
	ds_bpermute_b32 v4, v4, v2
	s_waitcnt lgkmcnt(0)
	v_add_f32_e32 v2, v2, v4
	v_xor_b32_e32 v4, 2, v1
	v_cmp_lt_i32_e32 vcc, v4, v3
	s_nop 1
	v_cndmask_b32_e32 v4, v1, v4, vcc
	v_lshlrev_b32_e32 v4, 2, v4
	ds_bpermute_b32 v4, v4, v2
	s_waitcnt lgkmcnt(0)
	v_add_f32_e32 v2, v2, v4
	v_xor_b32_e32 v4, 4, v1
	v_cmp_lt_i32_e32 vcc, v4, v3
	s_nop 1
	v_cndmask_b32_e32 v4, v1, v4, vcc
	v_lshlrev_b32_e32 v4, 2, v4
	ds_bpermute_b32 v4, v4, v2
	s_waitcnt lgkmcnt(0)
	v_add_f32_e32 v2, v2, v4
	v_xor_b32_e32 v4, 8, v1
	v_cmp_lt_i32_e32 vcc, v4, v3
	s_nop 1
	v_cndmask_b32_e32 v4, v1, v4, vcc
	v_lshlrev_b32_e32 v4, 2, v4
	ds_bpermute_b32 v4, v4, v2
	s_waitcnt lgkmcnt(0)
	v_add_f32_e32 v2, v2, v4
	v_xor_b32_e32 v4, 16, v1
	v_cmp_lt_i32_e32 vcc, v4, v3
	s_nop 1
	v_cndmask_b32_e32 v4, v1, v4, vcc
	v_lshlrev_b32_e32 v4, 2, v4
	ds_bpermute_b32 v4, v4, v2
	s_waitcnt lgkmcnt(0)
	v_add_f32_e32 v2, v2, v4
	v_xor_b32_e32 v4, 32, v1
	v_cmp_lt_i32_e32 vcc, v4, v3
	s_nop 1
	v_cndmask_b32_e32 v3, v1, v4, vcc
	v_lshlrev_b32_e32 v3, 2, v3
	ds_bpermute_b32 v3, v3, v2
	v_cvt_pk_bf16_f32 v4, v22, v23
	global_store_dwordx2 v83, v[4:5], s[20:21] sc1
	v_cvt_pk_bf16_f32 v4, v18, v19
	v_cvt_pk_bf16_f32 v5, v20, v21
	global_store_dwordx2 v83, v[4:5], s[20:21] offset:512 sc1
	v_cvt_pk_bf16_f32 v4, v30, v31
	v_cvt_pk_bf16_f32 v5, v32, v33
	global_store_dwordx2 v83, v[4:5], s[20:21] offset:1024 sc1
	v_cvt_pk_bf16_f32 v4, v26, v27
	v_cvt_pk_bf16_f32 v5, v28, v29
	global_store_dwordx2 v83, v[4:5], s[20:21] offset:1536 sc1
	s_and_saveexec_b64 s[6:7], s[4:5]
	s_cbranch_execz .LBB0_203
	s_waitcnt lgkmcnt(0)
	v_add_f32_e32 v2, v2, v3
	global_store_dword v85, v2, s[22:23] sc1

.LBB0_204:
	s_cmp_eq_u64 s[24:25], 0
	s_cbranch_scc1 .LBB0_208
	s_waitcnt vmcnt(0)
	v_mul_f32_e32 v2, v39, v39
	s_waitcnt lgkmcnt(0)
	v_mul_f32_e32 v3, v41, v41
	v_fmac_f32_e32 v2, v38, v38
	v_fmac_f32_e32 v3, v40, v40
	v_add_f32_e32 v2, v2, v3
	v_mul_f32_e32 v3, v35, v35
	v_mul_f32_e32 v4, v37, v37
	v_fmac_f32_e32 v3, v34, v34
	v_fmac_f32_e32 v4, v36, v36
	v_add_f32_e32 v3, v3, v4
	v_add_f32_e32 v2, v2, v3
	v_mul_f32_e32 v3, v47, v47
	v_mul_f32_e32 v4, v49, v49
	v_fmac_f32_e32 v3, v46, v46
	v_fmac_f32_e32 v4, v48, v48
	v_add_f32_e32 v3, v3, v4
	v_add_f32_e32 v2, v2, v3
	v_mul_f32_e32 v3, v43, v43
	v_mul_f32_e32 v4, v45, v45
	v_fmac_f32_e32 v3, v42, v42
	v_fmac_f32_e32 v4, v44, v44
	v_add_f32_e32 v3, v3, v4
	v_add_f32_e32 v2, v2, v3
	v_and_b32_e32 v3, 64, v1
	v_add_u32_e32 v3, 64, v3
	v_xor_b32_e32 v4, 1, v1
	v_cmp_lt_i32_e32 vcc, v4, v3
	v_cvt_pk_bf16_f32 v5, v40, v41
	s_nop 0
	v_cndmask_b32_e32 v4, v1, v4, vcc
	v_lshlrev_b32_e32 v4, 2, v4
	ds_bpermute_b32 v4, v4, v2
	s_waitcnt lgkmcnt(0)
	v_add_f32_e32 v2, v2, v4
	v_xor_b32_e32 v4, 2, v1
	v_cmp_lt_i32_e32 vcc, v4, v3
	s_nop 1
	v_cndmask_b32_e32 v4, v1, v4, vcc
	v_lshlrev_b32_e32 v4, 2, v4
	ds_bpermute_b32 v4, v4, v2
	s_waitcnt lgkmcnt(0)
	v_add_f32_e32 v2, v2, v4
	v_xor_b32_e32 v4, 4, v1
	v_cmp_lt_i32_e32 vcc, v4, v3
	s_nop 1
	v_cndmask_b32_e32 v4, v1, v4, vcc
	v_lshlrev_b32_e32 v4, 2, v4
	ds_bpermute_b32 v4, v4, v2
	s_waitcnt lgkmcnt(0)
	v_add_f32_e32 v2, v2, v4
	v_xor_b32_e32 v4, 8, v1
	v_cmp_lt_i32_e32 vcc, v4, v3
	s_nop 1
	v_cndmask_b32_e32 v4, v1, v4, vcc
	v_lshlrev_b32_e32 v4, 2, v4
	ds_bpermute_b32 v4, v4, v2
	s_waitcnt lgkmcnt(0)
	v_add_f32_e32 v2, v2, v4
	v_xor_b32_e32 v4, 16, v1
	v_cmp_lt_i32_e32 vcc, v4, v3
	s_nop 1
	v_cndmask_b32_e32 v4, v1, v4, vcc
	v_lshlrev_b32_e32 v4, 2, v4
	ds_bpermute_b32 v4, v4, v2
	s_waitcnt lgkmcnt(0)
	v_add_f32_e32 v2, v2, v4
	v_xor_b32_e32 v4, 32, v1
	v_cmp_lt_i32_e32 vcc, v4, v3
	s_nop 1
	v_cndmask_b32_e32 v3, v1, v4, vcc
	v_lshlrev_b32_e32 v3, 2, v3
	ds_bpermute_b32 v3, v3, v2
	v_cvt_pk_bf16_f32 v4, v38, v39
	global_store_dwordx2 v83, v[4:5], s[24:25] sc1
	v_cvt_pk_bf16_f32 v4, v34, v35
	v_cvt_pk_bf16_f32 v5, v36, v37
	global_store_dwordx2 v83, v[4:5], s[24:25] offset:512 sc1
	v_cvt_pk_bf16_f32 v4, v46, v47
	v_cvt_pk_bf16_f32 v5, v48, v49
	global_store_dwordx2 v83, v[4:5], s[24:25] offset:1024 sc1
	v_cvt_pk_bf16_f32 v4, v42, v43
	v_cvt_pk_bf16_f32 v5, v44, v45
	global_store_dwordx2 v83, v[4:5], s[24:25] offset:1536 sc1
	s_and_saveexec_b64 s[6:7], s[4:5]
	s_cbranch_execz .LBB0_207
	s_waitcnt lgkmcnt(0)
	v_add_f32_e32 v2, v2, v3
	global_store_dword v85, v2, s[26:27] sc1

.LBB0_208:
	s_cmp_eq_u64 s[28:29], 0
	s_cbranch_scc1 .LBB0_212
	s_waitcnt vmcnt(0)
	v_mul_f32_e32 v2, v55, v55
	s_waitcnt lgkmcnt(0)
	v_mul_f32_e32 v3, v57, v57
	v_fmac_f32_e32 v2, v54, v54
	v_fmac_f32_e32 v3, v56, v56
	v_add_f32_e32 v2, v2, v3
	v_mul_f32_e32 v3, v51, v51
	v_mul_f32_e32 v4, v53, v53
	v_fmac_f32_e32 v3, v50, v50
	v_fmac_f32_e32 v4, v52, v52
	v_add_f32_e32 v3, v3, v4
	v_add_f32_e32 v2, v2, v3
	v_mul_f32_e32 v3, v63, v63
	v_mul_f32_e32 v4, v65, v65
	v_fmac_f32_e32 v3, v62, v62
	v_fmac_f32_e32 v4, v64, v64
	v_add_f32_e32 v3, v3, v4
	v_add_f32_e32 v2, v2, v3
	v_mul_f32_e32 v3, v59, v59
	v_mul_f32_e32 v4, v61, v61
	v_fmac_f32_e32 v3, v58, v58
	v_fmac_f32_e32 v4, v60, v60
	v_add_f32_e32 v3, v3, v4
	v_add_f32_e32 v2, v2, v3
	v_and_b32_e32 v3, 64, v1
	v_add_u32_e32 v3, 64, v3
	v_xor_b32_e32 v4, 1, v1
	v_cmp_lt_i32_e32 vcc, v4, v3
	v_cvt_pk_bf16_f32 v5, v56, v57
	s_nop 0
	v_cndmask_b32_e32 v4, v1, v4, vcc
	v_lshlrev_b32_e32 v4, 2, v4
	ds_bpermute_b32 v4, v4, v2
	s_waitcnt lgkmcnt(0)
	v_add_f32_e32 v2, v2, v4
	v_xor_b32_e32 v4, 2, v1
	v_cmp_lt_i32_e32 vcc, v4, v3
	s_nop 1
	v_cndmask_b32_e32 v4, v1, v4, vcc
	v_lshlrev_b32_e32 v4, 2, v4
	ds_bpermute_b32 v4, v4, v2
	s_waitcnt lgkmcnt(0)
	v_add_f32_e32 v2, v2, v4
	v_xor_b32_e32 v4, 4, v1
	v_cmp_lt_i32_e32 vcc, v4, v3
	s_nop 1
	v_cndmask_b32_e32 v4, v1, v4, vcc
	v_lshlrev_b32_e32 v4, 2, v4
	ds_bpermute_b32 v4, v4, v2
	s_waitcnt lgkmcnt(0)
	v_add_f32_e32 v2, v2, v4
	v_xor_b32_e32 v4, 8, v1
	v_cmp_lt_i32_e32 vcc, v4, v3
	s_nop 1
	v_cndmask_b32_e32 v4, v1, v4, vcc
	v_lshlrev_b32_e32 v4, 2, v4
	ds_bpermute_b32 v4, v4, v2
	s_waitcnt lgkmcnt(0)
	v_add_f32_e32 v2, v2, v4
	v_xor_b32_e32 v4, 16, v1
	v_cmp_lt_i32_e32 vcc, v4, v3
	s_nop 1
	v_cndmask_b32_e32 v4, v1, v4, vcc
	v_lshlrev_b32_e32 v4, 2, v4
	ds_bpermute_b32 v4, v4, v2
	s_waitcnt lgkmcnt(0)
	v_add_f32_e32 v2, v2, v4
	v_xor_b32_e32 v4, 32, v1
	v_cmp_lt_i32_e32 vcc, v4, v3
	s_nop 1
	v_cndmask_b32_e32 v3, v1, v4, vcc
	v_lshlrev_b32_e32 v3, 2, v3
	ds_bpermute_b32 v3, v3, v2
	v_cvt_pk_bf16_f32 v4, v54, v55
	global_store_dwordx2 v83, v[4:5], s[28:29] sc1
	v_cvt_pk_bf16_f32 v4, v50, v51
	v_cvt_pk_bf16_f32 v5, v52, v53
	global_store_dwordx2 v83, v[4:5], s[28:29] offset:512 sc1
	v_cvt_pk_bf16_f32 v4, v62, v63
	v_cvt_pk_bf16_f32 v5, v64, v65
	global_store_dwordx2 v83, v[4:5], s[28:29] offset:1024 sc1
	v_cvt_pk_bf16_f32 v4, v58, v59
	v_cvt_pk_bf16_f32 v5, v60, v61
	global_store_dwordx2 v83, v[4:5], s[28:29] offset:1536 sc1
	s_and_saveexec_b64 s[6:7], s[4:5]
	s_cbranch_execz .LBB0_211
	s_waitcnt lgkmcnt(0)
	v_add_f32_e32 v2, v2, v3
	global_store_dword v85, v2, s[30:31] sc1

.LBB0_212:
	s_cmp_eq_u64 s[68:69], 0
	s_cbranch_scc1 .LBB0_83
	s_waitcnt vmcnt(0)
	v_mul_f32_e32 v2, v71, v71
	s_waitcnt lgkmcnt(0)
	v_mul_f32_e32 v3, v73, v73
	v_fmac_f32_e32 v2, v70, v70
	v_fmac_f32_e32 v3, v72, v72
	v_add_f32_e32 v2, v2, v3
	v_mul_f32_e32 v3, v67, v67
	v_mul_f32_e32 v4, v69, v69
	v_fmac_f32_e32 v3, v66, v66
	v_fmac_f32_e32 v4, v68, v68
	v_add_f32_e32 v3, v3, v4
	v_add_f32_e32 v2, v2, v3
	v_mul_f32_e32 v3, v79, v79
	v_mul_f32_e32 v4, v81, v81
	v_fmac_f32_e32 v3, v78, v78
	v_fmac_f32_e32 v4, v80, v80
	v_add_f32_e32 v3, v3, v4
	v_add_f32_e32 v2, v2, v3
	v_mul_f32_e32 v3, v75, v75
	v_mul_f32_e32 v4, v77, v77
	v_fmac_f32_e32 v3, v74, v74
	v_fmac_f32_e32 v4, v76, v76
	v_add_f32_e32 v3, v3, v4
	v_add_f32_e32 v2, v2, v3
	v_and_b32_e32 v3, 64, v1
	v_add_u32_e32 v3, 64, v3
	v_xor_b32_e32 v4, 1, v1
	v_cmp_lt_i32_e32 vcc, v4, v3
	v_cvt_pk_bf16_f32 v5, v72, v73
	s_nop 0
	v_cndmask_b32_e32 v4, v1, v4, vcc
	v_lshlrev_b32_e32 v4, 2, v4
	ds_bpermute_b32 v4, v4, v2
	s_waitcnt lgkmcnt(0)
	v_add_f32_e32 v2, v2, v4
	v_xor_b32_e32 v4, 2, v1
	v_cmp_lt_i32_e32 vcc, v4, v3
	s_nop 1
	v_cndmask_b32_e32 v4, v1, v4, vcc
	v_lshlrev_b32_e32 v4, 2, v4
	ds_bpermute_b32 v4, v4, v2
	s_waitcnt lgkmcnt(0)
	v_add_f32_e32 v2, v2, v4
	v_xor_b32_e32 v4, 4, v1
	v_cmp_lt_i32_e32 vcc, v4, v3
	s_nop 1
	v_cndmask_b32_e32 v4, v1, v4, vcc
	v_lshlrev_b32_e32 v4, 2, v4
	ds_bpermute_b32 v4, v4, v2
	s_waitcnt lgkmcnt(0)
	v_add_f32_e32 v2, v2, v4
	v_xor_b32_e32 v4, 8, v1
	v_cmp_lt_i32_e32 vcc, v4, v3
	s_nop 1
	v_cndmask_b32_e32 v4, v1, v4, vcc
	v_lshlrev_b32_e32 v4, 2, v4
	ds_bpermute_b32 v4, v4, v2
	s_waitcnt lgkmcnt(0)
	v_add_f32_e32 v2, v2, v4
	v_xor_b32_e32 v4, 16, v1
	v_cmp_lt_i32_e32 vcc, v4, v3
	s_nop 1
	v_cndmask_b32_e32 v4, v1, v4, vcc
	v_lshlrev_b32_e32 v4, 2, v4
	ds_bpermute_b32 v4, v4, v2
	s_waitcnt lgkmcnt(0)
	v_add_f32_e32 v2, v2, v4
	v_xor_b32_e32 v4, 32, v1
	v_cmp_lt_i32_e32 vcc, v4, v3
	s_nop 1
	v_cndmask_b32_e32 v3, v1, v4, vcc
	v_lshlrev_b32_e32 v3, 2, v3
	ds_bpermute_b32 v3, v3, v2
	v_cvt_pk_bf16_f32 v4, v70, v71
	global_store_dwordx2 v83, v[4:5], s[68:69] sc1
	v_cvt_pk_bf16_f32 v4, v66, v67
	v_cvt_pk_bf16_f32 v5, v68, v69
	global_store_dwordx2 v83, v[4:5], s[68:69] offset:512 sc1
	v_cvt_pk_bf16_f32 v4, v78, v79
	v_cvt_pk_bf16_f32 v5, v80, v81
	global_store_dwordx2 v83, v[4:5], s[68:69] offset:1024 sc1
	v_cvt_pk_bf16_f32 v4, v74, v75
	v_cvt_pk_bf16_f32 v5, v76, v77
	global_store_dwordx2 v83, v[4:5], s[68:69] offset:1536 sc1
	s_and_saveexec_b64 s[6:7], s[4:5]
	s_cbranch_execz .LBB0_82
	s_waitcnt lgkmcnt(0)
	v_add_f32_e32 v2, v2, v3
	global_store_dword v85, v2, s[36:37] sc1
	s_branch .LBB0_82

.LBB0_216:
	s_waitcnt vmcnt(0)
	s_add_u32 s10, s34, 0x1c4800
	s_addc_u32 s11, s35, 0
	s_waitcnt lgkmcnt(0)
	s_barrier
	s_mov_b64 s[4:5], exec
	v_readlane_b32 s2, v253, 3
	v_readlane_b32 s3, v253, 4
	s_and_b64 s[2:3], s[4:5], s[2:3]
	s_mov_b64 exec, s[2:3]
	s_cbranch_execz .LBB0_219
	s_mov_b64 s[6:7], exec
	s_waitcnt vmcnt(30)
	v_mbcnt_lo_u32_b32 v1, s6, 0
	s_nop 0
	s_waitcnt vmcnt(0)
	s_waitcnt vmcnt(0)
	v_mbcnt_hi_u32_b32 v1, s7, v1
	v_cmp_eq_u32_e32 vcc, 0, v1
	s_and_b64 s[2:3], exec, vcc
	s_mov_b64 exec, s[2:3]
	s_cbranch_execz .LBB0_219
	s_bcnt1_i32_b64 s2, s[6:7]
	v_mov_b32_e32 v1, 0
	v_mov_b32_e32 v2, s2
	global_atomic_add v1, v2, s[10:11]

.LBB0_253:
	s_lshl_b32 s2, s6, 8
	v_mov_b32_e32 v134, v1
	v_mov_b32_e32 v181, v168
	s_add_i32 s2, s2, s59
	s_lshl_b32 s6, s4, 8
	v_add_u32_e32 v140, s2, v134
	v_ashrrev_i32_e32 v141, 31, v140
	v_lshl_add_u64 v[142:143], v[140:141], 2, s[12:13]
	v_add_u32_e32 v154, 16, v140
	global_load_dword v134, v[142:143], off
	v_ashrrev_i32_e32 v155, 31, v154
	v_add_u32_e32 v152, 32, v140
	v_add_u32_e32 v150, 48, v140
	v_add_u32_e32 v148, 0x80, v140
	v_add_u32_e32 v146, 0x90, v140
	v_add_u32_e32 v144, 0xa0, v140
	v_add_u32_e32 v142, 0xb0, v140
	v_lshl_add_u64 v[156:157], v[154:155], 2, s[12:13]
	v_ashrrev_i32_e32 v153, 31, v152
	v_ashrrev_i32_e32 v151, 31, v150
	v_ashrrev_i32_e32 v149, 31, v148
	v_ashrrev_i32_e32 v147, 31, v146
	v_ashrrev_i32_e32 v145, 31, v144
	v_ashrrev_i32_e32 v143, 31, v142
	v_lshl_add_u64 v[158:159], v[152:153], 2, s[12:13]
	v_lshl_add_u64 v[160:161], v[150:151], 2, s[12:13]
	v_lshl_add_u64 v[162:163], v[148:149], 2, s[12:13]
	v_lshl_add_u64 v[164:165], v[146:147], 2, s[12:13]
	v_lshl_add_u64 v[166:167], v[144:145], 2, s[12:13]
	v_lshl_add_u64 v[182:183], v[142:143], 2, s[12:13]
	global_load_dword v180, v[156:157], off
	global_load_dword v179, v[158:159], off
	global_load_dword v178, v[160:161], off
	global_load_dword v177, v[162:163], off
	global_load_dword v176, v[164:165], off
	global_load_dword v175, v[166:167], off
	global_load_dword v174, v[182:183], off
	s_ashr_i32 s2, s4, 2
	s_ashr_i32 s3, s2, 31
	s_lshl_b64 s[4:5], s[2:3], 20
	s_add_u32 s28, s51, s4
	s_addc_u32 s29, s52, s5
	s_add_u32 s34, s53, s4
	s_addc_u32 s35, s54, s5
	s_lshl_b64 s[2:3], s[2:3], 19
	s_add_u32 s30, s55, s2
	s_addc_u32 s31, s56, s3
	s_add_u32 s36, s57, s2
	s_addc_u32 s37, s58, s3
	s_and_b32 s2, s6, 0x300
	s_or_b32 s2, s2, s60
	v_lshlrev_b64 v[162:163], 11, v[140:141]
	v_lshlrev_b64 v[164:165], 10, v[140:141]
	v_lshl_add_u32 v140, v181, 2, s2
	v_lshl_add_u64 v[156:157], s[34:35], 0, v[162:163]
	v_lshl_add_u64 v[158:159], s[36:37], 0, v[164:165]
	v_cmp_lt_i32_e32 vcc, s66, v140
	s_waitcnt vmcnt(0)
	v_fmamk_f32 v134, v134, 0x3a800000, v173
	v_rsq_f32_e32 v160, v134
	s_nop 0
	v_pk_mul_f32 v[128:129], v[128:129], v[160:161] op_sel_hi:[1,0]
	v_pk_mul_f32 v[126:127], v[126:127], v[160:161] op_sel_hi:[1,0]
	s_nop 0
	v_cvt_pk_bf16_f32 v166, v126, v127
	v_cvt_pk_bf16_f32 v167, v128, v129
	s_and_saveexec_b64 s[2:3], vcc
	s_xor_b64 s[4:5], exec, s[2:3]
	s_cbranch_execz .LBB0_255
	v_mov_b32_e32 v141, v135
	v_lshl_add_u64 v[182:183], v[140:141], 2, v[156:157]
	global_store_dwordx4 v[182:183], v[126:129], off offset:-2048 nt sc1
	s_nop 1
	v_lshl_add_u64 v[126:127], v[140:141], 1, v[158:159]
	global_store_dwordx2 v[126:127], v[166:167], off offset:-1024 sc1
.LBB0_255:
	s_or_saveexec_b64 s[4:5], s[4:5]
	v_lshl_add_u64 v[162:163], s[28:29], 0, v[162:163]
	v_lshl_add_u64 v[164:165], s[30:31], 0, v[164:165]
	v_ashrrev_i32_e32 v141, 31, v140
	s_xor_b64 exec, exec, s[4:5]
	s_cbranch_execz .LBB0_257
	v_lshl_add_u64 v[182:183], v[140:141], 2, v[162:163]
	global_store_dwordx4 v[182:183], v[126:129], off nt sc1
	s_nop 1
	v_lshl_add_u64 v[126:127], v[140:141], 1, v[164:165]
	global_store_dwordx2 v[126:127], v[166:167], off sc1
.LBB0_257:
	s_or_b64 exec, exec, s[4:5]
	v_mov_b32_e32 v161, v160
	v_mov_b32_e32 v126, v160
	v_mov_b32_e32 v127, v160
	v_add_u32_e32 v134, 16, v140
	v_pk_mul_f32 v[124:125], v[124:125], v[126:127]
	v_pk_mul_f32 v[122:123], v[122:123], v[160:161]
	v_cmp_lt_i32_e64 s[4:5], s67, v140
	v_cvt_pk_bf16_f32 v126, v122, v123
	v_cvt_pk_bf16_f32 v127, v124, v125
	s_and_saveexec_b64 s[2:3], s[4:5]
	s_xor_b64 s[6:7], exec, s[2:3]
	s_cbranch_execz .LBB0_259
	v_lshl_add_u64 v[128:129], v[134:135], 2, v[156:157]
	global_store_dwordx4 v[128:129], v[122:125], off offset:-2048 nt sc1
	s_nop 1
	v_lshl_add_u64 v[122:123], v[134:135], 1, v[158:159]
	global_store_dwordx2 v[122:123], v[126:127], off offset:-1024 sc1
.LBB0_259:
	s_andn2_saveexec_b64 s[6:7], s[6:7]
	s_cbranch_execz .LBB0_261
	v_lshl_add_u64 v[128:129], v[140:141], 2, v[162:163]
	global_store_dwordx4 v[128:129], v[122:125], off offset:64 nt sc1
	s_nop 1
	v_lshl_add_u64 v[122:123], v[140:141], 1, v[164:165]
	global_store_dwordx2 v[122:123], v[126:127], off offset:32 sc1
.LBB0_261:
	s_or_b64 exec, exec, s[6:7]
	v_mov_b32_e32 v124, v160
	v_mov_b32_e32 v125, v160
	v_add_u32_e32 v122, 0x80, v140
	v_pk_mul_f32 v[120:121], v[120:121], v[124:125]
	v_pk_mul_f32 v[118:119], v[118:119], v[160:161]
	v_cmp_lt_i32_e64 s[8:9], s68, v140
	v_cvt_pk_bf16_f32 v124, v118, v119
	v_cvt_pk_bf16_f32 v125, v120, v121
	s_and_saveexec_b64 s[2:3], s[8:9]
	s_xor_b64 s[6:7], exec, s[2:3]
	s_cbranch_execz .LBB0_263
	v_mov_b32_e32 v123, v135
	v_lshl_add_u64 v[126:127], v[122:123], 2, v[156:157]
	global_store_dwordx4 v[126:127], v[118:121], off offset:-2048 nt sc1
	s_nop 1
	v_lshl_add_u64 v[118:119], v[122:123], 1, v[158:159]
	global_store_dwordx2 v[118:119], v[124:125], off offset:-1024 sc1
.LBB0_263:
	s_andn2_saveexec_b64 s[6:7], s[6:7]
	s_cbranch_execz .LBB0_265
	v_lshl_add_u64 v[126:127], v[140:141], 2, v[162:163]
	global_store_dwordx4 v[126:127], v[118:121], off offset:512 nt sc1
	s_nop 1
	v_lshl_add_u64 v[118:119], v[140:141], 1, v[164:165]
	global_store_dwordx2 v[118:119], v[124:125], off offset:256 sc1
.LBB0_265:
	s_or_b64 exec, exec, s[6:7]
	v_mov_b32_e32 v120, v160
	v_mov_b32_e32 v121, v160
	v_add_u32_e32 v118, 0x90, v140
	v_pk_mul_f32 v[116:117], v[116:117], v[120:121]
	v_pk_mul_f32 v[114:115], v[114:115], v[160:161]
	v_cmp_lt_i32_e64 s[6:7], s69, v140
	v_cvt_pk_bf16_f32 v120, v114, v115
	v_cvt_pk_bf16_f32 v121, v116, v117
	s_and_saveexec_b64 s[2:3], s[6:7]
	s_xor_b64 s[38:39], exec, s[2:3]
	s_cbranch_execz .LBB0_267
	v_mov_b32_e32 v119, v135
	v_lshl_add_u64 v[124:125], v[118:119], 2, v[156:157]
	global_store_dwordx4 v[124:125], v[114:117], off offset:-2048 nt sc1
	s_nop 1
	v_lshl_add_u64 v[114:115], v[118:119], 1, v[158:159]
	global_store_dwordx2 v[114:115], v[120:121], off offset:-1024 sc1
.LBB0_267:
	s_andn2_saveexec_b64 s[38:39], s[38:39]
	s_cbranch_execz .LBB0_269
	v_lshl_add_u64 v[124:125], v[140:141], 2, v[162:163]
	global_store_dwordx4 v[124:125], v[114:117], off offset:576 nt sc1
	s_nop 1
	v_lshl_add_u64 v[114:115], v[140:141], 1, v[164:165]
	global_store_dwordx2 v[114:115], v[120:121], off offset:288 sc1
.LBB0_269:
	s_or_b64 exec, exec, s[38:39]
	v_fmamk_f32 v114, v180, 0x3a800000, v173
	v_rsq_f32_e32 v120, v114
	v_lshlrev_b64 v[124:125], 11, v[154:155]
	v_lshlrev_b64 v[126:127], 10, v[154:155]
	v_lshl_add_u64 v[114:115], s[34:35], 0, v[124:125]
	v_lshl_add_u64 v[116:117], s[36:37], 0, v[126:127]
	v_pk_mul_f32 v[112:113], v[112:113], v[120:121] op_sel_hi:[1,0]
	v_pk_mul_f32 v[110:111], v[110:111], v[120:121] op_sel_hi:[1,0]
	s_nop 0
	v_cvt_pk_bf16_f32 v128, v110, v111
	v_cvt_pk_bf16_f32 v129, v112, v113
	s_and_saveexec_b64 s[2:3], vcc
	s_xor_b64 s[38:39], exec, s[2:3]
	s_cbranch_execz .LBB0_271
	v_mov_b32_e32 v154, v140
	v_mov_b32_e32 v155, v135
	v_lshl_add_u64 v[156:157], v[154:155], 2, v[114:115]
	global_store_dwordx4 v[156:157], v[110:113], off offset:-2048 nt sc1
	s_nop 1
	v_lshl_add_u64 v[110:111], v[154:155], 1, v[116:117]
	global_store_dwordx2 v[110:111], v[128:129], off offset:-1024 sc1
.LBB0_271:
	s_or_saveexec_b64 s[38:39], s[38:39]
	v_lshl_add_u64 v[124:125], s[28:29], 0, v[124:125]
	v_lshl_add_u64 v[126:127], s[30:31], 0, v[126:127]
	s_xor_b64 exec, exec, s[38:39]
	s_cbranch_execz .LBB0_273
	v_lshl_add_u64 v[154:155], v[140:141], 2, v[124:125]
	global_store_dwordx4 v[154:155], v[110:113], off nt sc1
	s_nop 1
	v_lshl_add_u64 v[110:111], v[140:141], 1, v[126:127]
	global_store_dwordx2 v[110:111], v[128:129], off sc1
.LBB0_273:
	s_or_b64 exec, exec, s[38:39]
	v_mov_b32_e32 v121, v120
	v_mov_b32_e32 v110, v120
	v_mov_b32_e32 v111, v120
	v_pk_mul_f32 v[108:109], v[108:109], v[110:111]
	v_pk_mul_f32 v[106:107], v[106:107], v[120:121]
	s_nop 0
	v_cvt_pk_bf16_f32 v110, v106, v107
	v_cvt_pk_bf16_f32 v111, v108, v109
	s_and_saveexec_b64 s[2:3], s[4:5]
	s_xor_b64 s[38:39], exec, s[2:3]
	s_cbranch_execz .LBB0_275
	v_lshl_add_u64 v[112:113], v[134:135], 2, v[114:115]
	global_store_dwordx4 v[112:113], v[106:109], off offset:-2048 nt sc1
	s_nop 1
	v_lshl_add_u64 v[106:107], v[134:135], 1, v[116:117]
	global_store_dwordx2 v[106:107], v[110:111], off offset:-1024 sc1
.LBB0_275:
	s_andn2_saveexec_b64 s[38:39], s[38:39]
	s_cbranch_execz .LBB0_277
	v_lshl_add_u64 v[112:113], v[140:141], 2, v[124:125]
	global_store_dwordx4 v[112:113], v[106:109], off offset:64 nt sc1
	s_nop 1
	v_lshl_add_u64 v[106:107], v[140:141], 1, v[126:127]
	global_store_dwordx2 v[106:107], v[110:111], off offset:32 sc1
.LBB0_277:
	s_or_b64 exec, exec, s[38:39]
	v_mov_b32_e32 v106, v120
	v_mov_b32_e32 v107, v120
	v_pk_mul_f32 v[104:105], v[104:105], v[106:107]
	v_pk_mul_f32 v[102:103], v[102:103], v[120:121]
	s_nop 0
	v_cvt_pk_bf16_f32 v106, v102, v103
	v_cvt_pk_bf16_f32 v107, v104, v105
	s_and_saveexec_b64 s[2:3], s[8:9]
	s_xor_b64 s[38:39], exec, s[2:3]
	s_cbranch_execz .LBB0_279
	v_mov_b32_e32 v123, v135
	v_lshl_add_u64 v[108:109], v[122:123], 2, v[114:115]
	global_store_dwordx4 v[108:109], v[102:105], off offset:-2048 nt sc1
	s_nop 1
	v_lshl_add_u64 v[102:103], v[122:123], 1, v[116:117]
	global_store_dwordx2 v[102:103], v[106:107], off offset:-1024 sc1
.LBB0_279:
	s_andn2_saveexec_b64 s[38:39], s[38:39]
	s_cbranch_execz .LBB0_281
	v_lshl_add_u64 v[108:109], v[140:141], 2, v[124:125]
	global_store_dwordx4 v[108:109], v[102:105], off offset:512 nt sc1
	s_nop 1
	v_lshl_add_u64 v[102:103], v[140:141], 1, v[126:127]
	global_store_dwordx2 v[102:103], v[106:107], off offset:256 sc1
.LBB0_281:
	s_or_b64 exec, exec, s[38:39]
	v_mov_b32_e32 v102, v120
	v_mov_b32_e32 v103, v120
	v_pk_mul_f32 v[100:101], v[100:101], v[102:103]
	v_pk_mul_f32 v[98:99], v[98:99], v[120:121]
	s_nop 0
	v_cvt_pk_bf16_f32 v102, v98, v99
	v_cvt_pk_bf16_f32 v103, v100, v101
	s_and_saveexec_b64 s[2:3], s[6:7]
	s_xor_b64 s[38:39], exec, s[2:3]
	s_cbranch_execz .LBB0_283
	v_mov_b32_e32 v119, v135
	v_lshl_add_u64 v[104:105], v[118:119], 2, v[114:115]
	global_store_dwordx4 v[104:105], v[98:101], off offset:-2048 nt sc1
	s_nop 1
	v_lshl_add_u64 v[98:99], v[118:119], 1, v[116:117]
	global_store_dwordx2 v[98:99], v[102:103], off offset:-1024 sc1
.LBB0_283:
	s_andn2_saveexec_b64 s[38:39], s[38:39]
	s_cbranch_execz .LBB0_285
	v_lshl_add_u64 v[104:105], v[140:141], 2, v[124:125]
	global_store_dwordx4 v[104:105], v[98:101], off offset:576 nt sc1
	s_nop 1
	v_lshl_add_u64 v[98:99], v[140:141], 1, v[126:127]
	global_store_dwordx2 v[98:99], v[102:103], off offset:288 sc1
.LBB0_285:
	s_or_b64 exec, exec, s[38:39]
	v_fmamk_f32 v98, v179, 0x3a800000, v173
	v_rsq_f32_e32 v102, v98
	v_lshlrev_b64 v[104:105], 11, v[152:153]
	v_lshlrev_b64 v[106:107], 10, v[152:153]
	v_lshl_add_u64 v[98:99], s[34:35], 0, v[104:105]
	v_lshl_add_u64 v[100:101], s[36:37], 0, v[106:107]
	v_pk_mul_f32 v[96:97], v[96:97], v[102:103] op_sel_hi:[1,0]
	v_pk_mul_f32 v[94:95], v[94:95], v[102:103] op_sel_hi:[1,0]
	s_nop 0
	v_cvt_pk_bf16_f32 v108, v94, v95
	v_cvt_pk_bf16_f32 v109, v96, v97
	s_and_saveexec_b64 s[2:3], vcc
	s_xor_b64 s[38:39], exec, s[2:3]
	s_cbranch_execz .LBB0_287
	v_mov_b32_e32 v110, v140
	v_mov_b32_e32 v111, v135
	v_lshl_add_u64 v[112:113], v[110:111], 2, v[98:99]
	global_store_dwordx4 v[112:113], v[94:97], off offset:-2048 nt sc1
	s_nop 1
	v_lshl_add_u64 v[94:95], v[110:111], 1, v[100:101]
	global_store_dwordx2 v[94:95], v[108:109], off offset:-1024 sc1
.LBB0_287:
	s_or_saveexec_b64 s[38:39], s[38:39]
	v_lshl_add_u64 v[104:105], s[28:29], 0, v[104:105]
	v_lshl_add_u64 v[106:107], s[30:31], 0, v[106:107]
	s_xor_b64 exec, exec, s[38:39]
	s_cbranch_execz .LBB0_289
	v_lshl_add_u64 v[110:111], v[140:141], 2, v[104:105]
	global_store_dwordx4 v[110:111], v[94:97], off nt sc1
	s_nop 1
	v_lshl_add_u64 v[94:95], v[140:141], 1, v[106:107]
	global_store_dwordx2 v[94:95], v[108:109], off sc1
.LBB0_289:
	s_or_b64 exec, exec, s[38:39]
	v_mov_b32_e32 v103, v102
	v_mov_b32_e32 v94, v102
	v_mov_b32_e32 v95, v102
	v_pk_mul_f32 v[92:93], v[92:93], v[94:95]
	v_pk_mul_f32 v[90:91], v[90:91], v[102:103]
	s_nop 0
	v_cvt_pk_bf16_f32 v94, v90, v91
	v_cvt_pk_bf16_f32 v95, v92, v93
	s_and_saveexec_b64 s[2:3], s[4:5]
	s_xor_b64 s[38:39], exec, s[2:3]
	s_cbranch_execz .LBB0_291
	v_lshl_add_u64 v[96:97], v[134:135], 2, v[98:99]
	global_store_dwordx4 v[96:97], v[90:93], off offset:-2048 nt sc1
	s_nop 1
	v_lshl_add_u64 v[90:91], v[134:135], 1, v[100:101]
	global_store_dwordx2 v[90:91], v[94:95], off offset:-1024 sc1
.LBB0_291:
	s_andn2_saveexec_b64 s[38:39], s[38:39]
	s_cbranch_execz .LBB0_293
	v_lshl_add_u64 v[96:97], v[140:141], 2, v[104:105]
	global_store_dwordx4 v[96:97], v[90:93], off offset:64 nt sc1
	s_nop 1
	v_lshl_add_u64 v[90:91], v[140:141], 1, v[106:107]
	global_store_dwordx2 v[90:91], v[94:95], off offset:32 sc1
.LBB0_293:
	s_or_b64 exec, exec, s[38:39]
	v_mov_b32_e32 v90, v102
	v_mov_b32_e32 v91, v102
	v_pk_mul_f32 v[88:89], v[88:89], v[90:91]
	v_pk_mul_f32 v[86:87], v[86:87], v[102:103]
	s_nop 0
	v_cvt_pk_bf16_f32 v90, v86, v87
	v_cvt_pk_bf16_f32 v91, v88, v89
	s_and_saveexec_b64 s[2:3], s[8:9]
	s_xor_b64 s[38:39], exec, s[2:3]
	s_cbranch_execz .LBB0_295
	v_mov_b32_e32 v123, v135
	v_lshl_add_u64 v[92:93], v[122:123], 2, v[98:99]
	global_store_dwordx4 v[92:93], v[86:89], off offset:-2048 nt sc1
	s_nop 1
	v_lshl_add_u64 v[86:87], v[122:123], 1, v[100:101]
	global_store_dwordx2 v[86:87], v[90:91], off offset:-1024 sc1
.LBB0_295:
	s_andn2_saveexec_b64 s[38:39], s[38:39]
	s_cbranch_execz .LBB0_297
	v_lshl_add_u64 v[92:93], v[140:141], 2, v[104:105]
	global_store_dwordx4 v[92:93], v[86:89], off offset:512 nt sc1
	s_nop 1
	v_lshl_add_u64 v[86:87], v[140:141], 1, v[106:107]
	global_store_dwordx2 v[86:87], v[90:91], off offset:256 sc1
.LBB0_297:
	s_or_b64 exec, exec, s[38:39]
	v_mov_b32_e32 v86, v102
	v_mov_b32_e32 v87, v102
	v_pk_mul_f32 v[84:85], v[84:85], v[86:87]
	v_pk_mul_f32 v[82:83], v[82:83], v[102:103]
	s_nop 0
	v_cvt_pk_bf16_f32 v86, v82, v83
	v_cvt_pk_bf16_f32 v87, v84, v85
	s_and_saveexec_b64 s[2:3], s[6:7]
	s_xor_b64 s[38:39], exec, s[2:3]
	s_cbranch_execz .LBB0_299
	v_mov_b32_e32 v119, v135
	v_lshl_add_u64 v[88:89], v[118:119], 2, v[98:99]
	global_store_dwordx4 v[88:89], v[82:85], off offset:-2048 nt sc1
	s_nop 1
	v_lshl_add_u64 v[82:83], v[118:119], 1, v[100:101]
	global_store_dwordx2 v[82:83], v[86:87], off offset:-1024 sc1
.LBB0_299:
	s_andn2_saveexec_b64 s[38:39], s[38:39]
	s_cbranch_execz .LBB0_301
	v_lshl_add_u64 v[88:89], v[140:141], 2, v[104:105]
	global_store_dwordx4 v[88:89], v[82:85], off offset:576 nt sc1
	s_nop 1
	v_lshl_add_u64 v[82:83], v[140:141], 1, v[106:107]
	global_store_dwordx2 v[82:83], v[86:87], off offset:288 sc1
.LBB0_301:
	s_or_b64 exec, exec, s[38:39]
	v_fmamk_f32 v82, v178, 0x3a800000, v173
	v_rsq_f32_e32 v86, v82
	v_lshlrev_b64 v[88:89], 11, v[150:151]
	v_lshlrev_b64 v[90:91], 10, v[150:151]
	v_lshl_add_u64 v[82:83], s[34:35], 0, v[88:89]
	v_lshl_add_u64 v[84:85], s[36:37], 0, v[90:91]
	v_pk_mul_f32 v[80:81], v[80:81], v[86:87] op_sel_hi:[1,0]
	v_pk_mul_f32 v[78:79], v[78:79], v[86:87] op_sel_hi:[1,0]
	s_nop 0
	v_cvt_pk_bf16_f32 v92, v78, v79
	v_cvt_pk_bf16_f32 v93, v80, v81
	s_and_saveexec_b64 s[2:3], vcc
	s_xor_b64 s[38:39], exec, s[2:3]
	s_cbranch_execz .LBB0_303
	v_mov_b32_e32 v94, v140
	v_mov_b32_e32 v95, v135
	v_lshl_add_u64 v[96:97], v[94:95], 2, v[82:83]
	global_store_dwordx4 v[96:97], v[78:81], off offset:-2048 nt sc1
	s_nop 1
	v_lshl_add_u64 v[78:79], v[94:95], 1, v[84:85]
	global_store_dwordx2 v[78:79], v[92:93], off offset:-1024 sc1
.LBB0_303:
	s_or_saveexec_b64 s[38:39], s[38:39]
	v_lshl_add_u64 v[88:89], s[28:29], 0, v[88:89]
	v_lshl_add_u64 v[90:91], s[30:31], 0, v[90:91]
	s_xor_b64 exec, exec, s[38:39]
	s_cbranch_execz .LBB0_305
	v_lshl_add_u64 v[94:95], v[140:141], 2, v[88:89]
	global_store_dwordx4 v[94:95], v[78:81], off nt sc1
	s_nop 1
	v_lshl_add_u64 v[78:79], v[140:141], 1, v[90:91]
	global_store_dwordx2 v[78:79], v[92:93], off sc1
.LBB0_305:
	s_or_b64 exec, exec, s[38:39]
	v_mov_b32_e32 v87, v86
	v_mov_b32_e32 v78, v86
	v_mov_b32_e32 v79, v86
	v_pk_mul_f32 v[76:77], v[76:77], v[78:79]
	v_pk_mul_f32 v[74:75], v[74:75], v[86:87]
	s_nop 0
	v_cvt_pk_bf16_f32 v78, v74, v75
	v_cvt_pk_bf16_f32 v79, v76, v77
	s_and_saveexec_b64 s[2:3], s[4:5]
	s_xor_b64 s[38:39], exec, s[2:3]
	s_cbranch_execz .LBB0_307
	v_lshl_add_u64 v[80:81], v[134:135], 2, v[82:83]
	global_store_dwordx4 v[80:81], v[74:77], off offset:-2048 nt sc1
	s_nop 1
	v_lshl_add_u64 v[74:75], v[134:135], 1, v[84:85]
	global_store_dwordx2 v[74:75], v[78:79], off offset:-1024 sc1
.LBB0_307:
	s_andn2_saveexec_b64 s[38:39], s[38:39]
	s_cbranch_execz .LBB0_309
	v_lshl_add_u64 v[80:81], v[140:141], 2, v[88:89]
	global_store_dwordx4 v[80:81], v[74:77], off offset:64 nt sc1
	s_nop 1
	v_lshl_add_u64 v[74:75], v[140:141], 1, v[90:91]
	global_store_dwordx2 v[74:75], v[78:79], off offset:32 sc1
.LBB0_309:
	s_or_b64 exec, exec, s[38:39]
	v_mov_b32_e32 v74, v86
	v_mov_b32_e32 v75, v86
	v_pk_mul_f32 v[72:73], v[72:73], v[74:75]
	v_pk_mul_f32 v[70:71], v[70:71], v[86:87]
	s_nop 0
	v_cvt_pk_bf16_f32 v74, v70, v71
	v_cvt_pk_bf16_f32 v75, v72, v73
	s_and_saveexec_b64 s[2:3], s[8:9]
	s_xor_b64 s[38:39], exec, s[2:3]
	s_cbranch_execz .LBB0_311
	v_mov_b32_e32 v123, v135
	v_lshl_add_u64 v[76:77], v[122:123], 2, v[82:83]
	global_store_dwordx4 v[76:77], v[70:73], off offset:-2048 nt sc1
	s_nop 1
	v_lshl_add_u64 v[70:71], v[122:123], 1, v[84:85]
	global_store_dwordx2 v[70:71], v[74:75], off offset:-1024 sc1
.LBB0_311:
	s_andn2_saveexec_b64 s[38:39], s[38:39]
	s_cbranch_execz .LBB0_313
	v_lshl_add_u64 v[76:77], v[140:141], 2, v[88:89]
	global_store_dwordx4 v[76:77], v[70:73], off offset:512 nt sc1
	s_nop 1
	v_lshl_add_u64 v[70:71], v[140:141], 1, v[90:91]
	global_store_dwordx2 v[70:71], v[74:75], off offset:256 sc1
.LBB0_313:
	s_or_b64 exec, exec, s[38:39]
	v_mov_b32_e32 v70, v86
	v_mov_b32_e32 v71, v86
	v_pk_mul_f32 v[68:69], v[68:69], v[70:71]
	v_pk_mul_f32 v[66:67], v[66:67], v[86:87]
	s_nop 0
	v_cvt_pk_bf16_f32 v70, v66, v67
	v_cvt_pk_bf16_f32 v71, v68, v69
	s_and_saveexec_b64 s[2:3], s[6:7]
	s_xor_b64 s[38:39], exec, s[2:3]
	s_cbranch_execz .LBB0_315
	v_mov_b32_e32 v119, v135
	v_lshl_add_u64 v[72:73], v[118:119], 2, v[82:83]
	global_store_dwordx4 v[72:73], v[66:69], off offset:-2048 nt sc1
	s_nop 1
	v_lshl_add_u64 v[66:67], v[118:119], 1, v[84:85]
	global_store_dwordx2 v[66:67], v[70:71], off offset:-1024 sc1
.LBB0_315:
	s_andn2_saveexec_b64 s[38:39], s[38:39]
	s_cbranch_execz .LBB0_317
	v_lshl_add_u64 v[72:73], v[140:141], 2, v[88:89]
	global_store_dwordx4 v[72:73], v[66:69], off offset:576 nt sc1
	s_nop 1
	v_lshl_add_u64 v[66:67], v[140:141], 1, v[90:91]
	global_store_dwordx2 v[66:67], v[70:71], off offset:288 sc1
.LBB0_317:
	s_or_b64 exec, exec, s[38:39]
	v_fmamk_f32 v66, v177, 0x3a800000, v173
	v_rsq_f32_e32 v70, v66
	v_lshlrev_b64 v[72:73], 11, v[148:149]
	v_lshlrev_b64 v[74:75], 10, v[148:149]
	v_lshl_add_u64 v[66:67], s[34:35], 0, v[72:73]
	v_lshl_add_u64 v[68:69], s[36:37], 0, v[74:75]
	v_pk_mul_f32 v[64:65], v[64:65], v[70:71] op_sel_hi:[1,0]
	v_pk_mul_f32 v[62:63], v[62:63], v[70:71] op_sel_hi:[1,0]
	s_nop 0
	v_cvt_pk_bf16_f32 v76, v62, v63
	v_cvt_pk_bf16_f32 v77, v64, v65
	s_and_saveexec_b64 s[2:3], vcc
	s_xor_b64 s[38:39], exec, s[2:3]
	s_cbranch_execz .LBB0_319
	v_mov_b32_e32 v78, v140
	v_mov_b32_e32 v79, v135
	v_lshl_add_u64 v[80:81], v[78:79], 2, v[66:67]
	global_store_dwordx4 v[80:81], v[62:65], off offset:-2048 nt sc1
	s_nop 1
	v_lshl_add_u64 v[62:63], v[78:79], 1, v[68:69]
	global_store_dwordx2 v[62:63], v[76:77], off offset:-1024 sc1
.LBB0_319:
	s_or_saveexec_b64 s[38:39], s[38:39]
	v_lshl_add_u64 v[72:73], s[28:29], 0, v[72:73]
	v_lshl_add_u64 v[74:75], s[30:31], 0, v[74:75]
	s_xor_b64 exec, exec, s[38:39]
	s_cbranch_execz .LBB0_321
	v_lshl_add_u64 v[78:79], v[140:141], 2, v[72:73]
	global_store_dwordx4 v[78:79], v[62:65], off nt sc1
	s_nop 1
	v_lshl_add_u64 v[62:63], v[140:141], 1, v[74:75]
	global_store_dwordx2 v[62:63], v[76:77], off sc1
.LBB0_321:
	s_or_b64 exec, exec, s[38:39]
	v_mov_b32_e32 v71, v70
	v_mov_b32_e32 v62, v70
	v_mov_b32_e32 v63, v70
	v_pk_mul_f32 v[60:61], v[60:61], v[62:63]
	v_pk_mul_f32 v[58:59], v[58:59], v[70:71]
	s_nop 0
	v_cvt_pk_bf16_f32 v62, v58, v59
	v_cvt_pk_bf16_f32 v63, v60, v61
	s_and_saveexec_b64 s[2:3], s[4:5]
	s_xor_b64 s[38:39], exec, s[2:3]
	s_cbranch_execz .LBB0_323
	v_lshl_add_u64 v[64:65], v[134:135], 2, v[66:67]
	global_store_dwordx4 v[64:65], v[58:61], off offset:-2048 nt sc1
	s_nop 1
	v_lshl_add_u64 v[58:59], v[134:135], 1, v[68:69]
	global_store_dwordx2 v[58:59], v[62:63], off offset:-1024 sc1
.LBB0_323:
	s_andn2_saveexec_b64 s[38:39], s[38:39]
	s_cbranch_execz .LBB0_325
	v_lshl_add_u64 v[64:65], v[140:141], 2, v[72:73]
	global_store_dwordx4 v[64:65], v[58:61], off offset:64 nt sc1
	s_nop 1
	v_lshl_add_u64 v[58:59], v[140:141], 1, v[74:75]
	global_store_dwordx2 v[58:59], v[62:63], off offset:32 sc1
.LBB0_325:
	s_or_b64 exec, exec, s[38:39]
	v_mov_b32_e32 v58, v70
	v_mov_b32_e32 v59, v70
	v_pk_mul_f32 v[56:57], v[56:57], v[58:59]
	v_pk_mul_f32 v[54:55], v[54:55], v[70:71]
	s_nop 0
	v_cvt_pk_bf16_f32 v58, v54, v55
	v_cvt_pk_bf16_f32 v59, v56, v57
	s_and_saveexec_b64 s[2:3], s[8:9]
	s_xor_b64 s[38:39], exec, s[2:3]
	s_cbranch_execz .LBB0_327
	v_mov_b32_e32 v123, v135
	v_lshl_add_u64 v[60:61], v[122:123], 2, v[66:67]
	global_store_dwordx4 v[60:61], v[54:57], off offset:-2048 nt sc1
	s_nop 1
	v_lshl_add_u64 v[54:55], v[122:123], 1, v[68:69]
	global_store_dwordx2 v[54:55], v[58:59], off offset:-1024 sc1
.LBB0_327:
	s_andn2_saveexec_b64 s[38:39], s[38:39]
	s_cbranch_execz .LBB0_329
	v_lshl_add_u64 v[60:61], v[140:141], 2, v[72:73]
	global_store_dwordx4 v[60:61], v[54:57], off offset:512 nt sc1
	s_nop 1
	v_lshl_add_u64 v[54:55], v[140:141], 1, v[74:75]
	global_store_dwordx2 v[54:55], v[58:59], off offset:256 sc1
.LBB0_329:
	s_or_b64 exec, exec, s[38:39]
	v_mov_b32_e32 v54, v70
	v_mov_b32_e32 v55, v70
	v_pk_mul_f32 v[52:53], v[52:53], v[54:55]
	v_pk_mul_f32 v[50:51], v[50:51], v[70:71]
	s_nop 0
	v_cvt_pk_bf16_f32 v54, v50, v51
	v_cvt_pk_bf16_f32 v55, v52, v53
	s_and_saveexec_b64 s[2:3], s[6:7]
	s_xor_b64 s[38:39], exec, s[2:3]
	s_cbranch_execz .LBB0_331
	v_mov_b32_e32 v119, v135
	v_lshl_add_u64 v[56:57], v[118:119], 2, v[66:67]
	global_store_dwordx4 v[56:57], v[50:53], off offset:-2048 nt sc1
	s_nop 1
	v_lshl_add_u64 v[50:51], v[118:119], 1, v[68:69]
	global_store_dwordx2 v[50:51], v[54:55], off offset:-1024 sc1
.LBB0_331:
	s_andn2_saveexec_b64 s[38:39], s[38:39]
	s_cbranch_execz .LBB0_333
	v_lshl_add_u64 v[56:57], v[140:141], 2, v[72:73]
	global_store_dwordx4 v[56:57], v[50:53], off offset:576 nt sc1
	s_nop 1
	v_lshl_add_u64 v[50:51], v[140:141], 1, v[74:75]
	global_store_dwordx2 v[50:51], v[54:55], off offset:288 sc1
.LBB0_333:
	s_or_b64 exec, exec, s[38:39]
	v_fmamk_f32 v50, v176, 0x3a800000, v173
	v_rsq_f32_e32 v54, v50
	v_lshlrev_b64 v[56:57], 11, v[146:147]
	v_lshlrev_b64 v[58:59], 10, v[146:147]
	v_lshl_add_u64 v[50:51], s[34:35], 0, v[56:57]
	v_lshl_add_u64 v[52:53], s[36:37], 0, v[58:59]
	v_pk_mul_f32 v[48:49], v[48:49], v[54:55] op_sel_hi:[1,0]
	v_pk_mul_f32 v[46:47], v[46:47], v[54:55] op_sel_hi:[1,0]
	s_nop 0
	v_cvt_pk_bf16_f32 v60, v46, v47
	v_cvt_pk_bf16_f32 v61, v48, v49
	s_and_saveexec_b64 s[2:3], vcc
	s_xor_b64 s[38:39], exec, s[2:3]
	s_cbranch_execz .LBB0_335
	v_mov_b32_e32 v62, v140
	v_mov_b32_e32 v63, v135
	v_lshl_add_u64 v[64:65], v[62:63], 2, v[50:51]
	global_store_dwordx4 v[64:65], v[46:49], off offset:-2048 nt sc1
	s_nop 1
	v_lshl_add_u64 v[46:47], v[62:63], 1, v[52:53]
	global_store_dwordx2 v[46:47], v[60:61], off offset:-1024 sc1
.LBB0_335:
	s_or_saveexec_b64 s[38:39], s[38:39]
	v_lshl_add_u64 v[56:57], s[28:29], 0, v[56:57]
	v_lshl_add_u64 v[58:59], s[30:31], 0, v[58:59]
	s_xor_b64 exec, exec, s[38:39]
	s_cbranch_execz .LBB0_337
	v_lshl_add_u64 v[62:63], v[140:141], 2, v[56:57]
	global_store_dwordx4 v[62:63], v[46:49], off nt sc1
	s_nop 1
	v_lshl_add_u64 v[46:47], v[140:141], 1, v[58:59]
	global_store_dwordx2 v[46:47], v[60:61], off sc1
.LBB0_337:
	s_or_b64 exec, exec, s[38:39]
	v_mov_b32_e32 v55, v54
	v_mov_b32_e32 v46, v54
	v_mov_b32_e32 v47, v54
	v_pk_mul_f32 v[44:45], v[44:45], v[46:47]
	v_pk_mul_f32 v[42:43], v[42:43], v[54:55]
	s_nop 0
	v_cvt_pk_bf16_f32 v46, v42, v43
	v_cvt_pk_bf16_f32 v47, v44, v45
	s_and_saveexec_b64 s[2:3], s[4:5]
	s_xor_b64 s[38:39], exec, s[2:3]
	s_cbranch_execz .LBB0_339
	v_lshl_add_u64 v[48:49], v[134:135], 2, v[50:51]
	global_store_dwordx4 v[48:49], v[42:45], off offset:-2048 nt sc1
	s_nop 1
	v_lshl_add_u64 v[42:43], v[134:135], 1, v[52:53]
	global_store_dwordx2 v[42:43], v[46:47], off offset:-1024 sc1
.LBB0_339:
	s_andn2_saveexec_b64 s[38:39], s[38:39]
	s_cbranch_execz .LBB0_341
	v_lshl_add_u64 v[48:49], v[140:141], 2, v[56:57]
	global_store_dwordx4 v[48:49], v[42:45], off offset:64 nt sc1
	s_nop 1
	v_lshl_add_u64 v[42:43], v[140:141], 1, v[58:59]
	global_store_dwordx2 v[42:43], v[46:47], off offset:32 sc1
.LBB0_341:
	s_or_b64 exec, exec, s[38:39]
	v_mov_b32_e32 v42, v54
	v_mov_b32_e32 v43, v54
	v_pk_mul_f32 v[40:41], v[40:41], v[42:43]
	v_pk_mul_f32 v[38:39], v[38:39], v[54:55]
	s_nop 0
	v_cvt_pk_bf16_f32 v42, v38, v39
	v_cvt_pk_bf16_f32 v43, v40, v41
	s_and_saveexec_b64 s[2:3], s[8:9]
	s_xor_b64 s[38:39], exec, s[2:3]
	s_cbranch_execz .LBB0_343
	v_mov_b32_e32 v123, v135
	v_lshl_add_u64 v[44:45], v[122:123], 2, v[50:51]
	global_store_dwordx4 v[44:45], v[38:41], off offset:-2048 nt sc1
	s_nop 1
	v_lshl_add_u64 v[38:39], v[122:123], 1, v[52:53]
	global_store_dwordx2 v[38:39], v[42:43], off offset:-1024 sc1
.LBB0_343:
	s_andn2_saveexec_b64 s[38:39], s[38:39]
	s_cbranch_execz .LBB0_345
	v_lshl_add_u64 v[44:45], v[140:141], 2, v[56:57]
	global_store_dwordx4 v[44:45], v[38:41], off offset:512 nt sc1
	s_nop 1
	v_lshl_add_u64 v[38:39], v[140:141], 1, v[58:59]
	global_store_dwordx2 v[38:39], v[42:43], off offset:256 sc1
.LBB0_345:
	s_or_b64 exec, exec, s[38:39]
	v_mov_b32_e32 v38, v54
	v_mov_b32_e32 v39, v54
	v_pk_mul_f32 v[36:37], v[36:37], v[38:39]
	v_pk_mul_f32 v[34:35], v[34:35], v[54:55]
	s_nop 0
	v_cvt_pk_bf16_f32 v38, v34, v35
	v_cvt_pk_bf16_f32 v39, v36, v37
	s_and_saveexec_b64 s[2:3], s[6:7]
	s_xor_b64 s[38:39], exec, s[2:3]
	s_cbranch_execz .LBB0_347
	v_mov_b32_e32 v119, v135
	v_lshl_add_u64 v[40:41], v[118:119], 2, v[50:51]
	global_store_dwordx4 v[40:41], v[34:37], off offset:-2048 nt sc1
	s_nop 1
	v_lshl_add_u64 v[34:35], v[118:119], 1, v[52:53]
	global_store_dwordx2 v[34:35], v[38:39], off offset:-1024 sc1
.LBB0_347:
	s_andn2_saveexec_b64 s[38:39], s[38:39]
	s_cbranch_execz .LBB0_349
	v_lshl_add_u64 v[40:41], v[140:141], 2, v[56:57]
	global_store_dwordx4 v[40:41], v[34:37], off offset:576 nt sc1
	s_nop 1
	v_lshl_add_u64 v[34:35], v[140:141], 1, v[58:59]
	global_store_dwordx2 v[34:35], v[38:39], off offset:288 sc1
.LBB0_349:
	s_or_b64 exec, exec, s[38:39]
	v_fmamk_f32 v34, v175, 0x3a800000, v173
	v_rsq_f32_e32 v38, v34
	v_lshlrev_b64 v[40:41], 11, v[144:145]
	v_lshlrev_b64 v[42:43], 10, v[144:145]
	v_lshl_add_u64 v[34:35], s[34:35], 0, v[40:41]
	v_lshl_add_u64 v[36:37], s[36:37], 0, v[42:43]
	v_pk_mul_f32 v[32:33], v[32:33], v[38:39] op_sel_hi:[1,0]
	v_pk_mul_f32 v[30:31], v[30:31], v[38:39] op_sel_hi:[1,0]
	s_nop 0
	v_cvt_pk_bf16_f32 v44, v30, v31
	v_cvt_pk_bf16_f32 v45, v32, v33
	s_and_saveexec_b64 s[2:3], vcc
	s_xor_b64 s[38:39], exec, s[2:3]
	s_cbranch_execz .LBB0_351
	v_mov_b32_e32 v46, v140
	v_mov_b32_e32 v47, v135
	v_lshl_add_u64 v[48:49], v[46:47], 2, v[34:35]
	global_store_dwordx4 v[48:49], v[30:33], off offset:-2048 nt sc1
	s_nop 1
	v_lshl_add_u64 v[30:31], v[46:47], 1, v[36:37]
	global_store_dwordx2 v[30:31], v[44:45], off offset:-1024 sc1
.LBB0_351:
	s_or_saveexec_b64 s[38:39], s[38:39]
	v_lshl_add_u64 v[40:41], s[28:29], 0, v[40:41]
	v_lshl_add_u64 v[42:43], s[30:31], 0, v[42:43]
	s_xor_b64 exec, exec, s[38:39]
	s_cbranch_execz .LBB0_353
	v_lshl_add_u64 v[46:47], v[140:141], 2, v[40:41]
	global_store_dwordx4 v[46:47], v[30:33], off nt sc1
	s_nop 1
	v_lshl_add_u64 v[30:31], v[140:141], 1, v[42:43]
	global_store_dwordx2 v[30:31], v[44:45], off sc1
.LBB0_353:
	s_or_b64 exec, exec, s[38:39]
	v_mov_b32_e32 v39, v38
	v_mov_b32_e32 v30, v38
	v_mov_b32_e32 v31, v38
	v_pk_mul_f32 v[28:29], v[28:29], v[30:31]
	v_pk_mul_f32 v[26:27], v[26:27], v[38:39]
	s_nop 0
	v_cvt_pk_bf16_f32 v30, v26, v27
	v_cvt_pk_bf16_f32 v31, v28, v29
	s_and_saveexec_b64 s[2:3], s[4:5]
	s_xor_b64 s[38:39], exec, s[2:3]
	s_cbranch_execz .LBB0_355
	v_lshl_add_u64 v[32:33], v[134:135], 2, v[34:35]
	global_store_dwordx4 v[32:33], v[26:29], off offset:-2048 nt sc1
	s_nop 1
	v_lshl_add_u64 v[26:27], v[134:135], 1, v[36:37]
	global_store_dwordx2 v[26:27], v[30:31], off offset:-1024 sc1
.LBB0_355:
	s_andn2_saveexec_b64 s[38:39], s[38:39]
	s_cbranch_execz .LBB0_357
	v_lshl_add_u64 v[32:33], v[140:141], 2, v[40:41]
	global_store_dwordx4 v[32:33], v[26:29], off offset:64 nt sc1
	s_nop 1
	v_lshl_add_u64 v[26:27], v[140:141], 1, v[42:43]
	global_store_dwordx2 v[26:27], v[30:31], off offset:32 sc1
.LBB0_357:
	s_or_b64 exec, exec, s[38:39]
	v_mov_b32_e32 v26, v38
	v_mov_b32_e32 v27, v38
	v_pk_mul_f32 v[24:25], v[24:25], v[26:27]
	v_pk_mul_f32 v[22:23], v[22:23], v[38:39]
	s_nop 0
	v_cvt_pk_bf16_f32 v26, v22, v23
	v_cvt_pk_bf16_f32 v27, v24, v25
	s_and_saveexec_b64 s[2:3], s[8:9]
	s_xor_b64 s[38:39], exec, s[2:3]
	s_cbranch_execz .LBB0_359
	v_mov_b32_e32 v123, v135
	v_lshl_add_u64 v[28:29], v[122:123], 2, v[34:35]
	global_store_dwordx4 v[28:29], v[22:25], off offset:-2048 nt sc1
	s_nop 1
	v_lshl_add_u64 v[22:23], v[122:123], 1, v[36:37]
	global_store_dwordx2 v[22:23], v[26:27], off offset:-1024 sc1
.LBB0_359:
	s_andn2_saveexec_b64 s[38:39], s[38:39]
	s_cbranch_execz .LBB0_361
	v_lshl_add_u64 v[28:29], v[140:141], 2, v[40:41]
	global_store_dwordx4 v[28:29], v[22:25], off offset:512 nt sc1
	s_nop 1
	v_lshl_add_u64 v[22:23], v[140:141], 1, v[42:43]
	global_store_dwordx2 v[22:23], v[26:27], off offset:256 sc1
.LBB0_361:
	s_or_b64 exec, exec, s[38:39]
	v_mov_b32_e32 v22, v38
	v_mov_b32_e32 v23, v38
	v_pk_mul_f32 v[20:21], v[20:21], v[22:23]
	v_pk_mul_f32 v[18:19], v[18:19], v[38:39]
	s_nop 0
	v_cvt_pk_bf16_f32 v22, v18, v19
	v_cvt_pk_bf16_f32 v23, v20, v21
	s_and_saveexec_b64 s[2:3], s[6:7]
	s_xor_b64 s[38:39], exec, s[2:3]
	s_cbranch_execz .LBB0_363
	v_mov_b32_e32 v119, v135
	v_lshl_add_u64 v[24:25], v[118:119], 2, v[34:35]
	global_store_dwordx4 v[24:25], v[18:21], off offset:-2048 nt sc1
	s_nop 1
	v_lshl_add_u64 v[18:19], v[118:119], 1, v[36:37]
	global_store_dwordx2 v[18:19], v[22:23], off offset:-1024 sc1
.LBB0_363:
	s_andn2_saveexec_b64 s[38:39], s[38:39]
	s_cbranch_execz .LBB0_365
	v_lshl_add_u64 v[24:25], v[140:141], 2, v[40:41]
	global_store_dwordx4 v[24:25], v[18:21], off offset:576 nt sc1
	s_nop 1
	v_lshl_add_u64 v[18:19], v[140:141], 1, v[42:43]
	global_store_dwordx2 v[18:19], v[22:23], off offset:288 sc1
.LBB0_365:
	s_or_b64 exec, exec, s[38:39]
	v_fmamk_f32 v18, v174, 0x3a800000, v173
	v_rsq_f32_e32 v24, v18
	v_lshlrev_b64 v[22:23], 11, v[142:143]
	v_lshlrev_b64 v[26:27], 10, v[142:143]
	v_lshl_add_u64 v[18:19], s[34:35], 0, v[22:23]
	v_lshl_add_u64 v[20:21], s[36:37], 0, v[26:27]
	v_pk_mul_f32 v[16:17], v[16:17], v[24:25] op_sel_hi:[1,0]
	v_pk_mul_f32 v[14:15], v[14:15], v[24:25] op_sel_hi:[1,0]
	s_nop 0
	v_cvt_pk_bf16_f32 v28, v14, v15
	v_cvt_pk_bf16_f32 v29, v16, v17
	s_and_saveexec_b64 s[2:3], vcc
	s_xor_b64 s[34:35], exec, s[2:3]
	s_cbranch_execz .LBB0_367
	v_mov_b32_e32 v30, v140
	v_mov_b32_e32 v31, v135
	v_lshl_add_u64 v[32:33], v[30:31], 2, v[18:19]
	global_store_dwordx4 v[32:33], v[14:17], off offset:-2048 nt sc1
	s_nop 1
	v_lshl_add_u64 v[14:15], v[30:31], 1, v[20:21]
	global_store_dwordx2 v[14:15], v[28:29], off offset:-1024 sc1
.LBB0_367:
	s_or_saveexec_b64 s[34:35], s[34:35]
	v_lshl_add_u64 v[22:23], s[28:29], 0, v[22:23]
	v_lshl_add_u64 v[26:27], s[30:31], 0, v[26:27]
	s_xor_b64 exec, exec, s[34:35]
	s_cbranch_execz .LBB0_369
	v_lshl_add_u64 v[30:31], v[140:141], 2, v[22:23]
	global_store_dwordx4 v[30:31], v[14:17], off nt sc1
	s_nop 1
	v_lshl_add_u64 v[14:15], v[140:141], 1, v[26:27]
	global_store_dwordx2 v[14:15], v[28:29], off sc1
.LBB0_369:
	s_or_b64 exec, exec, s[34:35]
	v_mov_b32_e32 v25, v24
	v_mov_b32_e32 v14, v24
	v_mov_b32_e32 v15, v24
	v_pk_mul_f32 v[12:13], v[12:13], v[14:15]
	v_pk_mul_f32 v[10:11], v[10:11], v[24:25]
	s_nop 0
	v_cvt_pk_bf16_f32 v14, v10, v11
	v_cvt_pk_bf16_f32 v15, v12, v13
	s_and_saveexec_b64 s[2:3], s[4:5]
	s_xor_b64 s[4:5], exec, s[2:3]
	s_cbranch_execz .LBB0_371
	v_lshl_add_u64 v[16:17], v[134:135], 2, v[18:19]
	global_store_dwordx4 v[16:17], v[10:13], off offset:-2048 nt sc1
	s_nop 1
	v_lshl_add_u64 v[10:11], v[134:135], 1, v[20:21]
	global_store_dwordx2 v[10:11], v[14:15], off offset:-1024 sc1
.LBB0_371:
	s_andn2_saveexec_b64 s[4:5], s[4:5]
	s_cbranch_execz .LBB0_373
	v_lshl_add_u64 v[16:17], v[140:141], 2, v[22:23]
	global_store_dwordx4 v[16:17], v[10:13], off offset:64 nt sc1
	s_nop 1
	v_lshl_add_u64 v[10:11], v[140:141], 1, v[26:27]
	global_store_dwordx2 v[10:11], v[14:15], off offset:32 sc1
.LBB0_373:
	s_or_b64 exec, exec, s[4:5]
	v_mov_b32_e32 v10, v24
	v_mov_b32_e32 v11, v24
	v_pk_mul_f32 v[8:9], v[8:9], v[10:11]
	v_pk_mul_f32 v[6:7], v[6:7], v[24:25]
	s_nop 0
	v_cvt_pk_bf16_f32 v10, v6, v7
	v_cvt_pk_bf16_f32 v11, v8, v9
	s_and_saveexec_b64 s[2:3], s[8:9]
	s_xor_b64 s[4:5], exec, s[2:3]
	s_cbranch_execz .LBB0_375
	v_mov_b32_e32 v123, v135
	v_lshl_add_u64 v[12:13], v[122:123], 2, v[18:19]
	global_store_dwordx4 v[12:13], v[6:9], off offset:-2048 nt sc1
	s_nop 1
	v_lshl_add_u64 v[6:7], v[122:123], 1, v[20:21]
	global_store_dwordx2 v[6:7], v[10:11], off offset:-1024 sc1
.LBB0_375:
	s_andn2_saveexec_b64 s[4:5], s[4:5]
	s_cbranch_execz .LBB0_377
	v_lshl_add_u64 v[12:13], v[140:141], 2, v[22:23]
	global_store_dwordx4 v[12:13], v[6:9], off offset:512 nt sc1
	s_nop 1
	v_lshl_add_u64 v[6:7], v[140:141], 1, v[26:27]
	global_store_dwordx2 v[6:7], v[10:11], off offset:256 sc1
.LBB0_377:
	s_or_b64 exec, exec, s[4:5]
	v_mov_b32_e32 v6, v24
	v_mov_b32_e32 v7, v24
	v_pk_mul_f32 v[4:5], v[4:5], v[6:7]
	v_pk_mul_f32 v[2:3], v[2:3], v[24:25]
	s_nop 0
	v_cvt_pk_bf16_f32 v6, v2, v3
	v_cvt_pk_bf16_f32 v7, v4, v5
	s_and_saveexec_b64 s[2:3], s[6:7]
	s_xor_b64 s[4:5], exec, s[2:3]
	s_cbranch_execz .LBB0_380
	v_mov_b32_e32 v119, v135
	v_lshl_add_u64 v[8:9], v[118:119], 2, v[18:19]
	global_store_dwordx4 v[8:9], v[2:5], off offset:-2048 nt sc1
	s_nop 1
	v_lshl_add_u64 v[2:3], v[118:119], 1, v[20:21]
	global_store_dwordx2 v[2:3], v[6:7], off offset:-1024 sc1
	s_andn2_saveexec_b64 s[4:5], s[4:5]
	s_cbranch_execnz .LBB0_381

.LBB0_381:
	v_lshl_add_u64 v[8:9], v[140:141], 2, v[22:23]
	global_store_dwordx4 v[8:9], v[2:5], off offset:576 nt sc1
	s_nop 1
	v_lshl_add_u64 v[2:3], v[140:141], 1, v[26:27]
	global_store_dwordx2 v[2:3], v[6:7], off offset:288 sc1
	s_or_b64 exec, exec, s[4:5]
	s_andn2_b64 vcc, exec, s[18:19]
	s_mov_b64 s[4:5], -1
	s_cbranch_vccnz .LBB0_242

.LBB0_406:
	s_or_b64 exec, exec, s[2:3]
	s_waitcnt vmcnt(0)
	v_cmp_eq_u32_e32 vcc, 0, v197
	s_barrier
	s_and_saveexec_b64 s[2:3], vcc
	s_cbranch_execz .LBB0_409
	s_mov_b64 s[20:21], exec
	v_mbcnt_lo_u32_b32 v2, s20, 0
	s_nop 0
	s_waitcnt vmcnt(0)
	s_waitcnt vmcnt(0)
	v_mbcnt_hi_u32_b32 v2, s21, v2
	v_cmp_eq_u32_e32 vcc, 0, v2
	s_and_b64 s[22:23], exec, vcc
	s_mov_b64 exec, s[22:23]
	s_cbranch_execz .LBB0_409
	s_bcnt1_i32_b64 s20, s[20:21]
	v_mov_b32_e32 v4, s20
	v_mov_b32_e32 v2, 0x1c4000
	global_atomic_add v2, v4, s[36:37]

.LBB0_464:
	s_or_b64 exec, exec, s[20:21]
	s_lshl_b32 s20, s29, 2
	s_add_i32 s20, s20, 0
	v_lshl_add_u32 v2, v212, 2, s20
	s_waitcnt vmcnt(0) lgkmcnt(0)
	s_barrier
	v_add_u32_e32 v168, 0x1000, v2
	ds_read2_b32 v[166:167], v168 offset1:16
	v_lshlrev_b64 v[148:149], 12, v[148:149]
	v_lshl_add_u64 v[148:149], s[46:47], 0, v[148:149]
	v_lshlrev_b64 v[146:147], 2, v[146:147]
	v_lshl_add_u64 v[148:149], v[148:149], 0, v[146:147]
	s_waitcnt lgkmcnt(0)
	v_pk_mul_f32 v[118:119], v[118:119], v[166:167] op_sel_hi:[1,0]
	v_pk_mul_f32 v[116:117], v[116:117], v[166:167] op_sel_hi:[1,0]
	s_waitcnt vmcnt(0)
	v_pk_mul_f32 v[118:119], v[6:7], v[118:119]
	v_pk_mul_f32 v[116:117], v[4:5], v[116:117]
	global_store_dwordx4 v[148:149], v[116:119], off offset:576 nt sc1
	v_mov_b32_e32 v2, v167
	v_pk_mul_f32 v[106:107], v[106:107], v[2:3] op_sel_hi:[1,0]
	v_lshlrev_b64 v[116:117], 12, v[144:145]
	v_lshl_add_u64 v[116:117], s[46:47], 0, v[116:117]
	v_pk_mul_f32 v[104:105], v[104:105], v[2:3] op_sel_hi:[1,0]
	v_lshl_add_u64 v[116:117], v[116:117], 0, v[146:147]
	v_pk_mul_f32 v[106:107], v[10:11], v[106:107]
	v_pk_mul_f32 v[104:105], v[8:9], v[104:105]
	global_store_dwordx4 v[116:117], v[104:107], off offset:512 nt sc1
	ds_read2_b32 v[104:105], v168 offset0:32 offset1:48
	v_pk_mul_f32 v[98:99], v[98:99], v[2:3] op_sel_hi:[1,0]
	v_pk_mul_f32 v[96:97], v[96:97], v[2:3] op_sel_hi:[1,0]
	v_pk_mul_f32 v[98:99], v[6:7], v[98:99]
	v_pk_mul_f32 v[96:97], v[4:5], v[96:97]
	global_store_dwordx4 v[116:117], v[96:99], off offset:576 nt sc1
	s_waitcnt lgkmcnt(0)
	v_pk_mul_f32 v[82:83], v[82:83], v[104:105] op_sel_hi:[1,0]
	v_pk_mul_f32 v[80:81], v[80:81], v[104:105] op_sel_hi:[1,0]
	v_lshlrev_b64 v[96:97], 12, v[142:143]
	v_lshl_add_u64 v[96:97], s[46:47], 0, v[96:97]
	v_lshl_add_u64 v[106:107], v[96:97], 0, v[146:147]
	v_pk_mul_f32 v[82:83], v[6:7], v[82:83]
	v_pk_mul_f32 v[80:81], v[4:5], v[80:81]
	v_pk_mul_f32 v[114:115], v[114:115], v[2:3] op_sel_hi:[1,0]
	v_pk_mul_f32 v[112:113], v[112:113], v[2:3] op_sel_hi:[1,0]
	v_pk_mul_f32 v[110:111], v[110:111], v[2:3] op_sel_hi:[1,0]
	v_pk_mul_f32 v[108:109], v[108:109], v[2:3] op_sel_hi:[1,0]
	v_pk_mul_f32 v[90:91], v[90:91], v[104:105] op_sel_hi:[1,0]
	v_pk_mul_f32 v[88:89], v[88:89], v[104:105] op_sel_hi:[1,0]
	global_store_dwordx4 v[106:107], v[80:83], off offset:576 nt sc1
	v_mov_b32_e32 v2, v105
	v_pk_mul_f32 v[90:91], v[10:11], v[90:91]
	v_lshlrev_b64 v[80:81], 12, v[140:141]
	v_pk_mul_f32 v[88:89], v[8:9], v[88:89]
	v_lshl_add_u64 v[80:81], s[46:47], 0, v[80:81]
	v_pk_mul_f32 v[74:75], v[74:75], v[2:3] op_sel_hi:[1,0]
	v_pk_mul_f32 v[72:73], v[72:73], v[2:3] op_sel_hi:[1,0]
	global_store_dwordx4 v[106:107], v[88:91], off offset:512 nt sc1
	v_pk_mul_f32 v[74:75], v[10:11], v[74:75]
	v_pk_mul_f32 v[72:73], v[8:9], v[72:73]
	v_lshl_add_u64 v[88:89], v[80:81], 0, v[146:147]
	global_store_dwordx4 v[88:89], v[72:75], off offset:512 nt sc1
	ds_read2_b32 v[72:73], v168 offset0:128 offset1:144
	v_pk_mul_f32 v[70:71], v[70:71], v[2:3] op_sel_hi:[1,0]
	v_pk_mul_f32 v[68:69], v[68:69], v[2:3] op_sel_hi:[1,0]
	v_pk_mul_f32 v[70:71], v[6:7], v[70:71]
	v_pk_mul_f32 v[68:69], v[4:5], v[68:69]
	global_store_dwordx4 v[88:89], v[68:71], off offset:576 nt sc1
	s_waitcnt lgkmcnt(0)
	v_pk_mul_f32 v[50:51], v[50:51], v[72:73] op_sel_hi:[1,0]
	v_pk_mul_f32 v[48:49], v[48:49], v[72:73] op_sel_hi:[1,0]
	v_lshlrev_b64 v[68:69], 12, v[138:139]
	v_lshl_add_u64 v[68:69], s[46:47], 0, v[68:69]
	v_lshl_add_u64 v[68:69], v[68:69], 0, v[146:147]
	v_pk_mul_f32 v[50:51], v[6:7], v[50:51]
	v_pk_mul_f32 v[48:49], v[4:5], v[48:49]
	v_pk_mul_f32 v[80:81], v[86:87], v[2:3] op_sel_hi:[1,0]
	v_pk_mul_f32 v[84:85], v[84:85], v[2:3] op_sel_hi:[1,0]
	v_pk_mul_f32 v[78:79], v[78:79], v[2:3] op_sel_hi:[1,0]
	v_pk_mul_f32 v[76:77], v[76:77], v[2:3] op_sel_hi:[1,0]
	v_pk_mul_f32 v[58:59], v[58:59], v[72:73] op_sel_hi:[1,0]
	v_pk_mul_f32 v[56:57], v[56:57], v[72:73] op_sel_hi:[1,0]
	global_store_dwordx4 v[68:69], v[48:51], off offset:576 nt sc1
	v_mov_b32_e32 v2, v73
	v_pk_mul_f32 v[58:59], v[10:11], v[58:59]
	v_lshlrev_b64 v[48:49], 12, v[136:137]
	v_pk_mul_f32 v[56:57], v[8:9], v[56:57]
	v_lshl_add_u64 v[48:49], s[46:47], 0, v[48:49]
	v_pk_mul_f32 v[42:43], v[42:43], v[2:3] op_sel_hi:[1,0]
	v_pk_mul_f32 v[40:41], v[40:41], v[2:3] op_sel_hi:[1,0]
	global_store_dwordx4 v[68:69], v[56:59], off offset:512 nt sc1
	v_pk_mul_f32 v[42:43], v[10:11], v[42:43]
	v_pk_mul_f32 v[40:41], v[8:9], v[40:41]
	v_lshl_add_u64 v[56:57], v[48:49], 0, v[146:147]
	global_store_dwordx4 v[56:57], v[40:43], off offset:512 nt sc1
	ds_read2_b32 v[40:41], v168 offset0:160 offset1:176
	v_pk_mul_f32 v[34:35], v[34:35], v[2:3] op_sel_hi:[1,0]
	v_pk_mul_f32 v[32:33], v[32:33], v[2:3] op_sel_hi:[1,0]
	v_pk_mul_f32 v[34:35], v[6:7], v[34:35]
	v_pk_mul_f32 v[32:33], v[4:5], v[32:33]
	global_store_dwordx4 v[56:57], v[32:35], off offset:576 nt sc1
	s_waitcnt lgkmcnt(0)
	v_pk_mul_f32 v[30:31], v[30:31], v[40:41] op_sel_hi:[1,0]
	v_pk_mul_f32 v[28:29], v[28:29], v[40:41] op_sel_hi:[1,0]
	v_lshlrev_b64 v[32:33], 12, v[134:135]
	v_lshl_add_u64 v[32:33], s[46:47], 0, v[32:33]
	v_pk_mul_f32 v[26:27], v[26:27], v[40:41] op_sel_hi:[1,0]
	v_pk_mul_f32 v[24:25], v[24:25], v[40:41] op_sel_hi:[1,0]
	v_lshl_add_u64 v[42:43], v[32:33], 0, v[146:147]
	v_pk_mul_f32 v[30:31], v[14:15], v[30:31]
	v_pk_mul_f32 v[28:29], v[12:13], v[28:29]
	v_pk_mul_f32 v[26:27], v[10:11], v[26:27]
	v_pk_mul_f32 v[24:25], v[8:9], v[24:25]
	global_store_dwordx4 v[42:43], v[28:31], off offset:64 nt sc1
	global_store_dwordx4 v[42:43], v[24:27], off offset:512 nt sc1
	v_pk_mul_f32 v[48:49], v[54:55], v[2:3] op_sel_hi:[1,0]
	v_pk_mul_f32 v[28:29], v[158:159], v[40:41] op_sel_hi:[1,0]
	v_pk_mul_f32 v[24:25], v[156:157], v[40:41] op_sel_hi:[1,0]
	v_pk_mul_f32 v[52:53], v[52:53], v[2:3] op_sel_hi:[1,0]
	v_pk_mul_f32 v[26:27], v[6:7], v[24:25]
	v_pk_mul_f32 v[24:25], v[4:5], v[28:29]
	v_pk_mul_f32 v[46:47], v[46:47], v[2:3] op_sel_hi:[1,0]
	v_pk_mul_f32 v[44:45], v[44:45], v[2:3] op_sel_hi:[1,0]
	global_store_dwordx4 v[42:43], v[24:27], off offset:576 nt sc1
	v_mov_b32_e32 v2, v41
	v_pk_mul_f32 v[130:131], v[130:131], v[166:167] op_sel_hi:[1,0]
	v_lshlrev_b64 v[24:25], 12, v[132:133]
	v_pk_mul_f32 v[128:129], v[128:129], v[166:167] op_sel_hi:[1,0]
	v_pk_mul_f32 v[96:97], v[102:103], v[104:105] op_sel_hi:[1,0]
	v_pk_mul_f32 v[100:101], v[100:101], v[104:105] op_sel_hi:[1,0]
	v_pk_mul_f32 v[66:67], v[66:67], v[72:73] op_sel_hi:[1,0]
	v_pk_mul_f32 v[64:65], v[64:65], v[72:73] op_sel_hi:[1,0]
	v_pk_mul_f32 v[32:33], v[38:39], v[40:41] op_sel_hi:[1,0]
	v_pk_mul_f32 v[36:37], v[36:37], v[40:41] op_sel_hi:[1,0]
	v_lshl_add_u64 v[24:25], s[46:47], 0, v[24:25]
	v_pk_mul_f32 v[22:23], v[22:23], v[2:3] op_sel_hi:[1,0]
	v_pk_mul_f32 v[20:21], v[20:21], v[2:3] op_sel_hi:[1,0]
	v_pk_mul_f32 v[130:131], v[18:19], v[130:131]
	v_pk_mul_f32 v[128:129], v[16:17], v[128:129]
	v_pk_mul_f32 v[114:115], v[18:19], v[114:115]
	v_pk_mul_f32 v[112:113], v[16:17], v[112:113]
	v_pk_mul_f32 v[98:99], v[18:19], v[96:97]
	v_pk_mul_f32 v[96:97], v[16:17], v[100:101]
	v_pk_mul_f32 v[82:83], v[18:19], v[80:81]
	v_pk_mul_f32 v[80:81], v[16:17], v[84:85]
	v_pk_mul_f32 v[66:67], v[18:19], v[66:67]
	v_pk_mul_f32 v[64:65], v[16:17], v[64:65]
	v_pk_mul_f32 v[50:51], v[18:19], v[48:49]
	v_pk_mul_f32 v[48:49], v[16:17], v[52:53]
	v_pk_mul_f32 v[34:35], v[18:19], v[32:33]
	v_pk_mul_f32 v[32:33], v[16:17], v[36:37]
	v_lshl_add_u64 v[24:25], v[24:25], 0, v[146:147]
	v_pk_mul_f32 v[18:19], v[18:19], v[22:23]
	v_pk_mul_f32 v[16:17], v[16:17], v[20:21]
	v_pk_mul_f32 v[126:127], v[126:127], v[166:167] op_sel_hi:[1,0]
	v_pk_mul_f32 v[124:125], v[124:125], v[166:167] op_sel_hi:[1,0]
	v_pk_mul_f32 v[94:95], v[94:95], v[104:105] op_sel_hi:[1,0]
	v_pk_mul_f32 v[92:93], v[92:93], v[104:105] op_sel_hi:[1,0]
	v_pk_mul_f32 v[62:63], v[62:63], v[72:73] op_sel_hi:[1,0]
	v_pk_mul_f32 v[60:61], v[60:61], v[72:73] op_sel_hi:[1,0]
	global_store_dwordx4 v[24:25], v[16:19], off nt sc1
	v_pk_mul_f32 v[126:127], v[14:15], v[126:127]
	v_pk_mul_f32 v[124:125], v[12:13], v[124:125]
	v_pk_mul_f32 v[16:17], v[154:155], v[2:3] op_sel_hi:[1,0]
	v_pk_mul_f32 v[18:19], v[160:161], v[2:3] op_sel_hi:[1,0]
	v_pk_mul_f32 v[110:111], v[14:15], v[110:111]
	v_pk_mul_f32 v[108:109], v[12:13], v[108:109]
	v_pk_mul_f32 v[94:95], v[14:15], v[94:95]
	v_pk_mul_f32 v[92:93], v[12:13], v[92:93]
	v_pk_mul_f32 v[78:79], v[14:15], v[78:79]
	v_pk_mul_f32 v[76:77], v[12:13], v[76:77]
	v_pk_mul_f32 v[62:63], v[14:15], v[62:63]
	v_pk_mul_f32 v[60:61], v[12:13], v[60:61]
	v_pk_mul_f32 v[46:47], v[14:15], v[46:47]
	v_pk_mul_f32 v[44:45], v[12:13], v[44:45]
	v_pk_mul_f32 v[14:15], v[14:15], v[16:17]
	v_pk_mul_f32 v[12:13], v[12:13], v[18:19]
	v_pk_mul_f32 v[122:123], v[122:123], v[166:167] op_sel_hi:[1,0]
	v_pk_mul_f32 v[120:121], v[120:121], v[166:167] op_sel_hi:[1,0]
	global_store_dwordx4 v[24:25], v[12:15], off offset:64 nt sc1
	v_pk_mul_f32 v[122:123], v[10:11], v[122:123]
	v_pk_mul_f32 v[120:121], v[8:9], v[120:121]
	v_pk_mul_f32 v[12:13], v[152:153], v[2:3] op_sel_hi:[1,0]
	v_pk_mul_f32 v[14:15], v[162:163], v[2:3] op_sel_hi:[1,0]
	v_pk_mul_f32 v[10:11], v[10:11], v[12:13]
	v_pk_mul_f32 v[8:9], v[8:9], v[14:15]
	global_store_dwordx4 v[24:25], v[8:11], off offset:512 nt sc1
	global_store_dwordx4 v[148:149], v[128:131], off nt sc1
	global_store_dwordx4 v[148:149], v[124:127], off offset:64 nt sc1
	v_pk_mul_f32 v[8:9], v[150:151], v[2:3] op_sel_hi:[1,0]
	v_pk_mul_f32 v[10:11], v[164:165], v[2:3] op_sel_hi:[1,0]
	v_pk_mul_f32 v[6:7], v[6:7], v[8:9]
	v_pk_mul_f32 v[4:5], v[4:5], v[10:11]
	global_store_dwordx4 v[148:149], v[120:123], off offset:512 nt sc1
	global_store_dwordx4 v[116:117], v[112:115], off nt sc1
	global_store_dwordx4 v[116:117], v[108:111], off offset:64 nt sc1
	global_store_dwordx4 v[106:107], v[96:99], off nt sc1
	global_store_dwordx4 v[106:107], v[92:95], off offset:64 nt sc1
	global_store_dwordx4 v[88:89], v[80:83], off nt sc1
	global_store_dwordx4 v[88:89], v[76:79], off offset:64 nt sc1
	global_store_dwordx4 v[68:69], v[64:67], off nt sc1
	global_store_dwordx4 v[68:69], v[60:63], off offset:64 nt sc1
	global_store_dwordx4 v[56:57], v[48:51], off nt sc1
	global_store_dwordx4 v[56:57], v[44:47], off offset:64 nt sc1
	global_store_dwordx4 v[42:43], v[32:35], off nt sc1
	global_store_dwordx4 v[24:25], v[4:7], off offset:576 nt sc1

.LBB0_590:
	s_or_b64 exec, exec, s[44:45]
	v_lshl_add_u64 v[32:33], v[136:137], 2, s[42:43]
	v_lshl_add_u64 v[32:33], v[32:33], 0, v[2:3]
	s_waitcnt lgkmcnt(3)
	v_add_co_u32_e32 v34, vcc, 0x1000, v32
	s_waitcnt lgkmcnt(2)
	s_nop 0
	v_addc_co_u32_e32 v35, vcc, 0, v33, vcc
	global_load_dwordx4 v[104:107], v[32:33], off nt
	global_load_dwordx4 v[100:103], v[34:35], off nt
	v_add_co_u32_e32 v34, vcc, 0x2000, v32
	s_nop 1
	v_addc_co_u32_e32 v35, vcc, 0, v33, vcc
	v_add_co_u32_e32 v44, vcc, 0x3000, v32
	s_nop 1
	v_addc_co_u32_e32 v45, vcc, 0, v33, vcc
	global_load_dwordx4 v[112:115], v[34:35], off nt
	global_load_dwordx4 v[108:111], v[44:45], off nt
	v_add_co_u32_e32 v34, vcc, s90, v32
	s_nop 1
	v_addc_co_u32_e32 v35, vcc, 0, v33, vcc
	v_add_co_u32_e32 v44, vcc, 0x5000, v32
	s_nop 1
	v_addc_co_u32_e32 v45, vcc, 0, v33, vcc
	global_load_dwordx4 v[120:123], v[34:35], off nt
	global_load_dwordx4 v[116:119], v[44:45], off nt
	v_add_co_u32_e32 v34, vcc, s33, v32
	s_nop 1
	v_addc_co_u32_e32 v35, vcc, 0, v33, vcc
	v_add_co_u32_e32 v44, vcc, 0x7000, v32
	s_nop 1
	v_addc_co_u32_e32 v45, vcc, 0, v33, vcc
	global_load_dwordx4 v[128:131], v[34:35], off nt
	global_load_dwordx4 v[124:127], v[44:45], off nt
	v_add_co_u32_e32 v34, vcc, s92, v32
	s_nop 1
	v_addc_co_u32_e32 v35, vcc, 0, v33, vcc
	v_add_co_u32_e32 v44, vcc, 0x9000, v32
	s_nop 1
	v_addc_co_u32_e32 v45, vcc, 0, v33, vcc
	global_load_dwordx4 v[96:99], v[34:35], off nt
	global_load_dwordx4 v[92:95], v[44:45], off nt
	v_add_co_u32_e32 v34, vcc, s93, v32
	s_nop 1
	v_addc_co_u32_e32 v35, vcc, 0, v33, vcc
	v_add_co_u32_e32 v44, vcc, 0xb000, v32
	s_nop 1
	v_addc_co_u32_e32 v45, vcc, 0, v33, vcc
	global_load_dwordx4 v[88:91], v[34:35], off nt
	global_load_dwordx4 v[84:87], v[44:45], off nt
	v_add_co_u32_e32 v34, vcc, s6, v32
	s_nop 1
	v_addc_co_u32_e32 v35, vcc, 0, v33, vcc
	v_add_co_u32_e32 v44, vcc, 0xd000, v32
	s_nop 1
	v_addc_co_u32_e32 v45, vcc, 0, v33, vcc
	global_load_dwordx4 v[64:67], v[34:35], off nt
	global_load_dwordx4 v[56:59], v[44:45], off nt
	v_add_co_u32_e32 v34, vcc, 0xe000, v32
	s_nop 1
	v_addc_co_u32_e32 v35, vcc, 0, v33, vcc
	v_add_co_u32_e32 v32, vcc, 0xf000, v32
	s_nop 1
	v_addc_co_u32_e32 v33, vcc, 0, v33, vcc
	s_waitcnt lgkmcnt(0)
	global_load_dwordx4 v[44:47], v[34:35], off nt
	s_nop 0
	global_load_dwordx4 v[32:35], v[32:33], off nt
	s_movk_i32 s1, 0x80
	v_cmp_gt_i32_e64 s[42:43], s1, v132
	v_ashrrev_i32_e32 v133, 31, v132
	v_lshl_add_u32 v2, v132, 2, 0
	s_barrier
	s_and_saveexec_b64 s[44:45], s[42:43]
	s_cbranch_execz .LBB0_592
	ds_read2st64_b32 v[136:137], v2 offset0:8 offset1:10
	v_readlane_b32 s46, v254, 39
	v_readlane_b32 s47, v254, 40
	s_waitcnt lgkmcnt(0)
	v_add_f32_e32 v136, 0, v136
	v_add_f32_e32 v147, v136, v137
	ds_read2st64_b32 v[136:137], v2 offset0:12 offset1:14
	s_waitcnt lgkmcnt(0)
	v_add_f32_e32 v136, v147, v136
	v_add_f32_e32 v147, v136, v137
	ds_read2st64_b32 v[136:137], v2 offset0:16 offset1:18
	s_waitcnt lgkmcnt(0)
	v_add_f32_e32 v136, v147, v136
	v_add_f32_e32 v147, v136, v137
	ds_read2st64_b32 v[136:137], v2 offset0:20 offset1:22
	s_waitcnt lgkmcnt(0)
	v_add_f32_e32 v136, v147, v136
	v_add_f32_e32 v147, v136, v137
	v_lshlrev_b64 v[136:137], 1, v[132:133]
	v_lshl_add_u64 v[148:149], s[46:47], 0, v[136:137]
	global_load_ushort v148, v[148:149], off
	v_readlane_b32 s46, v255, 4
	v_readlane_b32 s47, v255, 5
	s_waitcnt vmcnt(0)
	v_lshlrev_b32_e32 v148, 16, v148
	v_mul_f32_e32 v147, v147, v148
	v_cvt_pk_bf16_f32 v147, v147, s0
	v_lshl_add_u64 v[136:137], s[46:47], 0, v[136:137]
	global_store_short v[136:137], v147, off sc1

.LBB0_626:
	s_or_b64 exec, exec, s[38:39]
	s_waitcnt lgkmcnt(0)
	s_barrier
	s_and_saveexec_b64 s[38:39], s[42:43]
	s_cbranch_execz .LBB0_538
	ds_read2st64_b32 v[4:5], v2 offset0:8 offset1:10
	v_readlane_b32 s40, v255, 6
	v_readlane_b32 s41, v255, 7
	s_waitcnt lgkmcnt(0)
	v_add_f32_e32 v4, 0, v4
	v_add_f32_e32 v6, v4, v5
	ds_read2st64_b32 v[4:5], v2 offset0:12 offset1:14
	s_waitcnt lgkmcnt(0)
	v_add_f32_e32 v4, v6, v4
	v_add_f32_e32 v6, v4, v5
	ds_read2st64_b32 v[4:5], v2 offset0:16 offset1:18
	s_waitcnt lgkmcnt(0)
	v_add_f32_e32 v4, v6, v4
	v_add_f32_e32 v6, v4, v5
	ds_read2st64_b32 v[4:5], v2 offset0:20 offset1:22
	s_waitcnt lgkmcnt(0)
	v_add_f32_e32 v2, v6, v4
	v_add_f32_e32 v2, v2, v5
	v_lshlrev_b64 v[4:5], 1, v[132:133]
	v_lshl_add_u64 v[6:7], s[40:41], 0, v[4:5]
	global_load_ushort v6, v[6:7], off
	v_readlane_b32 s40, v255, 2
	v_readlane_b32 s41, v255, 3
	s_waitcnt vmcnt(0)
	v_lshlrev_b32_e32 v6, 16, v6
	v_mul_f32_e32 v2, v2, v6
	v_cvt_pk_bf16_f32 v2, v2, s0
	v_lshl_add_u64 v[4:5], s[40:41], 0, v[4:5]
	global_store_short v[4:5], v2, off sc1
	s_branch .LBB0_538

.LBB0_672:
	s_waitcnt lgkmcnt(0)
	s_barrier
	ds_read_b128 v[4:7], v181
	v_add_u32_e32 v2, v172, v173
	s_mov_b32 s24, 0xbfb8aa3b
	s_ashr_i32 s31, s30, 31
	s_waitcnt lgkmcnt(0)
	v_lshlrev_b32_e32 v8, 16, v4
	v_and_b32_e32 v9, 0xffff0000, v4
	v_lshlrev_b32_e32 v4, 16, v5
	v_and_b32_e32 v5, 0xffff0000, v5
	v_lshlrev_b32_e32 v10, 16, v6
	v_and_b32_e32 v11, 0xffff0000, v6
	v_lshlrev_b32_e32 v6, 16, v7
	v_and_b32_e32 v7, 0xffff0000, v7
	v_pk_fma_f32 v[12:13], v[74:75], v[4:5], v[106:107]
	v_pk_fma_f32 v[14:15], v[70:71], v[6:7], v[102:103]
	ds_read_b128 v[4:7], v181 offset:144
	v_pk_fma_f32 v[8:9], v[72:73], v[8:9], v[104:105]
	v_pk_fma_f32 v[10:11], v[68:69], v[10:11], v[100:101]
	s_lshl_b64 s[38:39], s[30:31], 12
	v_cmp_lt_i32_e32 vcc, v236, v235
	s_waitcnt lgkmcnt(0)
	v_lshlrev_b32_e32 v16, 16, v4
	v_and_b32_e32 v17, 0xffff0000, v4
	v_lshlrev_b32_e32 v4, 16, v5
	v_and_b32_e32 v5, 0xffff0000, v5
	v_lshlrev_b32_e32 v18, 16, v6
	v_and_b32_e32 v19, 0xffff0000, v6
	v_lshlrev_b32_e32 v6, 16, v7
	v_and_b32_e32 v7, 0xffff0000, v7
	v_pk_fma_f32 v[12:13], v[78:79], v[4:5], v[12:13]
	v_pk_fma_f32 v[14:15], v[86:87], v[6:7], v[14:15]
	ds_read_b128 v[4:7], v181 offset:288
	v_pk_fma_f32 v[8:9], v[76:77], v[16:17], v[8:9]
	v_pk_fma_f32 v[10:11], v[84:85], v[18:19], v[10:11]
	s_waitcnt lgkmcnt(0)
	v_lshlrev_b32_e32 v16, 16, v4
	v_and_b32_e32 v17, 0xffff0000, v4
	v_lshlrev_b32_e32 v4, 16, v5
	v_and_b32_e32 v5, 0xffff0000, v5
	v_lshlrev_b32_e32 v18, 16, v6
	v_and_b32_e32 v19, 0xffff0000, v6
	v_lshlrev_b32_e32 v6, 16, v7
	v_and_b32_e32 v7, 0xffff0000, v7
	v_pk_fma_f32 v[8:9], v[80:81], v[16:17], v[8:9]
	v_pk_fma_f32 v[12:13], v[82:83], v[4:5], v[12:13]
	v_pk_fma_f32 v[16:17], v[88:89], v[18:19], v[10:11]
	v_pk_fma_f32 v[10:11], v[90:91], v[6:7], v[14:15]
	ds_read_b128 v[4:7], v181 offset:432
	s_waitcnt lgkmcnt(0)
	v_lshlrev_b32_e32 v14, 16, v4
	v_and_b32_e32 v15, 0xffff0000, v4
	v_lshlrev_b32_e32 v4, 16, v5
	v_and_b32_e32 v5, 0xffff0000, v5
	v_lshlrev_b32_e32 v18, 16, v6
	v_and_b32_e32 v19, 0xffff0000, v6
	v_lshlrev_b32_e32 v20, 16, v7
	v_and_b32_e32 v21, 0xffff0000, v7
	v_pk_fma_f32 v[6:7], v[94:95], v[4:5], v[12:13]
	v_pk_fma_f32 v[4:5], v[92:93], v[14:15], v[8:9]
	v_pk_fma_f32 v[10:11], v[98:99], v[20:21], v[10:11]
	v_pk_fma_f32 v[8:9], v[96:97], v[18:19], v[16:17]
	v_cvt_pk_bf16_f32 v12, v4, v5
	v_cvt_pk_bf16_f32 v13, v6, v7
	v_cvt_pk_bf16_f32 v14, v8, v9
	v_cvt_pk_bf16_f32 v15, v10, v11
	ds_write_b128 v181, v[12:15] offset:18880
	ds_write_b128 v2, v[4:7] offset:37312
	ds_write_b128 v2, v[8:11] offset:37328
	ds_read_b128 v[4:7], v181 offset:9216
	v_add_u32_e32 v2, 0xc0, v174
	s_waitcnt lgkmcnt(0)
	v_lshlrev_b32_e32 v8, 16, v4
	v_and_b32_e32 v9, 0xffff0000, v4
	v_lshlrev_b32_e32 v4, 16, v5
	v_and_b32_e32 v5, 0xffff0000, v5
	v_lshlrev_b32_e32 v10, 16, v6
	v_and_b32_e32 v11, 0xffff0000, v6
	v_lshlrev_b32_e32 v6, 16, v7
	v_and_b32_e32 v7, 0xffff0000, v7
	v_pk_fma_f32 v[12:13], v[74:75], v[4:5], v[106:107]
	v_pk_fma_f32 v[14:15], v[70:71], v[6:7], v[102:103]
	ds_read_b128 v[4:7], v181 offset:9360
	v_pk_fma_f32 v[8:9], v[72:73], v[8:9], v[104:105]
	v_pk_fma_f32 v[10:11], v[68:69], v[10:11], v[100:101]
	s_waitcnt lgkmcnt(0)
	v_lshlrev_b32_e32 v16, 16, v4
	v_and_b32_e32 v17, 0xffff0000, v4
	v_lshlrev_b32_e32 v4, 16, v5
	v_and_b32_e32 v5, 0xffff0000, v5
	v_lshlrev_b32_e32 v18, 16, v6
	v_and_b32_e32 v19, 0xffff0000, v6
	v_lshlrev_b32_e32 v6, 16, v7
	v_and_b32_e32 v7, 0xffff0000, v7
	v_pk_fma_f32 v[12:13], v[78:79], v[4:5], v[12:13]
	v_pk_fma_f32 v[14:15], v[86:87], v[6:7], v[14:15]
	ds_read_b128 v[4:7], v181 offset:9504
	v_pk_fma_f32 v[8:9], v[76:77], v[16:17], v[8:9]
	v_pk_fma_f32 v[10:11], v[84:85], v[18:19], v[10:11]
	s_waitcnt lgkmcnt(0)
	v_lshlrev_b32_e32 v16, 16, v4
	v_and_b32_e32 v17, 0xffff0000, v4
	v_lshlrev_b32_e32 v4, 16, v5
	v_and_b32_e32 v5, 0xffff0000, v5
	v_lshlrev_b32_e32 v18, 16, v6
	v_and_b32_e32 v19, 0xffff0000, v6
	v_lshlrev_b32_e32 v6, 16, v7
	v_and_b32_e32 v7, 0xffff0000, v7
	v_pk_fma_f32 v[8:9], v[80:81], v[16:17], v[8:9]
	v_pk_fma_f32 v[12:13], v[82:83], v[4:5], v[12:13]
	v_pk_fma_f32 v[16:17], v[88:89], v[18:19], v[10:11]
	v_pk_fma_f32 v[10:11], v[90:91], v[6:7], v[14:15]
	ds_read_b128 v[4:7], v181 offset:9648
	s_waitcnt lgkmcnt(0)
	v_lshlrev_b32_e32 v14, 16, v4
	v_and_b32_e32 v15, 0xffff0000, v4
	v_lshlrev_b32_e32 v4, 16, v5
	v_and_b32_e32 v5, 0xffff0000, v5
	v_lshlrev_b32_e32 v18, 16, v6
	v_and_b32_e32 v19, 0xffff0000, v6
	v_lshlrev_b32_e32 v20, 16, v7
	v_and_b32_e32 v21, 0xffff0000, v7
	v_pk_fma_f32 v[6:7], v[94:95], v[4:5], v[12:13]
	v_pk_fma_f32 v[4:5], v[92:93], v[14:15], v[8:9]
	v_pk_fma_f32 v[10:11], v[98:99], v[20:21], v[10:11]
	v_pk_fma_f32 v[8:9], v[96:97], v[18:19], v[16:17]
	v_cvt_pk_bf16_f32 v12, v4, v5
	v_cvt_pk_bf16_f32 v13, v6, v7
	v_cvt_pk_bf16_f32 v14, v8, v9
	v_cvt_pk_bf16_f32 v15, v10, v11
	ds_write_b128 v181, v[12:15] offset:28096
	ds_write_b128 v179, v[4:7] offset:37312
	ds_write_b128 v179, v[8:11] offset:37328
	s_waitcnt lgkmcnt(0)
	s_barrier
	ds_read_b128 v[4:7], v180 offset:18880
	ds_read_b128 v[182:185], v180 offset:18912
	ds_read_b128 v[186:189], v180 offset:18944
	ds_read_b128 v[198:201], v180 offset:18976
	s_waitcnt lgkmcnt(3)
	v_mfma_f32_32x32x16_bf16 v[20:35], v[4:7], v[36:39], 0
	ds_read2st64_b32 v[156:157], v2 offset0:145 offset1:146
	ds_read2st64_b32 v[170:171], v2 offset0:147 offset1:148
	ds_read2st64_b32 v[168:169], v2 offset0:153 offset1:154
	ds_read2st64_b32 v[166:167], v2 offset0:155 offset1:156
	ds_read2st64_b32 v[164:165], v2 offset0:161 offset1:162
	ds_read2st64_b32 v[162:163], v2 offset0:163 offset1:164
	ds_read2st64_b32 v[160:161], v2 offset0:169 offset1:170
	ds_read2st64_b32 v[158:159], v2 offset0:171 offset1:172
	v_mul_f32_e32 v2, s24, v123
	v_mfma_f32_32x32x16_bf16 v[4:19], v[4:7], v[44:47], 0
	s_waitcnt lgkmcnt(10)
	v_mfma_f32_32x32x16_bf16 v[20:35], v[182:185], v[40:43], v[20:35]
	v_mfma_f32_32x32x16_bf16 v[4:19], v[182:185], v[48:51], v[4:19]
	s_waitcnt lgkmcnt(9)
	v_mfma_f32_32x32x16_bf16 v[20:35], v[186:189], v[52:55], v[20:35]
	v_mfma_f32_32x32x16_bf16 v[4:19], v[186:189], v[60:63], v[4:19]
	s_waitcnt lgkmcnt(8)
	v_mfma_f32_32x32x16_bf16 v[20:35], v[198:201], v[56:59], v[20:35]
	v_mfma_f32_32x32x16_bf16 v[4:19], v[198:201], v[64:67], v[4:19]
	s_nop 10
	v_fma_f32 v20, v20, s24, v2
	v_fma_f32 v21, v21, s24, v2
	v_fma_f32 v34, v34, s24, v2
	v_fma_f32 v35, v35, s24, v2
	v_fma_f32 v32, v32, s24, v2
	v_fma_f32 v33, v33, s24, v2
	v_pk_fma_f32 v[30:31], v[30:31], s[24:25], v[2:3] op_sel_hi:[1,0,0]
	v_pk_fma_f32 v[28:29], v[28:29], s[24:25], v[2:3] op_sel_hi:[1,0,0]
	v_pk_fma_f32 v[26:27], v[26:27], s[24:25], v[2:3] op_sel_hi:[1,0,0]
	v_pk_fma_f32 v[24:25], v[24:25], s[24:25], v[2:3] op_sel_hi:[1,0,0]
	v_pk_fma_f32 v[22:23], v[22:23], s[24:25], v[2:3] op_sel_hi:[1,0,0]
	v_mul_f32_e32 v2, s24, v127
	v_exp_f32_e32 v20, v20
	v_exp_f32_e32 v21, v21
	v_pk_fma_f32 v[6:7], v[6:7], s[24:25], v[2:3] op_sel_hi:[1,0,0]
	v_pk_fma_f32 v[14:15], v[14:15], s[24:25], v[2:3] op_sel_hi:[1,0,0]
	v_pk_fma_f32 v[12:13], v[12:13], s[24:25], v[2:3] op_sel_hi:[1,0,0]
	v_pk_fma_f32 v[10:11], v[10:11], s[24:25], v[2:3] op_sel_hi:[1,0,0]
	v_pk_fma_f32 v[8:9], v[8:9], s[24:25], v[2:3] op_sel_hi:[1,0,0]
	v_exp_f32_e32 v22, v22
	v_exp_f32_e32 v6, v6
	v_exp_f32_e32 v23, v23
	v_exp_f32_e32 v7, v7
	v_exp_f32_e32 v34, v34
	v_exp_f32_e32 v35, v35
	v_exp_f32_e32 v8, v8
	v_exp_f32_e32 v9, v9
	v_exp_f32_e32 v26, v26
	v_exp_f32_e32 v10, v10
	v_exp_f32_e32 v27, v27
	v_exp_f32_e32 v11, v11
	v_exp_f32_e32 v28, v28
	v_exp_f32_e32 v12, v12
	v_exp_f32_e32 v29, v29
	v_exp_f32_e32 v13, v13
	v_exp_f32_e32 v30, v30
	v_exp_f32_e32 v14, v14
	v_exp_f32_e32 v31, v31
	v_exp_f32_e32 v15, v15
	v_exp_f32_e32 v32, v32
	v_exp_f32_e32 v33, v33
	v_exp_f32_e32 v24, v24
	v_exp_f32_e32 v25, v25
	v_pk_add_f32 v[20:21], v[20:21], 1.0 op_sel_hi:[1,0]
	v_pk_fma_f32 v[18:19], v[18:19], s[24:25], v[2:3] op_sel_hi:[1,0,0]
	v_rcp_f32_e32 v20, v20
	v_rcp_f32_e32 v21, v21
	v_pk_fma_f32 v[16:17], v[16:17], s[24:25], v[2:3] op_sel_hi:[1,0,0]
	v_pk_add_f32 v[34:35], v[34:35], 1.0 op_sel_hi:[1,0]
	v_pk_add_f32 v[22:23], v[22:23], 1.0 op_sel_hi:[1,0]
	v_pk_add_f32 v[6:7], v[6:7], 1.0 op_sel_hi:[1,0]
	v_exp_f32_e32 v16, v16
	v_exp_f32_e32 v17, v17
	v_exp_f32_e32 v18, v18
	v_exp_f32_e32 v19, v19
	v_pk_add_f32 v[32:33], v[32:33], 1.0 op_sel_hi:[1,0]
	v_pk_add_f32 v[30:31], v[30:31], 1.0 op_sel_hi:[1,0]
	v_pk_add_f32 v[28:29], v[28:29], 1.0 op_sel_hi:[1,0]
	v_pk_add_f32 v[26:27], v[26:27], 1.0 op_sel_hi:[1,0]
	v_pk_add_f32 v[14:15], v[14:15], 1.0 op_sel_hi:[1,0]
	v_pk_add_f32 v[12:13], v[12:13], 1.0 op_sel_hi:[1,0]
	v_pk_add_f32 v[10:11], v[10:11], 1.0 op_sel_hi:[1,0]
	v_pk_add_f32 v[8:9], v[8:9], 1.0 op_sel_hi:[1,0]
	v_rcp_f32_e32 v22, v22
	v_rcp_f32_e32 v182, v6
	v_rcp_f32_e32 v23, v23
	v_rcp_f32_e32 v183, v7
	v_rcp_f32_e32 v6, v34
	v_rcp_f32_e32 v7, v35
	v_pk_add_f32 v[24:25], v[24:25], 1.0 op_sel_hi:[1,0]
	v_rcp_f32_e32 v184, v8
	v_rcp_f32_e32 v185, v9
	v_rcp_f32_e32 v8, v26
	v_rcp_f32_e32 v26, v10
	v_rcp_f32_e32 v9, v27
	v_rcp_f32_e32 v27, v11
	v_rcp_f32_e32 v10, v28
	v_rcp_f32_e32 v28, v12
	v_rcp_f32_e32 v11, v29
	v_rcp_f32_e32 v29, v13
	v_rcp_f32_e32 v12, v30
	v_rcp_f32_e32 v30, v14
	v_rcp_f32_e32 v13, v31
	v_rcp_f32_e32 v31, v15
	v_rcp_f32_e32 v14, v32
	v_rcp_f32_e32 v15, v33
	v_pk_fma_f32 v[4:5], v[4:5], s[24:25], v[2:3] op_sel_hi:[1,0,0]
	v_rcp_f32_e32 v24, v24
	v_rcp_f32_e32 v25, v25
	v_pk_mul_f32 v[206:207], v[124:125], v[20:21]
	v_exp_f32_e32 v4, v4
	v_exp_f32_e32 v5, v5
	v_exp_f32_e32 v208, v206
	v_exp_f32_e32 v209, v207
	v_pk_add_f32 v[18:19], v[18:19], 1.0 op_sel_hi:[1,0]
	v_pk_add_f32 v[16:17], v[16:17], 1.0 op_sel_hi:[1,0]
	v_pk_mul_f32 v[6:7], v[140:141], v[6:7]
	v_pk_mul_f32 v[202:203], v[128:129], v[22:23]
	v_rcp_f32_e32 v32, v16
	v_rcp_f32_e32 v33, v17
	v_rcp_f32_e32 v34, v18
	v_rcp_f32_e32 v35, v19
	v_pk_mul_f32 v[186:187], v[138:139], v[14:15]
	v_pk_mul_f32 v[190:191], v[134:135], v[10:11]
	v_pk_mul_f32 v[198:199], v[132:133], v[8:9]
	v_exp_f32_e32 v8, v202
	v_exp_f32_e32 v17, v203
	v_exp_f32_e32 v11, v6
	v_exp_f32_e32 v19, v7
	v_pk_mul_f32 v[188:189], v[136:137], v[12:13]
	v_pk_mul_f32 v[200:201], v[130:131], v[24:25]
	v_exp_f32_e32 v13, v186
	v_exp_f32_e32 v15, v187
	v_pk_add_f32 v[4:5], v[4:5], 1.0 op_sel_hi:[1,0]
	v_exp_f32_e32 v210, v200
	v_exp_f32_e32 v211, v201
	v_exp_f32_e32 v10, v188
	v_exp_f32_e32 v9, v189
	s_waitcnt lgkmcnt(5)
	v_pk_mul_f32 v[168:169], v[168:169], v[184:185]
	v_xor_b32_e32 v185, 0x80000000, v209
	v_xor_b32_e32 v184, 0x80000000, v208
	v_rcp_f32_e32 v4, v4
	v_rcp_f32_e32 v5, v5
	v_exp_f32_e32 v12, v190
	v_exp_f32_e32 v14, v191
	v_pk_fma_f32 v[184:185], v[184:185], v[208:209], 1.0 op_sel_hi:[1,1,0]
	v_exp_f32_e32 v212, v198
	v_exp_f32_e32 v213, v199
	v_pk_mul_f32 v[24:25], v[170:171], v[182:183]
	s_waitcnt lgkmcnt(4)
	v_pk_mul_f32 v[22:23], v[166:167], v[26:27]
	s_waitcnt lgkmcnt(3)
	v_pk_mul_f32 v[26:27], v[164:165], v[28:29]
	s_waitcnt lgkmcnt(2)
	v_pk_mul_f32 v[28:29], v[162:163], v[30:31]
	s_waitcnt lgkmcnt(1)
	v_pk_mul_f32 v[30:31], v[160:161], v[32:33]
	s_waitcnt lgkmcnt(0)
	v_pk_mul_f32 v[20:21], v[158:159], v[34:35]
	v_mov_b32_e32 v158, v11
	v_mov_b32_e32 v159, v19
	v_xor_b32_e32 v161, 0x80000000, v19
	v_xor_b32_e32 v160, 0x80000000, v11
	v_mov_b32_e32 v16, v8
	v_xor_b32_e32 v183, 0x80000000, v17
	v_xor_b32_e32 v182, 0x80000000, v8
	v_sqrt_f32_e32 v184, v184
	v_sqrt_f32_e32 v185, v185
	v_pk_fma_f32 v[158:159], v[160:161], v[158:159], 1.0 op_sel_hi:[1,1,0]
	v_mov_b32_e32 v160, v13
	v_mov_b32_e32 v161, v15
	v_xor_b32_e32 v163, 0x80000000, v15
	v_xor_b32_e32 v162, 0x80000000, v13
	v_pk_fma_f32 v[182:183], v[182:183], v[16:17], 1.0 op_sel_hi:[1,1,0]
	v_pk_fma_f32 v[160:161], v[162:163], v[160:161], 1.0 op_sel_hi:[1,1,0]
	v_mov_b32_e32 v162, v10
	v_mov_b32_e32 v163, v9
	v_xor_b32_e32 v165, 0x80000000, v9
	v_xor_b32_e32 v164, 0x80000000, v10
	v_xor_b32_e32 v171, 0x80000000, v211
	v_xor_b32_e32 v170, 0x80000000, v210
	v_sqrt_f32_e32 v182, v182
	v_sqrt_f32_e32 v183, v183
	v_pk_mul_f32 v[32:33], v[156:157], v[4:5]
	v_mul_f32_e32 v2, v211, v210
	v_pk_fma_f32 v[162:163], v[164:165], v[162:163], 1.0 op_sel_hi:[1,1,0]
	v_mov_b32_e32 v164, v12
	v_mov_b32_e32 v165, v14
	v_xor_b32_e32 v167, 0x80000000, v14
	v_xor_b32_e32 v166, 0x80000000, v12
	v_pk_fma_f32 v[170:171], v[170:171], v[210:211], 1.0 op_sel_hi:[1,1,0]
	v_mul_f32_e32 v2, v212, v2
	v_pk_fma_f32 v[164:165], v[166:167], v[164:165], 1.0 op_sel_hi:[1,1,0]
	v_xor_b32_e32 v167, 0x80000000, v213
	v_xor_b32_e32 v166, 0x80000000, v212
	v_sqrt_f32_e32 v170, v170
	v_sqrt_f32_e32 v171, v171
	v_sqrt_f32_e32 v158, v158
	v_sqrt_f32_e32 v159, v159
	v_pk_mul_f32 v[32:33], v[32:33], v[184:185]
	v_lshl_add_u64 v[34:35], v[142:143], 0, s[38:39]
	v_mul_f32_e32 v4, v213, v2
	v_pk_fma_f32 v[166:167], v[166:167], v[212:213], 1.0 op_sel_hi:[1,1,0]
	v_cvt_pk_bf16_f32 v2, v206, v32
	v_sqrt_f32_e32 v166, v166
	v_sqrt_f32_e32 v167, v167
	v_pk_mul_f32 v[24:25], v[24:25], v[182:183]
	global_store_dword v[34:35], v2, off nt sc1
	v_cvt_pk_bf16_f32 v2, v207, v33
	global_store_dword v[34:35], v2, off offset:256 nt sc1
	v_cvt_pk_bf16_f32 v2, v202, v24
	v_sqrt_f32_e32 v164, v164
	v_sqrt_f32_e32 v165, v165
	v_pk_mul_f32 v[20:21], v[20:21], v[158:159]
	v_pk_mul_f32 v[158:159], v[168:169], v[170:171]
	global_store_dword v[34:35], v2, off offset:512 nt sc1
	v_cvt_pk_bf16_f32 v2, v203, v25
	global_store_dword v[34:35], v2, off offset:768 nt sc1
	v_cvt_pk_bf16_f32 v2, v200, v158
	v_sqrt_f32_e32 v162, v162
	v_sqrt_f32_e32 v163, v163
	v_pk_mul_f32 v[22:23], v[22:23], v[166:167]
	global_store_dword v[34:35], v2, off offset:1024 nt sc1
	v_cvt_pk_bf16_f32 v2, v201, v159
	global_store_dword v[34:35], v2, off offset:1280 nt sc1
	v_cvt_pk_bf16_f32 v2, v198, v22
	v_sqrt_f32_e32 v160, v160
	v_sqrt_f32_e32 v161, v161
	v_pk_mul_f32 v[26:27], v[26:27], v[164:165]
	global_store_dword v[34:35], v2, off offset:1536 nt sc1
	v_cvt_pk_bf16_f32 v2, v199, v23
	global_store_dword v[34:35], v2, off offset:1792 nt sc1
	v_cvt_pk_bf16_f32 v2, v190, v26
	v_pk_mul_f32 v[28:29], v[28:29], v[162:163]
	global_store_dword v[34:35], v2, off offset:2048 nt sc1
	v_cvt_pk_bf16_f32 v2, v191, v27
	global_store_dword v[34:35], v2, off offset:2304 nt sc1
	v_cvt_pk_bf16_f32 v2, v188, v28
	v_pk_mul_f32 v[30:31], v[30:31], v[160:161]
	global_store_dword v[34:35], v2, off offset:2560 nt sc1
	v_cvt_pk_bf16_f32 v2, v189, v29
	global_store_dword v[34:35], v2, off offset:2816 nt sc1
	v_cvt_pk_bf16_f32 v2, v186, v30
	global_store_dword v[34:35], v2, off offset:3072 nt sc1
	v_cvt_pk_bf16_f32 v2, v187, v31
	global_store_dword v[34:35], v2, off offset:3328 nt sc1
	v_cvt_pk_bf16_f32 v2, v6, v20
	global_store_dword v[34:35], v2, off offset:3584 nt sc1
	v_cvt_pk_bf16_f32 v2, v7, v21
	global_store_dword v[34:35], v2, off offset:3840 nt sc1
	v_fma_f32 v2, 0, v208, v32
	v_fmac_f32_e32 v33, v209, v2
	v_fma_f32 v2, v8, v33, v24
	v_fmac_f32_e32 v25, v17, v2
	v_fma_f32 v2, 0, v210, v158
	v_fmac_f32_e32 v159, v211, v2
	v_fma_f32 v2, v212, v159, v22
	v_fmac_f32_e32 v23, v213, v2
	v_fma_f32 v2, 0, v12, v26
	v_fmac_f32_e32 v27, v14, v2
	v_mul_f32_e32 v156, v209, v208
	v_fma_f32 v157, v10, v27, v28
	v_fma_f32 v2, 0, v13, v30
	v_pk_mul_f32 v[6:7], v[8:9], v[156:157]
	v_mov_b32_e32 v28, v17
	v_fmac_f32_e32 v31, v15, v2
	v_pk_mul_f32 v[16:17], v[28:29], v[6:7]
	v_pk_mul_f32 v[6:7], v[14:15], v[12:13]
	v_fma_f32 v2, v11, v31, v20
	v_mov_b32_e32 v18, v9
	v_pk_mul_f32 v[6:7], v[10:11], v[6:7]
	v_fmac_f32_e32 v21, v19, v2
	v_cndmask_b32_e32 v2, v231, v236, vcc
	v_pk_fma_f32 v[26:27], v[8:9], v[156:157], v[28:29]
	v_pk_mul_f32 v[6:7], v[18:19], v[6:7]
	v_lshlrev_b32_e32 v197, 2, v2
	ds_bpermute_b32 v12, v197, v16
	ds_bpermute_b32 v13, v197, v25
	ds_bpermute_b32 v10, v197, v4
	ds_bpermute_b32 v2, v197, v23
	ds_bpermute_b32 v5, v197, v6
	ds_bpermute_b32 v11, v197, v27
	ds_bpermute_b32 v8, v197, v7
	ds_bpermute_b32 v9, v197, v21
	s_and_saveexec_b64 s[38:39], s[46:47]
	s_cbranch_execz .LBB0_674
	v_fmac_f32_e32 v25, 0, v16
	s_waitcnt lgkmcnt(6)
	v_fmac_f32_e32 v13, v25, v12
	v_fmac_f32_e32 v23, v4, v13
	s_waitcnt lgkmcnt(4)
	v_fmac_f32_e32 v2, v23, v10
	v_mul_f32_e32 v13, v6, v2
	v_pk_mul_f32 v[14:15], v[16:17], v[12:13]
	v_pk_add_f32 v[12:13], v[26:27], v[12:13]
	s_waitcnt lgkmcnt(3)
	v_mov_b32_e32 v2, v5
	v_mov_b32_e32 v12, v14
	v_pk_mul_f32 v[14:15], v[4:5], v[14:15]
	v_mov_b32_e32 v20, v5
	s_waitcnt lgkmcnt(2)
	v_pk_mul_f32 v[14:15], v[14:15], v[10:11]
	v_pk_fma_f32 v[10:11], v[4:5], v[12:13], v[10:11]
	s_nop 0
	v_mov_b32_e32 v15, v11
	v_pk_mul_f32 v[10:11], v[6:7], v[14:15]
	s_nop 0
	v_pk_mul_f32 v[4:5], v[10:11], v[2:3]
	v_pk_fma_f32 v[10:11], v[6:7], v[14:15], v[20:21]
	s_waitcnt lgkmcnt(0)
	v_pk_mov_b32 v[6:7], v[6:7], v[8:9] op_sel:[1,0]
	v_mov_b32_e32 v10, v4
	v_pk_mul_f32 v[4:5], v[6:7], v[4:5]
	v_pk_fma_f32 v[6:7], v[6:7], v[10:11], v[8:9]
	v_pk_mul_f32 v[4:5], v[4:5], v[8:9]
	s_nop 0
	v_mov_b32_e32 v5, v7
	ds_write_b64 v175, v[4:5]

.LBB0_676:
	v_writelane_b32 v254, s4, 37
	s_nop 0
	v_readlane_b32 s2, v254, 26
	v_readlane_b32 s3, v254, 27
	s_lshl_b64 s[20:21], s[2:3], 17
	s_add_u32 s0, s36, 0xfb00000
	s_addc_u32 s4, s37, 0
	s_and_b64 vcc, exec, s[66:67]
	s_cbranch_vccz .LBB0_680
	s_add_u32 s14, s0, s20
	s_addc_u32 s24, s4, s21
	s_lshl_b32 s9, s9, 3
	s_or_b32 s28, s9, s58
	s_ashr_i32 s29, s28, 31
	s_lshl_b64 s[28:29], s[28:29], 9
	s_add_u32 s28, s14, s28
	s_addc_u32 s29, s24, s29
	v_lshlrev_b32_e32 v2, 3, v122
	global_store_dwordx2 v2, v[4:5], s[28:29] sc1
	s_waitcnt vmcnt(0)
	v_cmp_eq_u32_e32 vcc, 0, v122
	s_and_saveexec_b64 s[40:41], vcc
	s_cbranch_execz .LBB0_679
	v_readlane_b32 s2, v254, 26
	s_lshl_b32 s14, s2, 8
	s_add_i32 s9, s9, s14
	s_or_b32 s28, s9, s58
	s_ashr_i32 s29, s28, 31
	s_lshl_b64 s[28:29], s[28:29], 8
	s_nop 0
	s_waitcnt vmcnt(0)
	s_waitcnt vmcnt(0)
	s_add_u32 s28, s36, s28
	s_addc_u32 s29, s37, s29
	v_mov_b32_e32 v2, 0x180000
	v_readlane_b32 s3, v254, 27
	global_store_dword v2, v245, s[28:29] sc1

.LBB0_717:
	s_or_b64 exec, exec, s[44:45]
	v_lshl_add_u64 v[40:41], v[136:137], 2, s[46:47]
	v_lshl_add_u64 v[40:41], v[40:41], 0, v[2:3]
	s_waitcnt lgkmcnt(3)
	v_add_co_u32_e32 v42, vcc, 0x1000, v40
	s_waitcnt lgkmcnt(2)
	s_nop 0
	v_addc_co_u32_e32 v43, vcc, 0, v41, vcc
	global_load_dwordx4 v[104:107], v[40:41], off nt
	global_load_dwordx4 v[100:103], v[42:43], off nt
	v_add_co_u32_e32 v42, vcc, 0x2000, v40
	s_nop 1
	v_addc_co_u32_e32 v43, vcc, 0, v41, vcc
	v_add_co_u32_e32 v52, vcc, 0x3000, v40
	s_nop 1
	v_addc_co_u32_e32 v53, vcc, 0, v41, vcc
	global_load_dwordx4 v[112:115], v[42:43], off nt
	global_load_dwordx4 v[108:111], v[52:53], off nt
	v_add_co_u32_e32 v42, vcc, s14, v40
	s_nop 1
	v_addc_co_u32_e32 v43, vcc, 0, v41, vcc
	v_add_co_u32_e32 v52, vcc, 0x5000, v40
	s_nop 1
	v_addc_co_u32_e32 v53, vcc, 0, v41, vcc
	global_load_dwordx4 v[120:123], v[42:43], off nt
	global_load_dwordx4 v[116:119], v[52:53], off nt
	v_add_co_u32_e32 v42, vcc, s33, v40
	s_nop 1
	v_addc_co_u32_e32 v43, vcc, 0, v41, vcc
	v_add_co_u32_e32 v52, vcc, 0x7000, v40
	s_nop 1
	v_addc_co_u32_e32 v53, vcc, 0, v41, vcc
	global_load_dwordx4 v[128:131], v[42:43], off nt
	global_load_dwordx4 v[124:127], v[52:53], off nt
	v_add_co_u32_e32 v42, vcc, s24, v40
	s_nop 1
	v_addc_co_u32_e32 v43, vcc, 0, v41, vcc
	v_add_co_u32_e32 v52, vcc, 0x9000, v40
	s_nop 1
	v_addc_co_u32_e32 v53, vcc, 0, v41, vcc
	global_load_dwordx4 v[96:99], v[42:43], off nt
	global_load_dwordx4 v[92:95], v[52:53], off nt
	v_add_co_u32_e32 v42, vcc, s20, v40
	s_nop 1
	v_addc_co_u32_e32 v43, vcc, 0, v41, vcc
	v_add_co_u32_e32 v52, vcc, 0xb000, v40
	s_nop 1
	v_addc_co_u32_e32 v53, vcc, 0, v41, vcc
	global_load_dwordx4 v[88:91], v[42:43], off nt
	global_load_dwordx4 v[84:87], v[52:53], off nt
	v_add_co_u32_e32 v42, vcc, s6, v40
	s_nop 1
	v_addc_co_u32_e32 v43, vcc, 0, v41, vcc
	v_add_co_u32_e32 v52, vcc, 0xd000, v40
	s_nop 1
	v_addc_co_u32_e32 v53, vcc, 0, v41, vcc
	global_load_dwordx4 v[72:75], v[42:43], off nt
	global_load_dwordx4 v[64:67], v[52:53], off nt
	v_add_co_u32_e32 v42, vcc, 0xe000, v40
	s_nop 1
	v_addc_co_u32_e32 v43, vcc, 0, v41, vcc
	v_add_co_u32_e32 v40, vcc, 0xf000, v40
	s_nop 1
	v_addc_co_u32_e32 v41, vcc, 0, v41, vcc
	s_waitcnt lgkmcnt(0)
	global_load_dwordx4 v[52:55], v[42:43], off nt
	s_nop 0
	global_load_dwordx4 v[40:43], v[40:41], off nt
	s_movk_i32 s14, 0x80
	v_cmp_gt_i32_e64 s[44:45], s14, v132
	v_ashrrev_i32_e32 v133, 31, v132
	v_lshl_add_u32 v2, v132, 2, 0
	s_barrier
	s_and_saveexec_b64 s[46:47], s[44:45]
	s_cbranch_execz .LBB0_719
	ds_read2st64_b32 v[136:137], v2 offset0:8 offset1:10
	s_waitcnt lgkmcnt(0)
	v_add_f32_e32 v136, 0, v136
	v_add_f32_e32 v141, v136, v137
	ds_read2st64_b32 v[136:137], v2 offset0:12 offset1:14
	s_waitcnt lgkmcnt(0)
	v_add_f32_e32 v136, v141, v136
	v_add_f32_e32 v141, v136, v137
	ds_read2st64_b32 v[136:137], v2 offset0:16 offset1:18
	s_waitcnt lgkmcnt(0)
	v_add_f32_e32 v136, v141, v136
	v_add_f32_e32 v141, v136, v137
	ds_read2st64_b32 v[136:137], v2 offset0:20 offset1:22
	s_waitcnt lgkmcnt(0)
	v_add_f32_e32 v136, v141, v136
	v_add_f32_e32 v141, v136, v137
	v_lshlrev_b64 v[136:137], 1, v[132:133]
	v_lshl_add_u64 v[142:143], s[68:69], 0, v[136:137]
	global_load_ushort v142, v[142:143], off
	v_lshl_add_u64 v[136:137], s[72:73], 0, v[136:137]
	s_waitcnt vmcnt(0)
	v_lshlrev_b32_e32 v142, 16, v142
	v_mul_f32_e32 v141, v141, v142
	v_cvt_pk_bf16_f32 v141, v141, s0
	global_store_short v[136:137], v141, off sc1

.LBB0_753:
	s_or_b64 exec, exec, s[40:41]
	s_waitcnt lgkmcnt(0)
	s_barrier
	s_and_saveexec_b64 s[40:41], s[44:45]
	s_cbranch_execz .LBB0_755
	ds_read2st64_b32 v[4:5], v2 offset0:8 offset1:10
	s_waitcnt lgkmcnt(0)
	v_add_f32_e32 v4, 0, v4
	v_add_f32_e32 v6, v4, v5
	ds_read2st64_b32 v[4:5], v2 offset0:12 offset1:14
	s_waitcnt lgkmcnt(0)
	v_add_f32_e32 v4, v6, v4
	v_add_f32_e32 v6, v4, v5
	ds_read2st64_b32 v[4:5], v2 offset0:16 offset1:18
	s_waitcnt lgkmcnt(0)
	v_add_f32_e32 v4, v6, v4
	v_add_f32_e32 v6, v4, v5
	ds_read2st64_b32 v[4:5], v2 offset0:20 offset1:22
	s_waitcnt lgkmcnt(0)
	v_add_f32_e32 v2, v6, v4
	v_add_f32_e32 v2, v2, v5
	v_lshlrev_b64 v[4:5], 1, v[132:133]
	v_lshl_add_u64 v[6:7], s[70:71], 0, v[4:5]
	global_load_ushort v6, v[6:7], off
	v_lshl_add_u64 v[4:5], s[74:75], 0, v[4:5]
	s_waitcnt vmcnt(0)
	v_lshlrev_b32_e32 v6, 16, v6
	v_mul_f32_e32 v2, v2, v6
	v_cvt_pk_bf16_f32 v2, v2, s0
	global_store_short v[4:5], v2, off sc1

.LBB0_857:
	v_cndmask_b32_e64 v9, v2, 1.0, s[38:39]
	v_cndmask_b32_e64 v2, v52, 0, s[38:39]
	s_waitcnt lgkmcnt(0)
	v_fmac_f32_e32 v2, v9, v11
	v_cndmask_b32_e64 v54, v57, v54, s[38:39]
	v_cndmask_b32_e64 v8, v55, v53, s[38:39]
	v_pk_fma_f32 v[36:37], v[36:37], v[2:3], v[40:41] op_sel_hi:[1,0,1]
	v_pk_fma_f32 v[40:41], v[50:51], v[2:3], v[42:43] op_sel_hi:[1,0,1]
	v_fmac_f32_e32 v8, v54, v11
	v_cvt_pk_bf16_f32 v2, v36, v37
	v_cndmask_b32_e64 v53, v61, v58, s[38:39]
	v_cndmask_b32_e64 v10, v59, v56, s[38:39]
	v_pk_fma_f32 v[30:31], v[30:31], v[8:9], v[34:35] op_sel_hi:[1,0,1]
	ds_write_b16 v72, v2
	ds_write_b16_d16_hi v72, v2 offset:144
	v_cvt_pk_bf16_f32 v2, v40, v41
	v_pk_fma_f32 v[34:35], v[46:47], v[8:9], v[38:39] op_sel_hi:[1,0,1]
	v_fmac_f32_e32 v10, v53, v11
	ds_write_b16 v72, v2 offset:288
	ds_write_b16_d16_hi v72, v2 offset:432
	v_cvt_pk_bf16_f32 v2, v30, v31
	v_cndmask_b32_e64 v55, v64, v62, s[38:39]
	v_cndmask_b32_e64 v52, v63, v60, s[38:39]
	v_pk_fma_f32 v[20:21], v[20:21], v[10:11], v[28:29] op_sel_hi:[1,0,1]
	ds_write_b16 v72, v2 offset:1152
	ds_write_b16_d16_hi v72, v2 offset:1296
	v_cvt_pk_bf16_f32 v2, v34, v35
	v_pk_fma_f32 v[28:29], v[44:45], v[10:11], v[32:33] op_sel_hi:[1,0,1]
	v_fmac_f32_e32 v52, v55, v11
	ds_write_b16 v72, v2 offset:1440
	ds_write_b16_d16_hi v72, v2 offset:1584
	v_cvt_pk_bf16_f32 v2, v20, v21
	v_pk_fma_f32 v[10:11], v[16:17], v[52:53], v[18:19] op_sel_hi:[1,0,1]
	ds_write_b16 v72, v2 offset:2304
	ds_write_b16_d16_hi v72, v2 offset:2448
	v_cvt_pk_bf16_f32 v2, v28, v29
	v_pk_fma_f32 v[8:9], v[48:49], v[52:53], v[22:23] op_sel_hi:[1,0,1]
	ds_write_b16 v72, v2 offset:2592
	ds_write_b16_d16_hi v72, v2 offset:2736
	v_cvt_pk_bf16_f32 v2, v10, v11
	ds_write_b16 v72, v2 offset:3456
	ds_write_b16_d16_hi v72, v2 offset:3600
	v_cvt_pk_bf16_f32 v2, v8, v9
	ds_write_b16 v72, v2 offset:3744
	ds_write_b16_d16_hi v72, v2 offset:3888
	s_waitcnt lgkmcnt(0)
	s_barrier
	s_and_saveexec_b64 s[22:23], s[2:3]
	s_cbranch_execz .LBB0_860
	s_cmp_lg_u32 s20, 7
	ds_write_b32 v69, v9
	s_cbranch_scc1 .LBB0_860
	v_readlane_b32 s20, v253, 11
	v_readlane_b32 s21, v253, 12
	s_load_dwordx2 s[28:29], s[20:21], 0xc8
	v_readlane_b32 s2, v254, 62
	v_readlane_b32 s3, v254, 63
	s_lshl_b64 s[2:3], s[2:3], 12
	v_lshlrev_b32_e32 v2, 2, v68
	s_waitcnt lgkmcnt(0)
	s_add_u32 s0, s28, s2
	s_addc_u32 s3, s29, s3
	s_add_u32 s2, s0, s4
	s_addc_u32 s3, s3, 0
	v_lshl_add_u64 v[10:11], s[2:3], 0, v[2:3]
	s_lshl_b32 s24, s1, 2
	v_lshl_add_u64 v[10:11], v[10:11], 0, s[24:25]
	v_add_co_u32_e32 v10, vcc, 0x4880000, v10
	s_nop 1
	v_addc_co_u32_e32 v11, vcc, 0, v11, vcc
	global_store_dword v[10:11], v9, off sc1

.LBB0_865:
	s_or_b64 exec, exec, s[20:21]
	s_andn2_b64 vcc, exec, s[2:3]
	s_waitcnt lgkmcnt(0)
	s_barrier
	s_cbranch_vccnz .LBB0_867
	v_mul_u32_u24_e32 v2, 0x90, v107
	v_lshlrev_b32_e32 v12, 4, v110
	v_add3_u32 v2, 0, v2, v12
	ds_read_b128 v[12:15], v2 offset:18880
	ds_read_b128 v[60:63], v2 offset:18912
	v_readlane_b32 s1, v254, 59
	s_add_i32 s1, s1, 0
	s_mov_b32 s2, 0xbfb8aa3b
	s_lshl_b32 s0, s0, 5
	s_mov_b32 s4, 0xf600000
	s_waitcnt lgkmcnt(1)
	v_mfma_f32_32x32x16_bf16 v[20:35], v[12:15], v[4:7], 0
	v_mfma_f32_32x32x16_bf16 v[4:19], v[12:15], v[8:11], 0
	s_waitcnt lgkmcnt(0)
	v_mfma_f32_32x32x16_bf16 v[20:35], v[60:63], v[52:55], v[20:35]
	v_lshlrev_b32_e32 v52, 2, v107
	v_mov_b32_e32 v107, v106
	v_mfma_f32_32x32x16_bf16 v[4:19], v[60:63], v[56:59], v[4:19]
	ds_read_b128 v[60:63], v2 offset:18944
	ds_read_b128 v[64:67], v2 offset:18976
	v_lshlrev_b32_e32 v2, 10, v110
	v_add3_u32 v2, s1, v2, v52
	v_add_u32_e32 v2, 0xc0, v2
	s_mov_b32 s1, 0x48d0000
	s_waitcnt lgkmcnt(1)
	v_mfma_f32_32x32x16_bf16 v[20:35], v[60:63], v[48:51], v[20:35]
	ds_read2st64_b32 v[48:49], v2 offset0:145 offset1:146
	ds_read2st64_b32 v[58:59], v2 offset0:147 offset1:148
	ds_read2st64_b32 v[56:57], v2 offset0:153 offset1:154
	ds_read2st64_b32 v[54:55], v2 offset0:155 offset1:156
	ds_read2st64_b32 v[52:53], v2 offset0:161 offset1:162
	ds_read2st64_b32 v[50:51], v2 offset0:163 offset1:164
	v_mfma_f32_32x32x16_bf16 v[4:19], v[60:63], v[40:43], v[4:19]
	s_waitcnt lgkmcnt(6)
	v_mfma_f32_32x32x16_bf16 v[20:35], v[64:67], v[44:47], v[20:35]
	ds_read2st64_b32 v[46:47], v2 offset0:169 offset1:170
	ds_read2st64_b32 v[44:45], v2 offset0:171 offset1:172
	v_mul_f32_e32 v2, s2, v137
	v_mfma_f32_32x32x16_bf16 v[4:19], v[64:67], v[36:39], v[4:19]
	s_nop 7
	v_fma_f32 v34, v34, s2, v2
	v_fma_f32 v35, v35, s2, v2
	v_fma_f32 v32, v32, s2, v2
	v_fma_f32 v33, v33, s2, v2
	v_fma_f32 v30, v30, s2, v2
	v_fma_f32 v31, v31, s2, v2
	v_pk_fma_f32 v[28:29], v[28:29], s[2:3], v[2:3] op_sel_hi:[1,0,0]
	v_pk_fma_f32 v[26:27], v[26:27], s[2:3], v[2:3] op_sel_hi:[1,0,0]
	v_pk_fma_f32 v[24:25], v[24:25], s[2:3], v[2:3] op_sel_hi:[1,0,0]
	v_pk_fma_f32 v[22:23], v[22:23], s[2:3], v[2:3] op_sel_hi:[1,0,0]
	v_pk_fma_f32 v[20:21], v[20:21], s[2:3], v[2:3] op_sel_hi:[1,0,0]
	v_mul_f32_e32 v2, s2, v135
	v_pk_fma_f32 v[14:15], v[14:15], s[2:3], v[2:3] op_sel_hi:[1,0,0]
	v_pk_fma_f32 v[8:9], v[8:9], s[2:3], v[2:3] op_sel_hi:[1,0,0]
	v_pk_fma_f32 v[6:7], v[6:7], s[2:3], v[2:3] op_sel_hi:[1,0,0]
	v_pk_fma_f32 v[4:5], v[4:5], s[2:3], v[2:3] op_sel_hi:[1,0,0]
	v_exp_f32_e32 v22, v22
	v_exp_f32_e32 v4, v4
	v_exp_f32_e32 v5, v5
	v_exp_f32_e32 v6, v6
	v_exp_f32_e32 v23, v23
	v_exp_f32_e32 v7, v7
	v_exp_f32_e32 v24, v24
	v_exp_f32_e32 v8, v8
	v_exp_f32_e32 v25, v25
	v_exp_f32_e32 v9, v9
	v_exp_f32_e32 v26, v26
	v_exp_f32_e32 v27, v27
	v_exp_f32_e32 v28, v28
	v_exp_f32_e32 v29, v29
	v_exp_f32_e32 v30, v30
	v_exp_f32_e32 v14, v14
	v_exp_f32_e32 v31, v31
	v_exp_f32_e32 v15, v15
	v_exp_f32_e32 v32, v32
	v_exp_f32_e32 v33, v33
	v_exp_f32_e32 v34, v34
	v_exp_f32_e32 v35, v35
	v_exp_f32_e32 v20, v20
	v_exp_f32_e32 v21, v21
	v_pk_add_f32 v[32:33], v[32:33], 1.0 op_sel_hi:[1,0]
	v_pk_add_f32 v[34:35], v[34:35], 1.0 op_sel_hi:[1,0]
	v_pk_add_f32 v[30:31], v[30:31], 1.0 op_sel_hi:[1,0]
	v_pk_add_f32 v[28:29], v[28:29], 1.0 op_sel_hi:[1,0]
	v_pk_add_f32 v[26:27], v[26:27], 1.0 op_sel_hi:[1,0]
	v_pk_add_f32 v[24:25], v[24:25], 1.0 op_sel_hi:[1,0]
	v_pk_add_f32 v[22:23], v[22:23], 1.0 op_sel_hi:[1,0]
	v_pk_add_f32 v[14:15], v[14:15], 1.0 op_sel_hi:[1,0]
	v_pk_add_f32 v[8:9], v[8:9], 1.0 op_sel_hi:[1,0]
	v_pk_add_f32 v[6:7], v[6:7], 1.0 op_sel_hi:[1,0]
	v_pk_add_f32 v[4:5], v[4:5], 1.0 op_sel_hi:[1,0]
	v_rcp_f32_e32 v38, v8
	v_rcp_f32_e32 v36, v4
	v_rcp_f32_e32 v37, v5
	v_rcp_f32_e32 v4, v22
	v_rcp_f32_e32 v22, v6
	v_rcp_f32_e32 v5, v23
	v_rcp_f32_e32 v23, v7
	v_rcp_f32_e32 v6, v24
	v_rcp_f32_e32 v7, v25
	v_rcp_f32_e32 v39, v9
	v_rcp_f32_e32 v8, v26
	v_rcp_f32_e32 v9, v27
	v_rcp_f32_e32 v24, v28
	v_rcp_f32_e32 v25, v29
	v_rcp_f32_e32 v26, v30
	v_rcp_f32_e32 v28, v14
	v_rcp_f32_e32 v27, v31
	v_rcp_f32_e32 v29, v15
	v_rcp_f32_e32 v14, v32
	v_rcp_f32_e32 v15, v33
	v_rcp_f32_e32 v30, v34
	v_rcp_f32_e32 v31, v35
	v_pk_add_f32 v[20:21], v[20:21], 1.0 op_sel_hi:[1,0]
	v_pk_fma_f32 v[18:19], v[18:19], s[2:3], v[2:3] op_sel_hi:[1,0,0]
	v_pk_fma_f32 v[10:11], v[10:11], s[2:3], v[2:3] op_sel_hi:[1,0,0]
	v_rcp_f32_e32 v20, v20
	v_rcp_f32_e32 v21, v21
	v_pk_fma_f32 v[12:13], v[12:13], s[2:3], v[2:3] op_sel_hi:[1,0,0]
	v_exp_f32_e32 v10, v10
	v_exp_f32_e32 v11, v11
	v_exp_f32_e32 v18, v18
	v_exp_f32_e32 v19, v19
	v_pk_mul_f32 v[30:31], v[106:107], v[30:31]
	v_pk_mul_f32 v[32:33], v[106:107], v[14:15]
	v_pk_mul_f32 v[14:15], v[106:107], v[24:25]
	v_pk_mul_f32 v[4:5], v[106:107], v[4:5]
	v_pk_fma_f32 v[16:17], v[16:17], s[2:3], v[2:3] op_sel_hi:[1,0,0]
	v_exp_f32_e32 v12, v12
	v_exp_f32_e32 v13, v13
	v_pk_mul_f32 v[6:7], v[106:107], v[6:7]
	v_exp_f32_e32 v40, v4
	v_exp_f32_e32 v41, v5
	v_exp_f32_e32 v14, v14
	v_exp_f32_e32 v15, v15
	v_exp_f32_e32 v5, v31
	v_exp_f32_e32 v4, v30
	v_exp_f32_e32 v16, v16
	v_exp_f32_e32 v17, v17
	v_exp_f32_e32 v24, v6
	v_exp_f32_e32 v25, v7
	v_exp_f32_e32 v6, v32
	v_exp_f32_e32 v7, v33
	v_pk_mul_f32 v[20:21], v[106:107], v[20:21]
	v_pk_add_f32 v[18:19], v[18:19], 1.0 op_sel_hi:[1,0]
	v_pk_add_f32 v[10:11], v[10:11], 1.0 op_sel_hi:[1,0]
	v_pk_mul_f32 v[26:27], v[106:107], v[26:27]
	v_pk_mul_f32 v[8:9], v[106:107], v[8:9]
	v_exp_f32_e32 v34, v20
	v_exp_f32_e32 v35, v21
	v_pk_add_f32 v[12:13], v[12:13], 1.0 op_sel_hi:[1,0]
	v_rcp_f32_e32 v10, v10
	v_rcp_f32_e32 v11, v11
	v_rcp_f32_e32 v18, v18
	v_rcp_f32_e32 v19, v19
	v_exp_f32_e32 v20, v8
	v_exp_f32_e32 v21, v9
	v_exp_f32_e32 v8, v26
	v_exp_f32_e32 v9, v27
	v_xor_b32_e32 v27, 0x80000000, v5
	v_xor_b32_e32 v26, 0x80000000, v4
	v_xor_b32_e32 v43, 0x80000000, v15
	v_xor_b32_e32 v42, 0x80000000, v14
	v_readlane_b32 s2, v253, 11
	v_pk_add_f32 v[16:17], v[16:17], 1.0 op_sel_hi:[1,0]
	v_rcp_f32_e32 v12, v12
	v_rcp_f32_e32 v13, v13
	v_pk_fma_f32 v[26:27], v[26:27], v[4:5], 1.0 op_sel_hi:[1,1,0]
	v_xor_b32_e32 v31, 0x80000000, v7
	v_xor_b32_e32 v30, 0x80000000, v6
	v_pk_fma_f32 v[42:43], v[42:43], v[14:15], 1.0 op_sel_hi:[1,1,0]
	v_readlane_b32 s3, v253, 12
	v_rcp_f32_e32 v16, v16
	v_rcp_f32_e32 v17, v17
	v_pk_fma_f32 v[30:31], v[30:31], v[6:7], 1.0 op_sel_hi:[1,1,0]
	v_sqrt_f32_e32 v42, v42
	v_sqrt_f32_e32 v43, v43
	v_sqrt_f32_e32 v26, v26
	v_sqrt_f32_e32 v27, v27
	s_load_dwordx2 s[2:3], s[2:3], 0xc8
	v_xor_b32_e32 v67, 0x80000000, v35
	v_xor_b32_e32 v66, 0x80000000, v34
	v_sqrt_f32_e32 v30, v30
	v_sqrt_f32_e32 v31, v31
	v_pk_fma_f32 v[66:67], v[66:67], v[34:35], 1.0 op_sel_hi:[1,1,0]
	s_waitcnt lgkmcnt(0)
	v_pk_mul_f32 v[54:55], v[54:55], v[10:11]
	v_pk_mul_f32 v[10:11], v[44:45], v[18:19]
	v_lshl_or_b32 v44, v110, 2, s0
	v_readlane_b32 s0, v255, 8
	v_sqrt_f32_e32 v66, v66
	v_sqrt_f32_e32 v67, v67
	v_pk_mul_f32 v[12:13], v[52:53], v[12:13]
	v_or_b32_e32 v2, s0, v44
	v_pk_mul_f32 v[16:17], v[46:47], v[16:17]
	v_pk_mul_f32 v[10:11], v[10:11], v[26:27]
	v_pk_mul_f32 v[26:27], v[12:13], v[42:43]
	v_lshlrev_b64 v[12:13], 12, v[2:3]
	v_xor_b32_e32 v33, 0x80000000, v9
	v_xor_b32_e32 v32, 0x80000000, v8
	v_xor_b32_e32 v63, 0x80000000, v25
	v_xor_b32_e32 v62, 0x80000000, v24
	v_pk_mul_f32 v[18:19], v[16:17], v[30:31]
	v_lshl_add_u64 v[12:13], s[2:3], 0, v[12:13]
	v_lshlrev_b64 v[16:17], 2, v[104:105]
	v_pk_fma_f32 v[32:33], v[32:33], v[8:9], 1.0 op_sel_hi:[1,1,0]
	v_pk_fma_f32 v[62:63], v[62:63], v[24:25], 1.0 op_sel_hi:[1,1,0]
	v_pk_mul_f32 v[58:59], v[58:59], v[22:23]
	v_pk_mul_f32 v[22:23], v[50:51], v[28:29]
	v_pk_mul_f32 v[28:29], v[48:49], v[36:37]
	v_lshl_add_u64 v[12:13], v[12:13], 0, v[16:17]
	v_sqrt_f32_e32 v62, v62
	v_sqrt_f32_e32 v63, v63
	v_sqrt_f32_e32 v32, v32
	v_sqrt_f32_e32 v33, v33
	v_pk_mul_f32 v[28:29], v[28:29], v[66:67]
	v_add_co_u32_e32 v12, vcc, s1, v12
	v_fma_f32 v28, v125, v34, v28
	s_nop 0
	v_addc_co_u32_e32 v13, vcc, 0, v13, vcc
	global_store_dword v[12:13], v28, off sc1
	v_mul_f32_e32 v12, v144, v28
	v_pk_mul_f32 v[38:39], v[56:57], v[38:39]
	v_cvt_pk_bf16_f32 v28, v12, s0
	v_mul_u32_u24_e32 v12, 0xc00, v44
	v_mov_b32_e32 v13, v3
	v_pk_mul_f32 v[22:23], v[22:23], v[32:33]
	v_pk_mul_f32 v[32:33], v[38:39], v[62:63]
	v_lshl_add_u64 v[38:39], s[36:37], 0, v[12:13]
	v_lshlrev_b64 v[12:13], 1, v[104:105]
	v_fmac_f32_e32 v29, v123, v35
	v_or_b32_e32 v34, 1, v2
	v_mov_b32_e32 v35, v3
	v_lshl_add_u64 v[38:39], v[38:39], 0, v[12:13]
	v_lshlrev_b64 v[34:35], 12, v[34:35]
	v_add_co_u32_e32 v42, vcc, s4, v38
	v_lshl_add_u64 v[34:35], s[2:3], 0, v[34:35]
	s_nop 0
	v_addc_co_u32_e32 v43, vcc, 0, v39, vcc
	v_lshl_add_u64 v[34:35], v[34:35], 0, v[16:17]
	v_xor_b32_e32 v65, 0x80000000, v41
	v_xor_b32_e32 v64, 0x80000000, v40
	global_store_short v[42:43], v28, off sc1
	v_add_co_u32_e32 v34, vcc, s1, v34
	v_mul_f32_e32 v28, v143, v29
	v_pk_fma_f32 v[64:65], v[64:65], v[40:41], 1.0 op_sel_hi:[1,1,0]
	v_addc_co_u32_e32 v35, vcc, 0, v35, vcc
	v_cvt_pk_bf16_f32 v28, v28, s0
	v_sqrt_f32_e32 v64, v64
	v_sqrt_f32_e32 v65, v65
	global_store_dword v[34:35], v29, off sc1
	global_store_short v[42:43], v28, off offset:3072 sc1
	v_or_b32_e32 v28, 2, v2
	v_mov_b32_e32 v29, v3
	v_lshlrev_b64 v[28:29], 12, v[28:29]
	v_lshl_add_u64 v[28:29], s[2:3], 0, v[28:29]
	v_lshl_add_u64 v[28:29], v[28:29], 0, v[16:17]
	v_pk_mul_f32 v[36:37], v[58:59], v[64:65]
	v_add_co_u32_e32 v28, vcc, s1, v28
	v_fma_f32 v34, v121, v40, v36
	s_nop 0
	v_addc_co_u32_e32 v29, vcc, 0, v29, vcc
	global_store_dword v[28:29], v34, off sc1
	v_mul_f32_e32 v28, v142, v34
	v_cvt_pk_bf16_f32 v34, v28, s0
	s_mov_b32 s0, 0xf601000
	v_add_co_u32_e32 v28, vcc, s0, v38
	v_fmac_f32_e32 v37, v119, v41
	s_nop 0
	v_addc_co_u32_e32 v29, vcc, 0, v39, vcc
	global_store_short v[28:29], v34, off offset:2048 sc1
	v_or_b32_e32 v28, 3, v2
	v_mov_b32_e32 v29, v3
	v_lshlrev_b64 v[28:29], 12, v[28:29]
	v_lshl_add_u64 v[28:29], s[2:3], 0, v[28:29]
	v_lshl_add_u64 v[28:29], v[28:29], 0, v[16:17]
	v_add_co_u32_e32 v28, vcc, s1, v28
	v_fma_f32 v24, v116, v24, v32
	s_nop 0
	v_addc_co_u32_e32 v29, vcc, 0, v29, vcc
	global_store_dword v[28:29], v37, off sc1
	v_mul_f32_e32 v28, v141, v37
	v_cvt_pk_bf16_f32 v34, v28, s0
	v_mov_b32_e32 v28, 0x2400
	v_mad_u32_u24 v28, v44, s5, v28
	v_mov_b32_e32 v29, v3
	v_lshl_add_u64 v[28:29], s[36:37], 0, v[28:29]
	v_lshl_add_u64 v[28:29], v[28:29], 0, v[12:13]
	v_add_co_u32_e32 v28, vcc, s4, v28
	v_fmac_f32_e32 v33, v114, v25
	s_nop 0
	v_addc_co_u32_e32 v29, vcc, 0, v29, vcc
	global_store_short v[28:29], v34, off sc1
	v_or_b32_e32 v28, 8, v2
	v_mov_b32_e32 v29, v3
	v_lshlrev_b64 v[28:29], 12, v[28:29]
	v_lshl_add_u64 v[28:29], s[2:3], 0, v[28:29]
	v_lshl_add_u64 v[28:29], v[28:29], 0, v[16:17]
	v_add_co_u32_e32 v28, vcc, s1, v28
	v_mov_b32_e32 v25, v3
	s_nop 0
	v_addc_co_u32_e32 v29, vcc, 0, v29, vcc
	global_store_dword v[28:29], v24, off sc1
	v_mov_b32_e32 v28, 0x6000
	v_mad_u32_u24 v28, v44, s5, v28
	v_mov_b32_e32 v29, v3
	v_lshl_add_u64 v[28:29], s[36:37], 0, v[28:29]
	v_lshl_add_u64 v[28:29], v[28:29], 0, v[12:13]
	v_mul_f32_e32 v24, v140, v24
	v_add_co_u32_e32 v28, vcc, s4, v28
	v_cvt_pk_bf16_f32 v24, v24, s0
	s_nop 0
	v_addc_co_u32_e32 v29, vcc, 0, v29, vcc
	global_store_short v[28:29], v24, off sc1
	v_or_b32_e32 v24, 9, v2
	v_lshlrev_b64 v[24:25], 12, v[24:25]
	v_lshl_add_u64 v[24:25], s[2:3], 0, v[24:25]
	v_lshl_add_u64 v[24:25], v[24:25], 0, v[16:17]
	v_add_co_u32_e32 v24, vcc, s1, v24
	v_xor_b32_e32 v61, 0x80000000, v21
	s_nop 0
	v_addc_co_u32_e32 v25, vcc, 0, v25, vcc
	global_store_dword v[24:25], v33, off sc1
	v_mul_f32_e32 v24, v139, v33
	v_cvt_pk_bf16_f32 v28, v24, s0
	v_mov_b32_e32 v24, 0x6c00
	v_mad_u32_u24 v24, v44, s5, v24
	v_mov_b32_e32 v25, v3
	v_lshl_add_u64 v[24:25], s[36:37], 0, v[24:25]
	v_lshl_add_u64 v[24:25], v[24:25], 0, v[12:13]
	v_xor_b32_e32 v60, 0x80000000, v20
	v_add_co_u32_e32 v24, vcc, s4, v24
	v_pk_fma_f32 v[60:61], v[60:61], v[20:21], 1.0 op_sel_hi:[1,1,0]
	s_nop 0
	v_addc_co_u32_e32 v25, vcc, 0, v25, vcc
	v_sqrt_f32_e32 v60, v60
	v_sqrt_f32_e32 v61, v61
	global_store_short v[24:25], v28, off sc1
	v_or_b32_e32 v24, 10, v2
	v_mov_b32_e32 v25, v3
	v_lshlrev_b64 v[24:25], 12, v[24:25]
	v_lshl_add_u64 v[24:25], s[2:3], 0, v[24:25]
	v_lshl_add_u64 v[24:25], v[24:25], 0, v[16:17]
	v_pk_mul_f32 v[30:31], v[54:55], v[60:61]
	v_add_co_u32_e32 v24, vcc, s1, v24
	v_fma_f32 v20, v112, v20, v30
	s_nop 0
	v_addc_co_u32_e32 v25, vcc, 0, v25, vcc
	global_store_dword v[24:25], v20, off sc1
	v_mov_b32_e32 v24, 0x7800
	v_mad_u32_u24 v24, v44, s5, v24
	v_mov_b32_e32 v25, v3
	v_lshl_add_u64 v[24:25], s[36:37], 0, v[24:25]
	v_lshl_add_u64 v[24:25], v[24:25], 0, v[12:13]
	v_mul_f32_e32 v20, v138, v20
	v_add_co_u32_e32 v24, vcc, s4, v24
	v_cvt_pk_bf16_f32 v20, v20, s0
	s_nop 0
	v_addc_co_u32_e32 v25, vcc, 0, v25, vcc
	global_store_short v[24:25], v20, off sc1
	v_fmac_f32_e32 v31, v111, v21
	v_or_b32_e32 v20, 11, v2
	v_mov_b32_e32 v21, v3
	v_lshlrev_b64 v[20:21], 12, v[20:21]
	v_lshl_add_u64 v[20:21], s[2:3], 0, v[20:21]
	v_lshl_add_u64 v[20:21], v[20:21], 0, v[16:17]
	v_add_co_u32_e32 v20, vcc, s1, v20
	s_waitcnt vmcnt(21)
	v_fma_f32 v14, v128, v14, v26
	v_addc_co_u32_e32 v21, vcc, 0, v21, vcc
	global_store_dword v[20:21], v31, off sc1
	v_mul_f32_e32 v20, v136, v31
	v_cvt_pk_bf16_f32 v24, v20, s0
	v_mov_b32_e32 v20, 0x8400
	v_mad_u32_u24 v20, v44, s5, v20
	v_mov_b32_e32 v21, v3
	v_lshl_add_u64 v[20:21], s[36:37], 0, v[20:21]
	v_lshl_add_u64 v[20:21], v[20:21], 0, v[12:13]
	v_add_co_u32_e32 v20, vcc, s4, v20
	s_waitcnt vmcnt(21)
	v_fmac_f32_e32 v27, v126, v15
	v_addc_co_u32_e32 v21, vcc, 0, v21, vcc
	global_store_short v[20:21], v24, off sc1
	v_or_b32_e32 v20, 16, v2
	v_mov_b32_e32 v21, v3
	v_lshlrev_b64 v[20:21], 12, v[20:21]
	v_lshl_add_u64 v[20:21], s[2:3], 0, v[20:21]
	v_lshl_add_u64 v[20:21], v[20:21], 0, v[16:17]
	v_add_co_u32_e32 v20, vcc, s1, v20
	v_mov_b32_e32 v15, v3
	s_nop 0
	v_addc_co_u32_e32 v21, vcc, 0, v21, vcc
	global_store_dword v[20:21], v14, off sc1
	v_mad_u32_u24 v20, v44, s5, v242
	v_mov_b32_e32 v21, v3
	v_lshl_add_u64 v[20:21], s[36:37], 0, v[20:21]
	v_lshl_add_u64 v[20:21], v[20:21], 0, v[12:13]
	v_mul_f32_e32 v14, v134, v14
	v_add_co_u32_e32 v20, vcc, s4, v20
	v_cvt_pk_bf16_f32 v14, v14, s0
	s_nop 0
	v_addc_co_u32_e32 v21, vcc, 0, v21, vcc
	global_store_short v[20:21], v14, off sc1
	v_or_b32_e32 v14, 17, v2
	v_lshlrev_b64 v[14:15], 12, v[14:15]
	v_lshl_add_u64 v[14:15], s[2:3], 0, v[14:15]
	v_lshl_add_u64 v[14:15], v[14:15], 0, v[16:17]
	v_add_co_u32_e32 v14, vcc, s1, v14
	s_waitcnt vmcnt(23)
	v_fma_f32 v8, v124, v8, v22
	v_addc_co_u32_e32 v15, vcc, 0, v15, vcc
	global_store_dword v[14:15], v27, off sc1
	v_mul_f32_e32 v14, v133, v27
	v_cvt_pk_bf16_f32 v20, v14, s0
	v_mov_b32_e32 v14, 0xcc00
	v_mad_u32_u24 v14, v44, s5, v14
	v_mov_b32_e32 v15, v3
	v_lshl_add_u64 v[14:15], s[36:37], 0, v[14:15]
	v_lshl_add_u64 v[14:15], v[14:15], 0, v[12:13]
	v_add_co_u32_e32 v14, vcc, s4, v14
	s_waitcnt vmcnt(23)
	v_fmac_f32_e32 v23, v122, v9
	v_addc_co_u32_e32 v15, vcc, 0, v15, vcc
	global_store_short v[14:15], v20, off sc1
	v_or_b32_e32 v14, 18, v2
	v_mov_b32_e32 v15, v3
	v_lshlrev_b64 v[14:15], 12, v[14:15]
	v_lshl_add_u64 v[14:15], s[2:3], 0, v[14:15]
	v_lshl_add_u64 v[14:15], v[14:15], 0, v[16:17]
	v_add_co_u32_e32 v14, vcc, s1, v14
	v_mov_b32_e32 v9, v3
	s_nop 0
	v_addc_co_u32_e32 v15, vcc, 0, v15, vcc
	global_store_dword v[14:15], v8, off sc1
	v_mad_u32_u24 v14, v44, s5, v244
	v_mov_b32_e32 v15, v3
	v_lshl_add_u64 v[14:15], s[36:37], 0, v[14:15]
	v_lshl_add_u64 v[14:15], v[14:15], 0, v[12:13]
	v_mul_f32_e32 v8, v132, v8
	v_add_co_u32_e32 v14, vcc, s4, v14
	v_cvt_pk_bf16_f32 v8, v8, s0
	s_nop 0
	v_addc_co_u32_e32 v15, vcc, 0, v15, vcc
	global_store_short v[14:15], v8, off sc1
	v_or_b32_e32 v8, 19, v2
	v_lshlrev_b64 v[8:9], 12, v[8:9]
	v_lshl_add_u64 v[8:9], s[2:3], 0, v[8:9]
	v_lshl_add_u64 v[8:9], v[8:9], 0, v[16:17]
	v_add_co_u32_e32 v8, vcc, s1, v8
	s_waitcnt vmcnt(25)
	v_fma_f32 v6, v120, v6, v18
	v_addc_co_u32_e32 v9, vcc, 0, v9, vcc
	global_store_dword v[8:9], v23, off sc1
	v_mul_f32_e32 v8, v131, v23
	v_cvt_pk_bf16_f32 v14, v8, s0
	v_mov_b32_e32 v8, 0xe400
	v_mad_u32_u24 v8, v44, s5, v8
	v_mov_b32_e32 v9, v3
	v_lshl_add_u64 v[8:9], s[36:37], 0, v[8:9]
	v_lshl_add_u64 v[8:9], v[8:9], 0, v[12:13]
	v_add_co_u32_e32 v8, vcc, s4, v8
	s_waitcnt vmcnt(25)
	v_fmac_f32_e32 v19, v118, v7
	v_addc_co_u32_e32 v9, vcc, 0, v9, vcc
	global_store_short v[8:9], v14, off sc1
	v_or_b32_e32 v8, 24, v2
	v_mov_b32_e32 v9, v3
	v_lshlrev_b64 v[8:9], 12, v[8:9]
	v_lshl_add_u64 v[8:9], s[2:3], 0, v[8:9]
	v_lshl_add_u64 v[8:9], v[8:9], 0, v[16:17]
	v_add_co_u32_e32 v8, vcc, s1, v8
	v_mov_b32_e32 v7, v3
	s_nop 0
	v_addc_co_u32_e32 v9, vcc, 0, v9, vcc
	global_store_dword v[8:9], v6, off sc1
	v_mov_b32_e32 v8, 0x12000
	v_mad_u32_u24 v8, v44, s5, v8
	v_mov_b32_e32 v9, v3
	v_lshl_add_u64 v[8:9], s[36:37], 0, v[8:9]
	v_lshl_add_u64 v[8:9], v[8:9], 0, v[12:13]
	v_mul_f32_e32 v6, v130, v6
	v_add_co_u32_e32 v8, vcc, s4, v8
	v_cvt_pk_bf16_f32 v6, v6, s0
	s_nop 0
	v_addc_co_u32_e32 v9, vcc, 0, v9, vcc
	global_store_short v[8:9], v6, off sc1
	v_or_b32_e32 v6, 25, v2
	v_lshlrev_b64 v[6:7], 12, v[6:7]
	v_lshl_add_u64 v[6:7], s[2:3], 0, v[6:7]
	v_lshl_add_u64 v[6:7], v[6:7], 0, v[16:17]
	v_add_co_u32_e32 v6, vcc, s1, v6
	s_waitcnt vmcnt(27)
	v_fma_f32 v4, v115, v4, v10
	v_addc_co_u32_e32 v7, vcc, 0, v7, vcc
	global_store_dword v[6:7], v19, off sc1
	v_mul_f32_e32 v6, v129, v19
	v_cvt_pk_bf16_f32 v8, v6, s0
	v_mov_b32_e32 v6, 0x12c00
	v_mad_u32_u24 v6, v44, s5, v6
	v_mov_b32_e32 v7, v3
	v_lshl_add_u64 v[6:7], s[36:37], 0, v[6:7]
	v_lshl_add_u64 v[6:7], v[6:7], 0, v[12:13]
	v_add_co_u32_e32 v6, vcc, s4, v6
	s_waitcnt vmcnt(27)
	v_fmac_f32_e32 v11, v113, v5
	v_addc_co_u32_e32 v7, vcc, 0, v7, vcc
	global_store_short v[6:7], v8, off sc1
	v_or_b32_e32 v6, 26, v2
	v_mov_b32_e32 v7, v3
	v_lshlrev_b64 v[6:7], 12, v[6:7]
	v_lshl_add_u64 v[6:7], s[2:3], 0, v[6:7]
	v_lshl_add_u64 v[6:7], v[6:7], 0, v[16:17]
	v_add_co_u32_e32 v6, vcc, s1, v6
	v_or_b32_e32 v2, 27, v2
	s_nop 0
	v_addc_co_u32_e32 v7, vcc, 0, v7, vcc
	global_store_dword v[6:7], v4, off sc1
	v_mov_b32_e32 v6, 0x13800
	v_mad_u32_u24 v6, v44, s5, v6
	v_mov_b32_e32 v7, v3
	v_lshl_add_u64 v[6:7], s[36:37], 0, v[6:7]
	v_lshl_add_u64 v[6:7], v[6:7], 0, v[12:13]
	v_mul_f32_e32 v4, v127, v4
	v_add_co_u32_e32 v6, vcc, s4, v6
	v_cvt_pk_bf16_f32 v4, v4, s0
	s_nop 0
	v_addc_co_u32_e32 v7, vcc, 0, v7, vcc
	global_store_short v[6:7], v4, off sc1
	v_lshlrev_b64 v[4:5], 12, v[2:3]
	v_lshl_add_u64 v[4:5], s[2:3], 0, v[4:5]
	v_lshl_add_u64 v[4:5], v[4:5], 0, v[16:17]
	v_mul_f32_e32 v2, v117, v11
	v_add_co_u32_e32 v4, vcc, s1, v4
	v_cvt_pk_bf16_f32 v6, v2, s0
	v_mov_b32_e32 v2, 0x14400
	v_addc_co_u32_e32 v5, vcc, 0, v5, vcc
	v_mad_u32_u24 v2, v44, s5, v2
	global_store_dword v[4:5], v11, off sc1
	v_lshl_add_u64 v[4:5], s[36:37], 0, v[2:3]
	v_lshl_add_u64 v[4:5], v[4:5], 0, v[12:13]
	v_add_co_u32_e32 v4, vcc, 0xf600000, v4
	s_nop 1
	v_addc_co_u32_e32 v5, vcc, 0, v5, vcc
	global_store_short v[4:5], v6, off sc1

.LBB0_1211:
	s_mov_b64 s[2:3], exec
	s_nop 0
	s_waitcnt vmcnt(0) lgkmcnt(0)
	s_waitcnt vmcnt(0)
	v_mbcnt_lo_u32_b32 v2, s2, 0
	v_mbcnt_hi_u32_b32 v2, s3, v2
	v_cmp_eq_u32_e32 vcc, 0, v2
	s_and_saveexec_b64 s[20:21], vcc
	s_cbranch_execz .LBB0_1213
	s_bcnt1_i32_b64 s2, s[2:3]
	v_mov_b32_e32 v5, s2
	v_readlane_b32 s2, v254, 17
	v_readlane_b32 s3, v254, 18
	s_nop 4
	global_atomic_add v5, v3, v5, s[2:3] sc0

.LBB0_1438:
	s_cmp_eq_u64 s[48:49], 0
	v_lshlrev_b32_e32 v86, 3, v82
	s_cbranch_scc1 .LBB0_1442
	v_mul_f32_e32 v87, v7, v7
	v_mul_f32_e32 v88, v9, v9
	v_fmac_f32_e32 v87, v6, v6
	v_fmac_f32_e32 v88, v8, v8
	v_add_f32_e32 v87, v87, v88
	v_mul_f32_e32 v88, v3, v3
	v_mul_f32_e32 v89, v5, v5
	v_fmac_f32_e32 v88, v2, v2
	v_fmac_f32_e32 v89, v4, v4
	v_add_f32_e32 v88, v88, v89
	v_add_f32_e32 v87, v87, v88
	v_mul_f32_e32 v88, v15, v15
	v_mul_f32_e32 v89, v17, v17
	v_fmac_f32_e32 v88, v14, v14
	v_fmac_f32_e32 v89, v16, v16
	v_add_f32_e32 v88, v88, v89
	v_add_f32_e32 v87, v87, v88
	v_mul_f32_e32 v88, v11, v11
	v_mul_f32_e32 v89, v13, v13
	v_fmac_f32_e32 v88, v10, v10
	v_fmac_f32_e32 v89, v12, v12
	v_add_f32_e32 v88, v88, v89
	v_add_f32_e32 v87, v87, v88
	v_and_b32_e32 v88, 64, v83
	v_add_u32_e32 v88, 64, v88
	v_xor_b32_e32 v89, 1, v83
	v_cmp_lt_i32_e32 vcc, v89, v88
	v_cvt_pk_bf16_f32 v2, v2, v3
	v_cvt_pk_bf16_f32 v3, v4, v5
	v_cndmask_b32_e32 v89, v83, v89, vcc
	v_lshlrev_b32_e32 v89, 2, v89
	ds_bpermute_b32 v89, v89, v87
	global_store_dwordx2 v86, v[2:3], s[48:49] offset:512 sc1
	v_cvt_pk_bf16_f32 v2, v14, v15
	v_cvt_pk_bf16_f32 v3, v16, v17
	v_cvt_pk_bf16_f32 v6, v6, v7
	s_waitcnt lgkmcnt(0)
	v_add_f32_e32 v87, v87, v89
	v_xor_b32_e32 v89, 2, v83
	v_cmp_lt_i32_e32 vcc, v89, v88
	v_cvt_pk_bf16_f32 v7, v8, v9
	global_store_dwordx2 v86, v[2:3], s[48:49] offset:1024 sc1
	v_cndmask_b32_e32 v89, v83, v89, vcc
	v_lshlrev_b32_e32 v89, 2, v89
	ds_bpermute_b32 v89, v89, v87
	v_cvt_pk_bf16_f32 v2, v10, v11
	v_cvt_pk_bf16_f32 v3, v12, v13
	global_store_dwordx2 v86, v[6:7], s[48:49] sc1
	global_store_dwordx2 v86, v[2:3], s[48:49] offset:1536 sc1
	s_waitcnt lgkmcnt(0)
	v_add_f32_e32 v87, v87, v89
	v_xor_b32_e32 v89, 4, v83
	v_cmp_lt_i32_e32 vcc, v89, v88
	s_nop 1
	v_cndmask_b32_e32 v89, v83, v89, vcc
	v_lshlrev_b32_e32 v89, 2, v89
	ds_bpermute_b32 v89, v89, v87
	s_waitcnt lgkmcnt(0)
	v_add_f32_e32 v87, v87, v89
	v_xor_b32_e32 v89, 8, v83
	v_cmp_lt_i32_e32 vcc, v89, v88
	s_nop 1
	v_cndmask_b32_e32 v89, v83, v89, vcc
	v_lshlrev_b32_e32 v89, 2, v89
	ds_bpermute_b32 v89, v89, v87
	s_waitcnt lgkmcnt(0)
	v_add_f32_e32 v87, v87, v89
	v_xor_b32_e32 v89, 16, v83
	v_cmp_lt_i32_e32 vcc, v89, v88
	s_nop 1
	v_cndmask_b32_e32 v89, v83, v89, vcc
	v_lshlrev_b32_e32 v89, 2, v89
	ds_bpermute_b32 v89, v89, v87
	s_waitcnt lgkmcnt(0)
	v_add_f32_e32 v87, v87, v89
	v_xor_b32_e32 v89, 32, v83
	v_cmp_lt_i32_e32 vcc, v89, v88
	s_nop 1
	v_cndmask_b32_e32 v88, v83, v89, vcc
	v_lshlrev_b32_e32 v88, 2, v88
	ds_bpermute_b32 v88, v88, v87
	s_and_saveexec_b64 s[6:7], s[4:5]
	s_cbranch_execz .LBB0_1441
	s_lshl_b64 s[12:13], s[46:47], 2
	s_add_u32 s12, s72, s12
	s_addc_u32 s13, s75, s13
	s_waitcnt lgkmcnt(0)
	v_add_f32_e32 v2, v87, v88
	global_store_dword v85, v2, s[12:13] sc1

.LBB0_1442:
	s_cmp_eq_u64 s[50:51], 0
	s_cbranch_scc1 .LBB0_1446
	v_mul_f32_e32 v2, v23, v23
	v_mul_f32_e32 v3, v25, v25
	v_fmac_f32_e32 v2, v22, v22
	v_fmac_f32_e32 v3, v24, v24
	v_add_f32_e32 v2, v2, v3
	v_mul_f32_e32 v3, v19, v19
	v_mul_f32_e32 v4, v21, v21
	v_fmac_f32_e32 v3, v18, v18
	v_fmac_f32_e32 v4, v20, v20
	v_add_f32_e32 v3, v3, v4
	v_add_f32_e32 v2, v2, v3
	s_waitcnt vmcnt(0)
	v_mul_f32_e32 v3, v31, v31
	v_mul_f32_e32 v4, v33, v33
	v_fmac_f32_e32 v3, v30, v30
	v_fmac_f32_e32 v4, v32, v32
	v_add_f32_e32 v3, v3, v4
	v_add_f32_e32 v2, v2, v3
	v_mul_f32_e32 v3, v27, v27
	v_mul_f32_e32 v4, v29, v29
	v_fmac_f32_e32 v3, v26, v26
	v_fmac_f32_e32 v4, v28, v28
	v_add_f32_e32 v3, v3, v4
	v_add_f32_e32 v2, v2, v3
	v_and_b32_e32 v3, 64, v83
	v_add_u32_e32 v3, 64, v3
	v_xor_b32_e32 v4, 1, v83
	v_cmp_lt_i32_e32 vcc, v4, v3
	v_cvt_pk_bf16_f32 v5, v24, v25
	s_nop 0
	v_cndmask_b32_e32 v4, v83, v4, vcc
	v_lshlrev_b32_e32 v4, 2, v4
	ds_bpermute_b32 v4, v4, v2
	s_waitcnt lgkmcnt(0)
	v_add_f32_e32 v2, v2, v4
	v_xor_b32_e32 v4, 2, v83
	v_cmp_lt_i32_e32 vcc, v4, v3
	s_nop 1
	v_cndmask_b32_e32 v4, v83, v4, vcc
	v_lshlrev_b32_e32 v4, 2, v4
	ds_bpermute_b32 v4, v4, v2
	s_waitcnt lgkmcnt(0)
	v_add_f32_e32 v2, v2, v4
	v_xor_b32_e32 v4, 4, v83
	v_cmp_lt_i32_e32 vcc, v4, v3
	s_nop 1
	v_cndmask_b32_e32 v4, v83, v4, vcc
	v_lshlrev_b32_e32 v4, 2, v4
	ds_bpermute_b32 v4, v4, v2
	s_waitcnt lgkmcnt(0)
	v_add_f32_e32 v2, v2, v4
	v_xor_b32_e32 v4, 8, v83
	v_cmp_lt_i32_e32 vcc, v4, v3
	s_nop 1
	v_cndmask_b32_e32 v4, v83, v4, vcc
	v_lshlrev_b32_e32 v4, 2, v4
	ds_bpermute_b32 v4, v4, v2
	s_waitcnt lgkmcnt(0)
	v_add_f32_e32 v2, v2, v4
	v_xor_b32_e32 v4, 16, v83
	v_cmp_lt_i32_e32 vcc, v4, v3
	s_nop 1
	v_cndmask_b32_e32 v4, v83, v4, vcc
	v_lshlrev_b32_e32 v4, 2, v4
	ds_bpermute_b32 v4, v4, v2
	s_waitcnt lgkmcnt(0)
	v_add_f32_e32 v2, v2, v4
	v_xor_b32_e32 v4, 32, v83
	v_cmp_lt_i32_e32 vcc, v4, v3
	s_nop 1
	v_cndmask_b32_e32 v3, v83, v4, vcc
	v_lshlrev_b32_e32 v3, 2, v3
	ds_bpermute_b32 v3, v3, v2
	v_cvt_pk_bf16_f32 v4, v22, v23
	global_store_dwordx2 v86, v[4:5], s[50:51] sc1
	v_cvt_pk_bf16_f32 v4, v18, v19
	v_cvt_pk_bf16_f32 v5, v20, v21
	global_store_dwordx2 v86, v[4:5], s[50:51] offset:512 sc1
	v_cvt_pk_bf16_f32 v4, v30, v31
	v_cvt_pk_bf16_f32 v5, v32, v33
	global_store_dwordx2 v86, v[4:5], s[50:51] offset:1024 sc1
	v_cvt_pk_bf16_f32 v4, v26, v27
	v_cvt_pk_bf16_f32 v5, v28, v29
	global_store_dwordx2 v86, v[4:5], s[50:51] offset:1536 sc1
	s_and_saveexec_b64 s[6:7], s[4:5]
	s_cbranch_execz .LBB0_1445
	s_waitcnt lgkmcnt(0)
	v_add_f32_e32 v2, v2, v3
	global_store_dword v85, v2, s[54:55] sc1

.LBB0_1446:
	s_cmp_eq_u64 s[56:57], 0
	s_cbranch_scc1 .LBB0_1450
	s_waitcnt vmcnt(0)
	v_mul_f32_e32 v2, v39, v39
	s_waitcnt lgkmcnt(0)
	v_mul_f32_e32 v3, v41, v41
	v_fmac_f32_e32 v2, v38, v38
	v_fmac_f32_e32 v3, v40, v40
	v_add_f32_e32 v2, v2, v3
	v_mul_f32_e32 v3, v35, v35
	v_mul_f32_e32 v4, v37, v37
	v_fmac_f32_e32 v3, v34, v34
	v_fmac_f32_e32 v4, v36, v36
	v_add_f32_e32 v3, v3, v4
	v_add_f32_e32 v2, v2, v3
	v_mul_f32_e32 v3, v47, v47
	v_mul_f32_e32 v4, v49, v49
	v_fmac_f32_e32 v3, v46, v46
	v_fmac_f32_e32 v4, v48, v48
	v_add_f32_e32 v3, v3, v4
	v_add_f32_e32 v2, v2, v3
	v_mul_f32_e32 v3, v43, v43
	v_mul_f32_e32 v4, v45, v45
	v_fmac_f32_e32 v3, v42, v42
	v_fmac_f32_e32 v4, v44, v44
	v_add_f32_e32 v3, v3, v4
	v_add_f32_e32 v2, v2, v3
	v_and_b32_e32 v3, 64, v83
	v_add_u32_e32 v3, 64, v3
	v_xor_b32_e32 v4, 1, v83
	v_cmp_lt_i32_e32 vcc, v4, v3
	v_cvt_pk_bf16_f32 v5, v40, v41
	s_nop 0
	v_cndmask_b32_e32 v4, v83, v4, vcc
	v_lshlrev_b32_e32 v4, 2, v4
	ds_bpermute_b32 v4, v4, v2
	s_waitcnt lgkmcnt(0)
	v_add_f32_e32 v2, v2, v4
	v_xor_b32_e32 v4, 2, v83
	v_cmp_lt_i32_e32 vcc, v4, v3
	s_nop 1
	v_cndmask_b32_e32 v4, v83, v4, vcc
	v_lshlrev_b32_e32 v4, 2, v4
	ds_bpermute_b32 v4, v4, v2
	s_waitcnt lgkmcnt(0)
	v_add_f32_e32 v2, v2, v4
	v_xor_b32_e32 v4, 4, v83
	v_cmp_lt_i32_e32 vcc, v4, v3
	s_nop 1
	v_cndmask_b32_e32 v4, v83, v4, vcc
	v_lshlrev_b32_e32 v4, 2, v4
	ds_bpermute_b32 v4, v4, v2
	s_waitcnt lgkmcnt(0)
	v_add_f32_e32 v2, v2, v4
	v_xor_b32_e32 v4, 8, v83
	v_cmp_lt_i32_e32 vcc, v4, v3
	s_nop 1
	v_cndmask_b32_e32 v4, v83, v4, vcc
	v_lshlrev_b32_e32 v4, 2, v4
	ds_bpermute_b32 v4, v4, v2
	s_waitcnt lgkmcnt(0)
	v_add_f32_e32 v2, v2, v4
	v_xor_b32_e32 v4, 16, v83
	v_cmp_lt_i32_e32 vcc, v4, v3
	s_nop 1
	v_cndmask_b32_e32 v4, v83, v4, vcc
	v_lshlrev_b32_e32 v4, 2, v4
	ds_bpermute_b32 v4, v4, v2
	s_waitcnt lgkmcnt(0)
	v_add_f32_e32 v2, v2, v4
	v_xor_b32_e32 v4, 32, v83
	v_cmp_lt_i32_e32 vcc, v4, v3
	s_nop 1
	v_cndmask_b32_e32 v3, v83, v4, vcc
	v_lshlrev_b32_e32 v3, 2, v3
	ds_bpermute_b32 v3, v3, v2
	v_cvt_pk_bf16_f32 v4, v38, v39
	global_store_dwordx2 v86, v[4:5], s[56:57] sc1
	v_cvt_pk_bf16_f32 v4, v34, v35
	v_cvt_pk_bf16_f32 v5, v36, v37
	global_store_dwordx2 v86, v[4:5], s[56:57] offset:512 sc1
	v_cvt_pk_bf16_f32 v4, v46, v47
	v_cvt_pk_bf16_f32 v5, v48, v49
	global_store_dwordx2 v86, v[4:5], s[56:57] offset:1024 sc1
	v_cvt_pk_bf16_f32 v4, v42, v43
	v_cvt_pk_bf16_f32 v5, v44, v45
	global_store_dwordx2 v86, v[4:5], s[56:57] offset:1536 sc1
	s_and_saveexec_b64 s[6:7], s[4:5]
	s_cbranch_execz .LBB0_1449
	s_waitcnt lgkmcnt(0)
	v_add_f32_e32 v2, v2, v3
	global_store_dword v85, v2, s[58:59] sc1

.LBB0_1450:
	s_cmp_eq_u64 s[60:61], 0
	s_cbranch_scc1 .LBB0_1454
	s_waitcnt vmcnt(0)
	v_mul_f32_e32 v2, v55, v55
	s_waitcnt lgkmcnt(0)
	v_mul_f32_e32 v3, v57, v57
	v_fmac_f32_e32 v2, v54, v54
	v_fmac_f32_e32 v3, v56, v56
	v_add_f32_e32 v2, v2, v3
	v_mul_f32_e32 v3, v51, v51
	v_mul_f32_e32 v4, v53, v53
	v_fmac_f32_e32 v3, v50, v50
	v_fmac_f32_e32 v4, v52, v52
	v_add_f32_e32 v3, v3, v4
	v_add_f32_e32 v2, v2, v3
	v_mul_f32_e32 v3, v63, v63
	v_mul_f32_e32 v4, v65, v65
	v_fmac_f32_e32 v3, v62, v62
	v_fmac_f32_e32 v4, v64, v64
	v_add_f32_e32 v3, v3, v4
	v_add_f32_e32 v2, v2, v3
	v_mul_f32_e32 v3, v59, v59
	v_mul_f32_e32 v4, v61, v61
	v_fmac_f32_e32 v3, v58, v58
	v_fmac_f32_e32 v4, v60, v60
	v_add_f32_e32 v3, v3, v4
	v_add_f32_e32 v2, v2, v3
	v_and_b32_e32 v3, 64, v83
	v_add_u32_e32 v3, 64, v3
	v_xor_b32_e32 v4, 1, v83
	v_cmp_lt_i32_e32 vcc, v4, v3
	v_cvt_pk_bf16_f32 v5, v56, v57
	s_nop 0
	v_cndmask_b32_e32 v4, v83, v4, vcc
	v_lshlrev_b32_e32 v4, 2, v4
	ds_bpermute_b32 v4, v4, v2
	s_waitcnt lgkmcnt(0)
	v_add_f32_e32 v2, v2, v4
	v_xor_b32_e32 v4, 2, v83
	v_cmp_lt_i32_e32 vcc, v4, v3
	s_nop 1
	v_cndmask_b32_e32 v4, v83, v4, vcc
	v_lshlrev_b32_e32 v4, 2, v4
	ds_bpermute_b32 v4, v4, v2
	s_waitcnt lgkmcnt(0)
	v_add_f32_e32 v2, v2, v4
	v_xor_b32_e32 v4, 4, v83
	v_cmp_lt_i32_e32 vcc, v4, v3
	s_nop 1
	v_cndmask_b32_e32 v4, v83, v4, vcc
	v_lshlrev_b32_e32 v4, 2, v4
	ds_bpermute_b32 v4, v4, v2
	s_waitcnt lgkmcnt(0)
	v_add_f32_e32 v2, v2, v4
	v_xor_b32_e32 v4, 8, v83
	v_cmp_lt_i32_e32 vcc, v4, v3
	s_nop 1
	v_cndmask_b32_e32 v4, v83, v4, vcc
	v_lshlrev_b32_e32 v4, 2, v4
	ds_bpermute_b32 v4, v4, v2
	s_waitcnt lgkmcnt(0)
	v_add_f32_e32 v2, v2, v4
	v_xor_b32_e32 v4, 16, v83
	v_cmp_lt_i32_e32 vcc, v4, v3
	s_nop 1
	v_cndmask_b32_e32 v4, v83, v4, vcc
	v_lshlrev_b32_e32 v4, 2, v4
	ds_bpermute_b32 v4, v4, v2
	s_waitcnt lgkmcnt(0)
	v_add_f32_e32 v2, v2, v4
	v_xor_b32_e32 v4, 32, v83
	v_cmp_lt_i32_e32 vcc, v4, v3
	s_nop 1
	v_cndmask_b32_e32 v3, v83, v4, vcc
	v_lshlrev_b32_e32 v3, 2, v3
	ds_bpermute_b32 v3, v3, v2
	v_cvt_pk_bf16_f32 v4, v54, v55
	global_store_dwordx2 v86, v[4:5], s[60:61] sc1
	v_cvt_pk_bf16_f32 v4, v50, v51
	v_cvt_pk_bf16_f32 v5, v52, v53
	global_store_dwordx2 v86, v[4:5], s[60:61] offset:512 sc1
	v_cvt_pk_bf16_f32 v4, v62, v63
	v_cvt_pk_bf16_f32 v5, v64, v65
	global_store_dwordx2 v86, v[4:5], s[60:61] offset:1024 sc1
	v_cvt_pk_bf16_f32 v4, v58, v59
	v_cvt_pk_bf16_f32 v5, v60, v61
	global_store_dwordx2 v86, v[4:5], s[60:61] offset:1536 sc1
	s_and_saveexec_b64 s[6:7], s[4:5]
	s_cbranch_execz .LBB0_1453
	s_waitcnt lgkmcnt(0)
	v_add_f32_e32 v2, v2, v3
	global_store_dword v85, v2, s[62:63] sc1

.LBB0_1454:
	s_cmp_eq_u64 s[64:65], 0
	s_cbranch_scc1 .LBB0_1345
	s_waitcnt vmcnt(0)
	v_mul_f32_e32 v2, v71, v71
	s_waitcnt lgkmcnt(0)
	v_mul_f32_e32 v3, v73, v73
	v_fmac_f32_e32 v2, v70, v70
	v_fmac_f32_e32 v3, v72, v72
	v_add_f32_e32 v2, v2, v3
	v_mul_f32_e32 v3, v67, v67
	v_mul_f32_e32 v4, v69, v69
	v_fmac_f32_e32 v3, v66, v66
	v_fmac_f32_e32 v4, v68, v68
	v_add_f32_e32 v3, v3, v4
	v_add_f32_e32 v2, v2, v3
	v_mul_f32_e32 v3, v79, v79
	v_mul_f32_e32 v4, v81, v81
	v_fmac_f32_e32 v3, v78, v78
	v_fmac_f32_e32 v4, v80, v80
	v_add_f32_e32 v3, v3, v4
	v_add_f32_e32 v2, v2, v3
	v_mul_f32_e32 v3, v75, v75
	v_mul_f32_e32 v4, v77, v77
	v_fmac_f32_e32 v3, v74, v74
	v_fmac_f32_e32 v4, v76, v76
	v_add_f32_e32 v3, v3, v4
	v_add_f32_e32 v2, v2, v3
	v_and_b32_e32 v3, 64, v83
	v_add_u32_e32 v3, 64, v3
	v_xor_b32_e32 v4, 1, v83
	v_cmp_lt_i32_e32 vcc, v4, v3
	v_cvt_pk_bf16_f32 v5, v72, v73
	s_nop 0
	v_cndmask_b32_e32 v4, v83, v4, vcc
	v_lshlrev_b32_e32 v4, 2, v4
	ds_bpermute_b32 v4, v4, v2
	s_waitcnt lgkmcnt(0)
	v_add_f32_e32 v2, v2, v4
	v_xor_b32_e32 v4, 2, v83
	v_cmp_lt_i32_e32 vcc, v4, v3
	s_nop 1
	v_cndmask_b32_e32 v4, v83, v4, vcc
	v_lshlrev_b32_e32 v4, 2, v4
	ds_bpermute_b32 v4, v4, v2
	s_waitcnt lgkmcnt(0)
	v_add_f32_e32 v2, v2, v4
	v_xor_b32_e32 v4, 4, v83
	v_cmp_lt_i32_e32 vcc, v4, v3
	s_nop 1
	v_cndmask_b32_e32 v4, v83, v4, vcc
	v_lshlrev_b32_e32 v4, 2, v4
	ds_bpermute_b32 v4, v4, v2
	s_waitcnt lgkmcnt(0)
	v_add_f32_e32 v2, v2, v4
	v_xor_b32_e32 v4, 8, v83
	v_cmp_lt_i32_e32 vcc, v4, v3
	s_nop 1
	v_cndmask_b32_e32 v4, v83, v4, vcc
	v_lshlrev_b32_e32 v4, 2, v4
	ds_bpermute_b32 v4, v4, v2
	s_waitcnt lgkmcnt(0)
	v_add_f32_e32 v2, v2, v4
	v_xor_b32_e32 v4, 16, v83
	v_cmp_lt_i32_e32 vcc, v4, v3
	s_nop 1
	v_cndmask_b32_e32 v4, v83, v4, vcc
	v_lshlrev_b32_e32 v4, 2, v4
	ds_bpermute_b32 v4, v4, v2
	s_waitcnt lgkmcnt(0)
	v_add_f32_e32 v2, v2, v4
	v_xor_b32_e32 v4, 32, v83
	v_cmp_lt_i32_e32 vcc, v4, v3
	s_nop 1
	v_cndmask_b32_e32 v3, v83, v4, vcc
	v_lshlrev_b32_e32 v3, 2, v3
	ds_bpermute_b32 v3, v3, v2
	v_cvt_pk_bf16_f32 v4, v70, v71
	global_store_dwordx2 v86, v[4:5], s[64:65] sc1
	v_cvt_pk_bf16_f32 v4, v66, v67
	v_cvt_pk_bf16_f32 v5, v68, v69
	global_store_dwordx2 v86, v[4:5], s[64:65] offset:512 sc1
	v_cvt_pk_bf16_f32 v4, v78, v79
	v_cvt_pk_bf16_f32 v5, v80, v81
	global_store_dwordx2 v86, v[4:5], s[64:65] offset:1024 sc1
	v_cvt_pk_bf16_f32 v4, v74, v75
	v_cvt_pk_bf16_f32 v5, v76, v77
	global_store_dwordx2 v86, v[4:5], s[64:65] offset:1536 sc1
	s_and_saveexec_b64 s[6:7], s[4:5]
	s_cbranch_execz .LBB0_1344
	s_waitcnt lgkmcnt(0)
	v_add_f32_e32 v2, v2, v3
	global_store_dword v85, v2, s[66:67] sc1
	s_branch .LBB0_1344

.LBB0_1459:
	v_and_b32_e32 v4, 0x10000, v9
	v_cmp_eq_u32_e32 vcc, 0, v4
	v_ashrrev_i32_e32 v12, 13, v9
	v_and_b32_e32 v14, 0xfc0, v6
	v_cndmask_b32_e32 v4, v7, v8, vcc
	v_lshl_add_u64 v[10:11], s[52:53], 0, v[4:5]
	global_load_dwordx2 v[10:11], v[10:11], off
	v_lshrrev_b32_e32 v4, 12, v9
	v_bfi_b32 v12, -16, v12, v4
	v_ashrrev_i32_e32 v13, 31, v12
	v_lshlrev_b64 v[12:13], 14, v[12:13]
	v_lshrrev_b32_e32 v15, 4, v9
	v_lshlrev_b32_e32 v4, 2, v14
	v_add_u32_e32 v9, s8, v9
	v_cmp_lt_i32_e32 vcc, s3, v9
	v_add_u32_e32 v6, s2, v6
	s_or_b64 s[12:13], vcc, s[12:13]
	s_waitcnt vmcnt(0)
	v_lshl_add_u64 v[10:11], v[10:11], 0, v[12:13]
	v_lshl_add_u64 v[10:11], v[10:11], 0, v[4:5]
	v_and_b32_e32 v4, 0xfc, v15
	v_lshl_add_u64 v[10:11], v[10:11], 0, v[4:5]
	global_load_dword v4, v[10:11], off
	s_waitcnt vmcnt(0)
	v_cvt_pk_bf16_f32 v4, v4, s0
	global_store_short v[2:3], v4, off sc1
	v_lshl_add_u64 v[2:3], v[2:3], 0, s[6:7]
	s_andn2_b64 exec, exec, s[12:13]
	s_cbranch_execnz .LBB0_1459

.LBB0_1475:
	s_or_b64 exec, exec, s[16:17]
	v_cmp_ne_u64_e32 vcc, -1, v[40:41]
	s_and_saveexec_b64 s[16:17], vcc
	s_cbranch_execz .LBB0_1479
	s_load_dwordx2 s[22:23], s[52:53], 0xc8
	s_waitcnt lgkmcnt(0)
	v_lshl_add_u64 v[40:41], v[40:41], 2, s[22:23]
	v_add_co_u32_e32 v48, vcc, 0x4cd0000, v40
	s_nop 1
	v_addc_co_u32_e32 v49, vcc, 0, v41, vcc
	s_waitcnt vmcnt(1)
	global_store_dwordx4 v[48:49], v[30:33], off nt sc1
	s_nop 1
	v_add_co_u32_e32 v30, vcc, 0x54d0000, v40
	s_nop 1
	v_addc_co_u32_e32 v31, vcc, 0, v41, vcc
	s_waitcnt vmcnt(1)
	global_store_dwordx4 v[30:31], v[26:29], off nt sc1
	s_or_b64 exec, exec, s[16:17]
	v_cmp_ne_u64_e32 vcc, -1, v[42:43]
	s_and_saveexec_b64 s[16:17], vcc
	s_cbranch_execnz .LBB0_1480

.LBB0_1478:
	s_load_dwordx2 s[22:23], s[52:53], 0xc8
	s_waitcnt vmcnt(0) lgkmcnt(0)
	v_lshl_add_u64 v[26:27], v[38:39], 2, s[22:23]
	v_add_co_u32_e32 v28, vcc, 0x4cd0000, v26
	s_nop 1
	v_addc_co_u32_e32 v29, vcc, 0, v27, vcc
	v_add_co_u32_e32 v26, vcc, 0x54d0000, v26
	global_store_dwordx4 v[28:29], v[18:21], off nt sc1
	s_nop 0
	v_addc_co_u32_e32 v27, vcc, 0, v27, vcc
	global_store_dwordx4 v[26:27], v[10:13], off nt sc1
	s_or_b64 exec, exec, s[16:17]
	v_cmp_ne_u64_e32 vcc, -1, v[36:37]
	s_and_saveexec_b64 s[16:17], vcc
	s_cbranch_execz .LBB0_1462
	s_branch .LBB0_1482

.LBB0_1480:
	s_load_dwordx2 s[22:23], s[52:53], 0xc8
	s_waitcnt vmcnt(0) lgkmcnt(0)
	v_lshl_add_u64 v[26:27], v[42:43], 2, s[22:23]
	v_add_co_u32_e32 v28, vcc, 0x4cd0000, v26
	s_nop 1
	v_addc_co_u32_e32 v29, vcc, 0, v27, vcc
	v_add_co_u32_e32 v26, vcc, 0x54d0000, v26
	global_store_dwordx4 v[28:29], v[2:5], off nt sc1
	s_nop 0
	v_addc_co_u32_e32 v27, vcc, 0, v27, vcc
	global_store_dwordx4 v[26:27], v[14:17], off nt sc1
	s_or_b64 exec, exec, s[16:17]
	v_cmp_ne_u64_e32 vcc, -1, v[38:39]
	s_and_saveexec_b64 s[16:17], vcc
	s_cbranch_execnz .LBB0_1478

.LBB0_1482:
	s_load_dwordx2 s[22:23], s[52:53], 0xc8
	s_waitcnt vmcnt(0) lgkmcnt(0)
	v_lshl_add_u64 v[26:27], v[36:37], 2, s[22:23]
	v_add_co_u32_e32 v28, vcc, 0x4cd0000, v26
	s_nop 1
	v_addc_co_u32_e32 v29, vcc, 0, v27, vcc
	v_add_co_u32_e32 v26, vcc, 0x54d0000, v26
	global_store_dwordx4 v[28:29], v[22:25], off nt sc1
	s_nop 0
	v_addc_co_u32_e32 v27, vcc, 0, v27, vcc
	global_store_dwordx4 v[26:27], v[6:9], off nt sc1
	s_branch .LBB0_1462

.LBB0_1486:
	s_or_b64 exec, exec, s[24:25]
	v_cmp_eq_u32_e64 s[4:5], 2, v25
	v_add_u32_e32 v34, s8, v34
	s_nop 0
	v_cndmask_b32_e64 v32, v28, v26, s[4:5]
	v_cndmask_b32_e64 v33, -v29, -v27, s[4:5]
	v_cmp_eq_u32_e64 s[4:5], 1, v25
	s_nop 1
	v_cndmask_b32_e64 v25, v32, v28, s[4:5]
	v_cndmask_b32_e64 v28, v33, v29, s[4:5]
	v_cndmask_b32_e32 v26, v25, v26, vcc
	v_ashrrev_i32_e32 v25, 31, v24
	v_cndmask_b32_e32 v27, v28, v27, vcc
	v_lshlrev_b64 v[24:25], 8, v[24:25]
	v_cmp_lt_i32_e32 vcc, s2, v34
	v_cvt_f32_f64_e32 v28, v[30:31]
	v_cvt_f32_f64_e32 v26, v[26:27]
	v_lshl_add_u64 v[24:25], v[2:3], 0, v[24:25]
	s_or_b64 s[12:13], vcc, s[12:13]
	global_store_dword v[24:25], v28, off sc1
	global_store_dword v[24:25], v26, off offset:128 sc1
	s_andn2_b64 exec, exec, s[12:13]
	s_cbranch_execz .LBB0_1490

.LBB0_1524:
	s_andn2_saveexec_b64 s[2:3], s[2:3]
	s_cbranch_execz .LBB0_1542
	s_mov_b64 s[2:3], exec
	s_nop 0
	s_waitcnt vmcnt(0) lgkmcnt(0)
	s_waitcnt vmcnt(0)
	v_mbcnt_lo_u32_b32 v2, s2, 0
	v_mbcnt_hi_u32_b32 v2, s3, v2
	v_cmp_eq_u32_e32 vcc, 0, v2
	s_and_saveexec_b64 s[6:7], vcc
	s_cbranch_execz .LBB0_1527
	s_bcnt1_i32_b64 s2, s[2:3]
	v_mov_b32_e32 v3, 0x7000
	v_mov_b32_e32 v4, s2
	global_atomic_add v3, v3, v4, s[76:77] offset:1024 sc0
